# speedup vs baseline: 1.0460x; 1.0047x over previous
.Lh2_loop:
	ds_read_b128 v[140:143], v138
	ds_read_b128 v[144:147], v138 offset:1024
	ds_read_b128 v[148:151], v138 offset:2048
	ds_read_b128 v[152:155], v138 offset:3072
	s_add_u32 s8, s6, s65
	s_addc_u32 s9, s7, s66
	ds_read_b128 v[156:159], v134
	ds_read_b128 v[160:163], v134 offset:1024
	ds_read_b128 v[164:167], v133
	ds_read_b128 v[168:171], v133 offset:1024
	ds_read_b128 v[172:175], v132
	ds_read_b128 v[176:179], v132 offset:1024
	ds_read_b128 v[180:183], v131
	ds_read_b128 v[184:187], v131 offset:1024
	s_mov_b32 m0, s76
	s_mov_b32 m0, s75
	s_nop 0
	s_waitcnt lgkmcnt(8)
	s_barrier
	s_waitcnt lgkmcnt(0)
	s_setprio 0
	s_waitcnt lgkmcnt(0)
	v_mfma_f32_16x16x32_bf16 v[124:127], v[140:143], v[156:159], v[124:127]
	v_mfma_f32_16x16x32_bf16 v[120:123], v[148:151], v[156:159], v[120:123]
	v_mfma_f32_16x16x32_bf16 v[116:119], v[140:143], v[164:167], v[116:119]
	v_mfma_f32_16x16x32_bf16 v[112:115], v[148:151], v[164:167], v[112:115]
	v_mfma_f32_16x16x32_bf16 v[108:111], v[140:143], v[172:175], v[108:111]
	v_mfma_f32_16x16x32_bf16 v[104:107], v[148:151], v[172:175], v[104:107]
	v_mfma_f32_16x16x32_bf16 v[100:103], v[140:143], v[180:183], v[100:103]
	v_mfma_f32_16x16x32_bf16 v[96:99], v[148:151], v[180:183], v[96:99]
	v_mfma_f32_16x16x32_bf16 v[124:127], v[144:147], v[160:163], v[124:127]
	v_mfma_f32_16x16x32_bf16 v[120:123], v[152:155], v[160:163], v[120:123]
	v_mfma_f32_16x16x32_bf16 v[116:119], v[144:147], v[168:171], v[116:119]
	v_mfma_f32_16x16x32_bf16 v[112:115], v[152:155], v[168:171], v[112:115]
	v_mfma_f32_16x16x32_bf16 v[108:111], v[144:147], v[176:179], v[108:111]
	v_mfma_f32_16x16x32_bf16 v[104:107], v[152:155], v[176:179], v[104:107]
	v_mfma_f32_16x16x32_bf16 v[100:103], v[144:147], v[184:187], v[100:103]
	v_mfma_f32_16x16x32_bf16 v[96:99], v[152:155], v[184:187], v[96:99]
	s_setprio 1
	s_barrier
	s_add_u32 s10, s6, s36
	s_addc_u32 s11, s7, s37
	ds_read_b128 v[188:191], v137
	ds_read_b128 v[192:195], v137 offset:1024
	ds_read_b128 v[202:205], v137 offset:2048
	ds_read_b128 v[206:209], v137 offset:3072
	s_mov_b32 m0, s63
	s_add_u32 s98, s10, s46
	s_addc_u32 s99, s11, s47
	global_load_lds_dwordx4 v129, s[98:99]
	s_mov_b32 m0, s64
	s_nop 0
	global_load_lds_dwordx4 v130, s[98:99]
	s_barrier
	s_waitcnt lgkmcnt(0)
	s_setprio 0
	s_waitcnt lgkmcnt(0)
	v_mfma_f32_16x16x32_bf16 v[92:95], v[188:191], v[156:159], v[92:95]
	v_mfma_f32_16x16x32_bf16 v[88:91], v[202:205], v[156:159], v[88:91]
	v_mfma_f32_16x16x32_bf16 v[84:87], v[188:191], v[164:167], v[84:87]
	v_mfma_f32_16x16x32_bf16 v[80:83], v[202:205], v[164:167], v[80:83]
	v_mfma_f32_16x16x32_bf16 v[76:79], v[188:191], v[172:175], v[76:79]
	v_mfma_f32_16x16x32_bf16 v[72:75], v[202:205], v[172:175], v[72:75]
	v_mfma_f32_16x16x32_bf16 v[68:71], v[188:191], v[180:183], v[68:71]
	v_mfma_f32_16x16x32_bf16 v[64:67], v[202:205], v[180:183], v[64:67]
	v_mfma_f32_16x16x32_bf16 v[92:95], v[192:195], v[160:163], v[92:95]
	v_mfma_f32_16x16x32_bf16 v[88:91], v[206:209], v[160:163], v[88:91]
	v_mfma_f32_16x16x32_bf16 v[84:87], v[192:195], v[168:171], v[84:87]
	v_mfma_f32_16x16x32_bf16 v[80:83], v[206:209], v[168:171], v[80:83]
	v_mfma_f32_16x16x32_bf16 v[76:79], v[192:195], v[176:179], v[76:79]
	v_mfma_f32_16x16x32_bf16 v[72:75], v[206:209], v[176:179], v[72:75]
	v_mfma_f32_16x16x32_bf16 v[68:71], v[192:195], v[184:187], v[68:71]
	v_mfma_f32_16x16x32_bf16 v[64:67], v[206:209], v[184:187], v[64:67]
	s_setprio 1
	s_barrier
	s_mov_b32 m0, s62
	s_add_u32 s98, s8, s48
	s_addc_u32 s99, s9, s49
	global_load_lds_dwordx4 v129, s[98:99]
	s_mov_b32 m0, s67
	s_nop 0
	global_load_lds_dwordx4 v130, s[98:99]
	s_waitcnt vmcnt(4)
	s_barrier
	s_mov_b32 m0, s68
	s_add_u32 s98, s10, s50
	s_addc_u32 s99, s11, s51
	global_load_lds_dwordx4 v129, s[98:99]
	s_mov_b32 m0, s69
	s_nop 0
	global_load_lds_dwordx4 v130, s[98:99]
	s_barrier
	ds_read_b128 v[140:143], v136
	ds_read_b128 v[144:147], v136 offset:1024
	ds_read_b128 v[148:151], v136 offset:2048
	ds_read_b128 v[152:155], v136 offset:3072
	ds_read_b128 v[156:159], v134 offset:32768
	ds_read_b128 v[160:163], v134 offset:33792
	ds_read_b128 v[164:167], v133 offset:32768
	ds_read_b128 v[168:171], v133 offset:33792
	ds_read_b128 v[172:175], v132 offset:32768
	ds_read_b128 v[176:179], v132 offset:33792
	ds_read_b128 v[180:183], v131 offset:32768
	ds_read_b128 v[184:187], v131 offset:33792
	s_mov_b32 m0, s70
	s_mov_b32 m0, s71
	s_nop 0
	s_waitcnt lgkmcnt(8)
	s_barrier
	s_waitcnt lgkmcnt(0)
	s_setprio 0
	s_waitcnt lgkmcnt(0)
	v_mfma_f32_16x16x32_bf16 v[124:127], v[140:143], v[156:159], v[124:127]
	v_mfma_f32_16x16x32_bf16 v[120:123], v[148:151], v[156:159], v[120:123]
	v_mfma_f32_16x16x32_bf16 v[116:119], v[140:143], v[164:167], v[116:119]
	v_mfma_f32_16x16x32_bf16 v[112:115], v[148:151], v[164:167], v[112:115]
	v_mfma_f32_16x16x32_bf16 v[108:111], v[140:143], v[172:175], v[108:111]
	v_mfma_f32_16x16x32_bf16 v[104:107], v[148:151], v[172:175], v[104:107]
	v_mfma_f32_16x16x32_bf16 v[100:103], v[140:143], v[180:183], v[100:103]
	v_mfma_f32_16x16x32_bf16 v[96:99], v[148:151], v[180:183], v[96:99]
	v_mfma_f32_16x16x32_bf16 v[124:127], v[144:147], v[160:163], v[124:127]
	v_mfma_f32_16x16x32_bf16 v[120:123], v[152:155], v[160:163], v[120:123]
	v_mfma_f32_16x16x32_bf16 v[116:119], v[144:147], v[168:171], v[116:119]
	v_mfma_f32_16x16x32_bf16 v[112:115], v[152:155], v[168:171], v[112:115]
	v_mfma_f32_16x16x32_bf16 v[108:111], v[144:147], v[176:179], v[108:111]
	v_mfma_f32_16x16x32_bf16 v[104:107], v[152:155], v[176:179], v[104:107]
	v_mfma_f32_16x16x32_bf16 v[100:103], v[144:147], v[184:187], v[100:103]
	v_mfma_f32_16x16x32_bf16 v[96:99], v[152:155], v[184:187], v[96:99]
	s_setprio 1
	s_barrier
	ds_read_b128 v[188:191], v135
	ds_read_b128 v[192:195], v135 offset:1024
	ds_read_b128 v[202:205], v135 offset:2048
	ds_read_b128 v[206:209], v135 offset:3072
	s_mov_b32 m0, s28
	s_add_u32 s98, s10, s92
	s_addc_u32 s99, s11, s93
	global_load_lds_dwordx4 v129, s[98:99]
	s_mov_b32 m0, s29
	s_nop 0
	global_load_lds_dwordx4 v130, s[98:99]
	s_barrier
	s_waitcnt lgkmcnt(0)
	s_setprio 0
	s_waitcnt lgkmcnt(0)
	v_mfma_f32_16x16x32_bf16 v[92:95], v[188:191], v[156:159], v[92:95]
	v_mfma_f32_16x16x32_bf16 v[88:91], v[202:205], v[156:159], v[88:91]
	v_mfma_f32_16x16x32_bf16 v[84:87], v[188:191], v[164:167], v[84:87]
	v_mfma_f32_16x16x32_bf16 v[80:83], v[202:205], v[164:167], v[80:83]
	v_mfma_f32_16x16x32_bf16 v[76:79], v[188:191], v[172:175], v[76:79]
	v_mfma_f32_16x16x32_bf16 v[72:75], v[202:205], v[172:175], v[72:75]
	v_mfma_f32_16x16x32_bf16 v[68:71], v[188:191], v[180:183], v[68:71]
	v_mfma_f32_16x16x32_bf16 v[64:67], v[202:205], v[180:183], v[64:67]
	v_mfma_f32_16x16x32_bf16 v[92:95], v[192:195], v[160:163], v[92:95]
	v_mfma_f32_16x16x32_bf16 v[88:91], v[206:209], v[160:163], v[88:91]
	v_mfma_f32_16x16x32_bf16 v[84:87], v[192:195], v[168:171], v[84:87]
	v_mfma_f32_16x16x32_bf16 v[80:83], v[206:209], v[168:171], v[80:83]
	v_mfma_f32_16x16x32_bf16 v[76:79], v[192:195], v[176:179], v[76:79]
	v_mfma_f32_16x16x32_bf16 v[72:75], v[206:209], v[176:179], v[72:75]
	v_mfma_f32_16x16x32_bf16 v[68:71], v[192:195], v[184:187], v[68:71]
	v_mfma_f32_16x16x32_bf16 v[64:67], v[206:209], v[184:187], v[64:67]
	s_setprio 1
	v_mov_b32_e32 v210, v130
	s_barrier
	v_mov_b32_e32 v211, v197
	s_mov_b32 m0, s72
	s_add_u32 s98, s8, s96
	s_addc_u32 s99, s9, s97
	global_load_lds_dwordx4 v129, s[98:99]
	s_mov_b32 m0, s73
	s_nop 0
	global_load_lds_dwordx4 v130, s[98:99]
	s_waitcnt vmcnt(4)
	s_barrier
	v_mov_b32_e32 v196, v129
	s_mov_b32 m0, s33
	s_add_u32 s98, s10, vcc_lo
	s_addc_u32 s99, s11, vcc_hi
	global_load_lds_dwordx4 v129, s[98:99]
	s_mov_b32 m0, s74
	s_nop 0
	global_load_lds_dwordx4 v130, s[98:99]
	s_barrier
	s_add_i32 s38, s38, 2
	s_add_u32 s6, s6, 0x100
	s_addc_u32 s7, s7, 0
	s_cmpk_lt_u32 s38, 0x54
	s_cbranch_scc1 .Lh2_loop
	s_setprio 0
	s_add_u32 s4, s4, 0x2b80
	s_addc_u32 s5, s5, 0
	s_mov_b32 m0, s76
	ds_read_b128 v[140:143], v138
	ds_read_b128 v[144:147], v138 offset:1024
	ds_read_b128 v[148:151], v138 offset:2048
	ds_read_b128 v[152:155], v138 offset:3072
	ds_read_b128 v[156:159], v134
	ds_read_b128 v[160:163], v134 offset:1024
	ds_read_b128 v[164:167], v133
	ds_read_b128 v[168:171], v133 offset:1024
	ds_read_b128 v[172:175], v132
	ds_read_b128 v[176:179], v132 offset:1024
	ds_read_b128 v[180:183], v131
	ds_read_b128 v[184:187], v131 offset:1024
	s_nop 0
	s_mov_b32 m0, s75
	s_nop 0
	s_barrier
	s_waitcnt lgkmcnt(0)
	s_setprio 1
	s_waitcnt lgkmcnt(0)
	v_mfma_f32_16x16x32_bf16 v[124:127], v[140:143], v[156:159], v[124:127]
	v_mfma_f32_16x16x32_bf16 v[120:123], v[148:151], v[156:159], v[120:123]
	v_mfma_f32_16x16x32_bf16 v[116:119], v[140:143], v[164:167], v[116:119]
	v_mfma_f32_16x16x32_bf16 v[112:115], v[148:151], v[164:167], v[112:115]
	v_mfma_f32_16x16x32_bf16 v[108:111], v[140:143], v[172:175], v[108:111]
	v_mfma_f32_16x16x32_bf16 v[100:103], v[140:143], v[180:183], v[100:103]
	v_mfma_f32_16x16x32_bf16 v[96:99], v[148:151], v[180:183], v[96:99]
	v_mfma_f32_16x16x32_bf16 v[124:127], v[144:147], v[160:163], v[124:127]
	v_mfma_f32_16x16x32_bf16 v[120:123], v[152:155], v[160:163], v[120:123]
	v_mfma_f32_16x16x32_bf16 v[116:119], v[144:147], v[168:171], v[116:119]
	v_mfma_f32_16x16x32_bf16 v[112:115], v[152:155], v[168:171], v[112:115]
	v_mfma_f32_16x16x32_bf16 v[108:111], v[144:147], v[176:179], v[108:111]
	v_mfma_f32_16x16x32_bf16 v[104:107], v[148:151], v[172:175], v[104:107]
	v_mfma_f32_16x16x32_bf16 v[100:103], v[144:147], v[184:187], v[100:103]
	v_mfma_f32_16x16x32_bf16 v[96:99], v[152:155], v[184:187], v[96:99]
	v_mfma_f32_16x16x32_bf16 v[188:191], v[152:155], v[176:179], v[104:107]
	s_setprio 0
	s_barrier
	s_nop 2
	ds_read_b128 v[104:107], v137
	ds_read_b128 v[192:195], v137 offset:1024
	ds_read_b128 v[202:205], v137 offset:2048
	ds_read_b128 v[206:209], v137 offset:3072
	s_barrier
	s_waitcnt lgkmcnt(0)
	s_setprio 1
	s_waitcnt lgkmcnt(0)
	v_mfma_f32_16x16x32_bf16 v[92:95], v[104:107], v[156:159], v[92:95]
	v_mfma_f32_16x16x32_bf16 v[88:91], v[202:205], v[156:159], v[88:91]
	v_mfma_f32_16x16x32_bf16 v[80:83], v[202:205], v[164:167], v[80:83]
	v_mfma_f32_16x16x32_bf16 v[72:75], v[202:205], v[172:175], v[72:75]
	v_mfma_f32_16x16x32_bf16 v[64:67], v[202:205], v[180:183], v[64:67]
	v_mfma_f32_16x16x32_bf16 v[92:95], v[192:195], v[160:163], v[92:95]
	v_mfma_f32_16x16x32_bf16 v[88:91], v[206:209], v[160:163], v[88:91]
	v_mfma_f32_16x16x32_bf16 v[84:87], v[104:107], v[164:167], v[84:87]
	v_mfma_f32_16x16x32_bf16 v[80:83], v[206:209], v[168:171], v[80:83]
	v_mfma_f32_16x16x32_bf16 v[76:79], v[104:107], v[172:175], v[76:79]
	v_mfma_f32_16x16x32_bf16 v[72:75], v[206:209], v[176:179], v[72:75]
	v_mfma_f32_16x16x32_bf16 v[68:71], v[104:107], v[180:183], v[68:71]
	v_mfma_f32_16x16x32_bf16 v[64:67], v[206:209], v[184:187], v[64:67]
	v_mfma_f32_16x16x32_bf16 v[156:159], v[192:195], v[168:171], v[84:87]
	v_mfma_f32_16x16x32_bf16 v[160:163], v[192:195], v[176:179], v[76:79]
	v_mfma_f32_16x16x32_bf16 v[164:167], v[192:195], v[184:187], v[68:71]
	s_setprio 0
	s_barrier
	s_nop 1
	s_waitcnt vmcnt(2)
	s_barrier
	s_waitcnt lgkmcnt(0)
	s_setprio 1
	s_waitcnt lgkmcnt(0)
	s_setprio 0
	s_setprio 1
	s_setprio 0
	s_barrier
	ds_read_b128 v[16:19], v136
	ds_read_b128 v[180:183], v136 offset:1024
	ds_read_b128 v[184:187], v136 offset:2048
	ds_read_b128 v[192:195], v136 offset:3072
	ds_read_b128 v[0:3], v134 offset:32768
	ds_read_b128 v[4:7], v134 offset:33792
	ds_read_b128 v[8:11], v133 offset:32768
	ds_read_b128 v[12:15], v133 offset:33792
	ds_read_b128 v[44:47], v132 offset:32768
	ds_read_b128 v[202:205], v132 offset:33792
	ds_read_b128 v[206:209], v131 offset:32768
	ds_read_b128 v[222:225], v131 offset:33792
	s_waitcnt vmcnt(0)
	s_barrier
	s_waitcnt lgkmcnt(0)
	s_setprio 1
	s_waitcnt lgkmcnt(0)
	v_mfma_f32_16x16x32_bf16 v[28:31], v[16:19], v[0:3], v[124:127]
	v_mfma_f32_16x16x32_bf16 v[52:55], v[180:183], v[4:7], v[28:31]
	v_mfma_f32_16x16x32_bf16 v[28:31], v[184:187], v[0:3], v[120:123]
	v_mfma_f32_16x16x32_bf16 v[104:107], v[192:195], v[4:7], v[28:31]
	v_mfma_f32_16x16x32_bf16 v[28:31], v[16:19], v[8:11], v[116:119]
	v_mfma_f32_16x16x32_bf16 v[68:71], v[180:183], v[12:15], v[28:31]
	v_mfma_f32_16x16x32_bf16 v[28:31], v[184:187], v[8:11], v[112:115]
	v_mfma_f32_16x16x32_bf16 v[116:119], v[192:195], v[12:15], v[28:31]
	v_mfma_f32_16x16x32_bf16 v[28:31], v[16:19], v[44:47], v[108:111]
	v_mfma_f32_16x16x32_bf16 v[76:79], v[180:183], v[202:205], v[28:31]
	v_mfma_f32_16x16x32_bf16 v[28:31], v[184:187], v[44:47], v[188:191]
	v_mfma_f32_16x16x32_bf16 v[108:111], v[192:195], v[202:205], v[28:31]
	v_mfma_f32_16x16x32_bf16 v[28:31], v[16:19], v[206:209], v[100:103]
	v_mfma_f32_16x16x32_bf16 v[84:87], v[180:183], v[222:225], v[28:31]
	v_mfma_f32_16x16x32_bf16 v[28:31], v[184:187], v[206:209], v[96:99]
	v_mfma_f32_16x16x32_bf16 v[96:99], v[192:195], v[222:225], v[28:31]
	s_setprio 0
	s_barrier
	ds_read_b128 v[188:191], v135
	ds_read_b128 v[228:231], v135 offset:1024
	ds_read_b128 v[232:235], v135 offset:2048
	ds_read_b128 v[236:239], v135 offset:3072
	s_waitcnt vmcnt(0)
	s_barrier
	s_waitcnt lgkmcnt(0)
	s_setprio 1
	s_waitcnt lgkmcnt(0)
	v_mfma_f32_16x16x32_bf16 v[28:31], v[188:191], v[0:3], v[92:95]
	v_mfma_f32_16x16x32_bf16 v[0:3], v[232:235], v[0:3], v[88:91]
	v_mfma_f32_16x16x32_bf16 v[28:31], v[228:231], v[4:7], v[28:31]
	v_mfma_f32_16x16x32_bf16 v[0:3], v[236:239], v[4:7], v[0:3]
	v_mfma_f32_16x16x32_bf16 v[4:7], v[188:191], v[8:11], v[156:159]
	v_mfma_f32_16x16x32_bf16 v[36:39], v[228:231], v[12:15], v[4:7]
	v_mfma_f32_16x16x32_bf16 v[4:7], v[232:235], v[8:11], v[80:83]
	v_mfma_f32_16x16x32_bf16 v[4:7], v[236:239], v[12:15], v[4:7]
	v_mfma_f32_16x16x32_bf16 v[8:11], v[188:191], v[44:47], v[160:163]
	v_mfma_f32_16x16x32_bf16 v[12:15], v[188:191], v[206:209], v[164:167]
	v_mfma_f32_16x16x32_bf16 v[40:43], v[228:231], v[202:205], v[8:11]
	v_mfma_f32_16x16x32_bf16 v[8:11], v[232:235], v[44:47], v[72:75]
	v_mfma_f32_16x16x32_bf16 v[44:47], v[228:231], v[222:225], v[12:15]
	v_mfma_f32_16x16x32_bf16 v[12:15], v[232:235], v[206:209], v[64:67]
	v_mfma_f32_16x16x32_bf16 v[8:11], v[236:239], v[202:205], v[8:11]
	v_mfma_f32_16x16x32_bf16 v[12:15], v[236:239], v[222:225], v[12:15]
	s_setprio 0
	s_barrier
	s_barrier
	s_waitcnt lgkmcnt(0)
	s_setprio 1
	s_waitcnt lgkmcnt(0)
	s_setprio 0
	s_setprio 1
	s_setprio 0
	s_movk_i32 s4, 0x100
	v_cmp_gt_u32_e32 vcc, s4, v128
	s_barrier
	s_and_saveexec_b64 s[4:5], vcc
	s_cbranch_execz .Lh2_epi
	s_barrier

.LBB0_138:
	ds_read_b128 v[140:143], v138
	ds_read_b128 v[144:147], v138 offset:1024
	ds_read_b128 v[148:151], v138 offset:2048
	ds_read_b128 v[152:155], v138 offset:3072
	s_add_u32 s8, s6, s65
	s_addc_u32 s9, s7, s66
	ds_read_b128 v[156:159], v134
	ds_read_b128 v[160:163], v134 offset:1024
	ds_read_b128 v[164:167], v133
	ds_read_b128 v[168:171], v133 offset:1024
	ds_read_b128 v[172:175], v132
	ds_read_b128 v[176:179], v132 offset:1024
	ds_read_b128 v[180:183], v131
	ds_read_b128 v[184:187], v131 offset:1024
	s_mov_b32 m0, s76
	s_add_u32 s98, s8, s44
	s_addc_u32 s99, s9, s45
	global_load_lds_dwordx4 v129, s[98:99]
	s_mov_b32 m0, s75
	s_nop 0
	global_load_lds_dwordx4 v130, s[98:99]
	s_waitcnt lgkmcnt(8)
	s_barrier
	s_waitcnt lgkmcnt(0)
	s_setprio 0
	s_waitcnt lgkmcnt(0)
	v_mfma_f32_16x16x32_bf16 v[124:127], v[140:143], v[156:159], v[124:127]
	v_mfma_f32_16x16x32_bf16 v[120:123], v[148:151], v[156:159], v[120:123]
	v_mfma_f32_16x16x32_bf16 v[116:119], v[140:143], v[164:167], v[116:119]
	v_mfma_f32_16x16x32_bf16 v[112:115], v[148:151], v[164:167], v[112:115]
	v_mfma_f32_16x16x32_bf16 v[108:111], v[140:143], v[172:175], v[108:111]
	v_mfma_f32_16x16x32_bf16 v[104:107], v[148:151], v[172:175], v[104:107]
	v_mfma_f32_16x16x32_bf16 v[100:103], v[140:143], v[180:183], v[100:103]
	v_mfma_f32_16x16x32_bf16 v[96:99], v[148:151], v[180:183], v[96:99]
	v_mfma_f32_16x16x32_bf16 v[124:127], v[144:147], v[160:163], v[124:127]
	v_mfma_f32_16x16x32_bf16 v[120:123], v[152:155], v[160:163], v[120:123]
	v_mfma_f32_16x16x32_bf16 v[116:119], v[144:147], v[168:171], v[116:119]
	v_mfma_f32_16x16x32_bf16 v[112:115], v[152:155], v[168:171], v[112:115]
	v_mfma_f32_16x16x32_bf16 v[108:111], v[144:147], v[176:179], v[108:111]
	v_mfma_f32_16x16x32_bf16 v[104:107], v[152:155], v[176:179], v[104:107]
	v_mfma_f32_16x16x32_bf16 v[100:103], v[144:147], v[184:187], v[100:103]
	v_mfma_f32_16x16x32_bf16 v[96:99], v[152:155], v[184:187], v[96:99]
	s_setprio 1
	s_barrier
	s_add_u32 s10, s6, s36
	s_addc_u32 s11, s7, s37
	ds_read_b128 v[188:191], v137
	ds_read_b128 v[192:195], v137 offset:1024
	ds_read_b128 v[202:205], v137 offset:2048
	ds_read_b128 v[206:209], v137 offset:3072
	s_mov_b32 m0, s63
	s_add_u32 s98, s10, s46
	s_addc_u32 s99, s11, s47
	global_load_lds_dwordx4 v129, s[98:99]
	s_mov_b32 m0, s64
	s_nop 0
	global_load_lds_dwordx4 v130, s[98:99]
	s_barrier
	s_waitcnt lgkmcnt(0)
	s_setprio 0
	s_waitcnt lgkmcnt(0)
	v_mfma_f32_16x16x32_bf16 v[92:95], v[188:191], v[156:159], v[92:95]
	v_mfma_f32_16x16x32_bf16 v[88:91], v[202:205], v[156:159], v[88:91]
	v_mfma_f32_16x16x32_bf16 v[84:87], v[188:191], v[164:167], v[84:87]
	v_mfma_f32_16x16x32_bf16 v[80:83], v[202:205], v[164:167], v[80:83]
	v_mfma_f32_16x16x32_bf16 v[76:79], v[188:191], v[172:175], v[76:79]
	v_mfma_f32_16x16x32_bf16 v[72:75], v[202:205], v[172:175], v[72:75]
	v_mfma_f32_16x16x32_bf16 v[68:71], v[188:191], v[180:183], v[68:71]
	v_mfma_f32_16x16x32_bf16 v[64:67], v[202:205], v[180:183], v[64:67]
	v_mfma_f32_16x16x32_bf16 v[92:95], v[192:195], v[160:163], v[92:95]
	v_mfma_f32_16x16x32_bf16 v[88:91], v[206:209], v[160:163], v[88:91]
	v_mfma_f32_16x16x32_bf16 v[84:87], v[192:195], v[168:171], v[84:87]
	v_mfma_f32_16x16x32_bf16 v[80:83], v[206:209], v[168:171], v[80:83]
	v_mfma_f32_16x16x32_bf16 v[76:79], v[192:195], v[176:179], v[76:79]
	v_mfma_f32_16x16x32_bf16 v[72:75], v[206:209], v[176:179], v[72:75]
	v_mfma_f32_16x16x32_bf16 v[68:71], v[192:195], v[184:187], v[68:71]
	v_mfma_f32_16x16x32_bf16 v[64:67], v[206:209], v[184:187], v[64:67]
	s_setprio 1
	s_barrier
	ds_read_b128 v[156:159], v134 offset:16384
	ds_read_b128 v[160:163], v134 offset:17408
	ds_read_b128 v[164:167], v133 offset:16384
	ds_read_b128 v[168:171], v133 offset:17408
	ds_read_b128 v[172:175], v132 offset:16384
	ds_read_b128 v[176:179], v132 offset:17408
	ds_read_b128 v[180:183], v131 offset:16384
	ds_read_b128 v[184:187], v131 offset:17408
	s_mov_b32 m0, s62
	s_add_u32 s98, s8, s48
	s_addc_u32 s99, s9, s49
	global_load_lds_dwordx4 v129, s[98:99]
	s_mov_b32 m0, s67
	s_nop 0
	global_load_lds_dwordx4 v130, s[98:99]
	s_barrier
	s_waitcnt lgkmcnt(0)
	s_setprio 0
	s_waitcnt lgkmcnt(0)
	v_mfma_f32_16x16x32_bf16 v[60:63], v[140:143], v[156:159], v[60:63]
	v_mfma_f32_16x16x32_bf16 v[56:59], v[148:151], v[156:159], v[56:59]
	v_mfma_f32_16x16x32_bf16 v[52:55], v[140:143], v[164:167], v[52:55]
	v_mfma_f32_16x16x32_bf16 v[48:51], v[148:151], v[164:167], v[48:51]
	v_mfma_f32_16x16x32_bf16 v[44:47], v[140:143], v[172:175], v[44:47]
	v_mfma_f32_16x16x32_bf16 v[40:43], v[148:151], v[172:175], v[40:43]
	v_mfma_f32_16x16x32_bf16 v[36:39], v[140:143], v[180:183], v[36:39]
	v_mfma_f32_16x16x32_bf16 v[32:35], v[148:151], v[180:183], v[32:35]
	v_mfma_f32_16x16x32_bf16 v[60:63], v[144:147], v[160:163], v[60:63]
	v_mfma_f32_16x16x32_bf16 v[56:59], v[152:155], v[160:163], v[56:59]
	v_mfma_f32_16x16x32_bf16 v[52:55], v[144:147], v[168:171], v[52:55]
	v_mfma_f32_16x16x32_bf16 v[48:51], v[152:155], v[168:171], v[48:51]
	v_mfma_f32_16x16x32_bf16 v[44:47], v[144:147], v[176:179], v[44:47]
	v_mfma_f32_16x16x32_bf16 v[40:43], v[152:155], v[176:179], v[40:43]
	v_mfma_f32_16x16x32_bf16 v[36:39], v[144:147], v[184:187], v[36:39]
	v_mfma_f32_16x16x32_bf16 v[32:35], v[152:155], v[184:187], v[32:35]
	s_setprio 1
	s_barrier
	s_mov_b32 m0, s68
	s_add_u32 s98, s10, s50
	s_addc_u32 s99, s11, s51
	global_load_lds_dwordx4 v129, s[98:99]
	s_mov_b32 m0, s69
	s_nop 0
	global_load_lds_dwordx4 v130, s[98:99]
	s_waitcnt vmcnt(6)
	s_barrier
	s_setprio 0
	v_mfma_f32_16x16x32_bf16 v[28:31], v[188:191], v[156:159], v[28:31]
	v_mfma_f32_16x16x32_bf16 v[24:27], v[202:205], v[156:159], v[24:27]
	v_mfma_f32_16x16x32_bf16 v[20:23], v[188:191], v[164:167], v[20:23]
	v_mfma_f32_16x16x32_bf16 v[16:19], v[202:205], v[164:167], v[16:19]
	v_mfma_f32_16x16x32_bf16 v[12:15], v[188:191], v[172:175], v[12:15]
	v_mfma_f32_16x16x32_bf16 v[8:11], v[202:205], v[172:175], v[8:11]
	v_mfma_f32_16x16x32_bf16 v[4:7], v[188:191], v[180:183], v[4:7]
	v_mfma_f32_16x16x32_bf16 v[0:3], v[202:205], v[180:183], v[0:3]
	v_mfma_f32_16x16x32_bf16 v[28:31], v[192:195], v[160:163], v[28:31]
	v_mfma_f32_16x16x32_bf16 v[24:27], v[206:209], v[160:163], v[24:27]
	v_mfma_f32_16x16x32_bf16 v[20:23], v[192:195], v[168:171], v[20:23]
	v_mfma_f32_16x16x32_bf16 v[16:19], v[206:209], v[168:171], v[16:19]
	v_mfma_f32_16x16x32_bf16 v[12:15], v[192:195], v[176:179], v[12:15]
	v_mfma_f32_16x16x32_bf16 v[8:11], v[206:209], v[176:179], v[8:11]
	v_mfma_f32_16x16x32_bf16 v[4:7], v[192:195], v[184:187], v[4:7]
	v_mfma_f32_16x16x32_bf16 v[0:3], v[206:209], v[184:187], v[0:3]
	s_setprio 1
	s_barrier
	ds_read_b128 v[140:143], v136
	ds_read_b128 v[144:147], v136 offset:1024
	ds_read_b128 v[148:151], v136 offset:2048
	ds_read_b128 v[152:155], v136 offset:3072
	ds_read_b128 v[156:159], v134 offset:32768
	ds_read_b128 v[160:163], v134 offset:33792
	ds_read_b128 v[164:167], v133 offset:32768
	ds_read_b128 v[168:171], v133 offset:33792
	ds_read_b128 v[172:175], v132 offset:32768
	ds_read_b128 v[176:179], v132 offset:33792
	ds_read_b128 v[180:183], v131 offset:32768
	ds_read_b128 v[184:187], v131 offset:33792
	s_mov_b32 m0, s70
	s_add_u32 s98, s8, s90
	s_addc_u32 s99, s9, s91
	global_load_lds_dwordx4 v129, s[98:99]
	s_mov_b32 m0, s71
	s_nop 0
	global_load_lds_dwordx4 v130, s[98:99]
	s_waitcnt lgkmcnt(8)
	s_barrier
	s_waitcnt lgkmcnt(0)
	s_setprio 0
	s_waitcnt lgkmcnt(0)
	v_mfma_f32_16x16x32_bf16 v[124:127], v[140:143], v[156:159], v[124:127]
	v_mfma_f32_16x16x32_bf16 v[120:123], v[148:151], v[156:159], v[120:123]
	v_mfma_f32_16x16x32_bf16 v[116:119], v[140:143], v[164:167], v[116:119]
	v_mfma_f32_16x16x32_bf16 v[112:115], v[148:151], v[164:167], v[112:115]
	v_mfma_f32_16x16x32_bf16 v[108:111], v[140:143], v[172:175], v[108:111]
	v_mfma_f32_16x16x32_bf16 v[104:107], v[148:151], v[172:175], v[104:107]
	v_mfma_f32_16x16x32_bf16 v[100:103], v[140:143], v[180:183], v[100:103]
	v_mfma_f32_16x16x32_bf16 v[96:99], v[148:151], v[180:183], v[96:99]
	v_mfma_f32_16x16x32_bf16 v[124:127], v[144:147], v[160:163], v[124:127]
	v_mfma_f32_16x16x32_bf16 v[120:123], v[152:155], v[160:163], v[120:123]
	v_mfma_f32_16x16x32_bf16 v[116:119], v[144:147], v[168:171], v[116:119]
	v_mfma_f32_16x16x32_bf16 v[112:115], v[152:155], v[168:171], v[112:115]
	v_mfma_f32_16x16x32_bf16 v[108:111], v[144:147], v[176:179], v[108:111]
	v_mfma_f32_16x16x32_bf16 v[104:107], v[152:155], v[176:179], v[104:107]
	v_mfma_f32_16x16x32_bf16 v[100:103], v[144:147], v[184:187], v[100:103]
	v_mfma_f32_16x16x32_bf16 v[96:99], v[152:155], v[184:187], v[96:99]
	s_setprio 1
	s_barrier
	ds_read_b128 v[188:191], v135
	ds_read_b128 v[192:195], v135 offset:1024
	ds_read_b128 v[202:205], v135 offset:2048
	ds_read_b128 v[206:209], v135 offset:3072
	s_mov_b32 m0, s28
	s_add_u32 s98, s10, s92
	s_addc_u32 s99, s11, s93
	global_load_lds_dwordx4 v129, s[98:99]
	s_mov_b32 m0, s29
	s_nop 0
	global_load_lds_dwordx4 v130, s[98:99]
	s_barrier
	s_waitcnt lgkmcnt(0)
	s_setprio 0
	s_waitcnt lgkmcnt(0)
	v_mfma_f32_16x16x32_bf16 v[92:95], v[188:191], v[156:159], v[92:95]
	v_mfma_f32_16x16x32_bf16 v[88:91], v[202:205], v[156:159], v[88:91]
	v_mfma_f32_16x16x32_bf16 v[84:87], v[188:191], v[164:167], v[84:87]
	v_mfma_f32_16x16x32_bf16 v[80:83], v[202:205], v[164:167], v[80:83]
	v_mfma_f32_16x16x32_bf16 v[76:79], v[188:191], v[172:175], v[76:79]
	v_mfma_f32_16x16x32_bf16 v[72:75], v[202:205], v[172:175], v[72:75]
	v_mfma_f32_16x16x32_bf16 v[68:71], v[188:191], v[180:183], v[68:71]
	v_mfma_f32_16x16x32_bf16 v[64:67], v[202:205], v[180:183], v[64:67]
	v_mfma_f32_16x16x32_bf16 v[92:95], v[192:195], v[160:163], v[92:95]
	v_mfma_f32_16x16x32_bf16 v[88:91], v[206:209], v[160:163], v[88:91]
	v_mfma_f32_16x16x32_bf16 v[84:87], v[192:195], v[168:171], v[84:87]
	v_mfma_f32_16x16x32_bf16 v[80:83], v[206:209], v[168:171], v[80:83]
	v_mfma_f32_16x16x32_bf16 v[76:79], v[192:195], v[176:179], v[76:79]
	v_mfma_f32_16x16x32_bf16 v[72:75], v[206:209], v[176:179], v[72:75]
	v_mfma_f32_16x16x32_bf16 v[68:71], v[192:195], v[184:187], v[68:71]
	v_mfma_f32_16x16x32_bf16 v[64:67], v[206:209], v[184:187], v[64:67]
	s_setprio 1
	v_mov_b32_e32 v210, v130
	s_barrier
	ds_read_b128 v[156:159], v134 offset:49152
	ds_read_b128 v[160:163], v134 offset:50176
	ds_read_b128 v[164:167], v133 offset:49152
	ds_read_b128 v[168:171], v133 offset:50176
	ds_read_b128 v[172:175], v132 offset:49152
	ds_read_b128 v[176:179], v132 offset:50176
	ds_read_b128 v[180:183], v131 offset:49152
	ds_read_b128 v[184:187], v131 offset:50176
	v_mov_b32_e32 v211, v197
	s_mov_b32 m0, s72
	s_add_u32 s98, s8, s96
	s_addc_u32 s99, s9, s97
	global_load_lds_dwordx4 v129, s[98:99]
	s_mov_b32 m0, s73
	s_nop 0
	global_load_lds_dwordx4 v130, s[98:99]
	s_barrier
	s_waitcnt lgkmcnt(0)
	s_setprio 0
	s_waitcnt lgkmcnt(0)
	v_mfma_f32_16x16x32_bf16 v[60:63], v[140:143], v[156:159], v[60:63]
	v_mfma_f32_16x16x32_bf16 v[56:59], v[148:151], v[156:159], v[56:59]
	v_mfma_f32_16x16x32_bf16 v[52:55], v[140:143], v[164:167], v[52:55]
	v_mfma_f32_16x16x32_bf16 v[48:51], v[148:151], v[164:167], v[48:51]
	v_mfma_f32_16x16x32_bf16 v[44:47], v[140:143], v[172:175], v[44:47]
	v_mfma_f32_16x16x32_bf16 v[40:43], v[148:151], v[172:175], v[40:43]
	v_mfma_f32_16x16x32_bf16 v[36:39], v[140:143], v[180:183], v[36:39]
	v_mfma_f32_16x16x32_bf16 v[32:35], v[148:151], v[180:183], v[32:35]
	v_mfma_f32_16x16x32_bf16 v[60:63], v[144:147], v[160:163], v[60:63]
	v_mfma_f32_16x16x32_bf16 v[56:59], v[152:155], v[160:163], v[56:59]
	v_mfma_f32_16x16x32_bf16 v[52:55], v[144:147], v[168:171], v[52:55]
	v_mfma_f32_16x16x32_bf16 v[48:51], v[152:155], v[168:171], v[48:51]
	v_mfma_f32_16x16x32_bf16 v[44:47], v[144:147], v[176:179], v[44:47]
	v_mfma_f32_16x16x32_bf16 v[40:43], v[152:155], v[176:179], v[40:43]
	v_mfma_f32_16x16x32_bf16 v[36:39], v[144:147], v[184:187], v[36:39]
	v_mfma_f32_16x16x32_bf16 v[32:35], v[152:155], v[184:187], v[32:35]
	s_setprio 1
	s_barrier
	v_mov_b32_e32 v196, v129
	s_mov_b32 m0, s33
	s_add_u32 s98, s10, vcc_lo
	s_addc_u32 s99, s11, vcc_hi
	global_load_lds_dwordx4 v129, s[98:99]
	s_mov_b32 m0, s74
	s_nop 0
	global_load_lds_dwordx4 v130, s[98:99]
	s_waitcnt vmcnt(6)
	s_barrier
	s_setprio 0
	v_mfma_f32_16x16x32_bf16 v[28:31], v[188:191], v[156:159], v[28:31]
	v_mfma_f32_16x16x32_bf16 v[24:27], v[202:205], v[156:159], v[24:27]
	v_mfma_f32_16x16x32_bf16 v[20:23], v[188:191], v[164:167], v[20:23]
	v_mfma_f32_16x16x32_bf16 v[16:19], v[202:205], v[164:167], v[16:19]
	v_mfma_f32_16x16x32_bf16 v[12:15], v[188:191], v[172:175], v[12:15]
	v_mfma_f32_16x16x32_bf16 v[8:11], v[202:205], v[172:175], v[8:11]
	v_mfma_f32_16x16x32_bf16 v[4:7], v[188:191], v[180:183], v[4:7]
	v_mfma_f32_16x16x32_bf16 v[0:3], v[202:205], v[180:183], v[0:3]
	v_mfma_f32_16x16x32_bf16 v[28:31], v[192:195], v[160:163], v[28:31]
	v_mfma_f32_16x16x32_bf16 v[24:27], v[206:209], v[160:163], v[24:27]
	v_mfma_f32_16x16x32_bf16 v[20:23], v[192:195], v[168:171], v[20:23]
	v_mfma_f32_16x16x32_bf16 v[16:19], v[206:209], v[168:171], v[16:19]
	v_mfma_f32_16x16x32_bf16 v[12:15], v[192:195], v[176:179], v[12:15]
	v_mfma_f32_16x16x32_bf16 v[8:11], v[206:209], v[176:179], v[8:11]
	v_mfma_f32_16x16x32_bf16 v[4:7], v[192:195], v[184:187], v[4:7]
	v_mfma_f32_16x16x32_bf16 v[0:3], v[206:209], v[184:187], v[0:3]
	s_setprio 1
	s_add_i32 s38, s38, 2
	s_add_u32 s6, s6, 0x100
	s_addc_u32 s7, s7, 0
	s_cmpk_lt_u32 s38, 0x54
	s_barrier
	s_cbranch_scc1 .LBB0_138
	s_setprio 0
	s_add_u32 s4, s4, 0x2b80
	s_addc_u32 s5, s5, 0
	s_mov_b32 m0, s76
	ds_read_b128 v[140:143], v138
	ds_read_b128 v[144:147], v138 offset:1024
	ds_read_b128 v[148:151], v138 offset:2048
	ds_read_b128 v[152:155], v138 offset:3072
	ds_read_b128 v[156:159], v134
	ds_read_b128 v[160:163], v134 offset:1024
	ds_read_b128 v[164:167], v133
	ds_read_b128 v[168:171], v133 offset:1024
	ds_read_b128 v[172:175], v132
	ds_read_b128 v[176:179], v132 offset:1024
	ds_read_b128 v[180:183], v131
	ds_read_b128 v[184:187], v131 offset:1024
	s_nop 0
	global_load_lds_dwordx4 v129, s[4:5]
	s_mov_b32 m0, s75
	s_nop 0
	global_load_lds_dwordx4 v130, s[4:5]
	s_barrier
	s_waitcnt lgkmcnt(0)
	s_setprio 1
	s_waitcnt lgkmcnt(0)
	v_mfma_f32_16x16x32_bf16 v[124:127], v[140:143], v[156:159], v[124:127]
	v_mfma_f32_16x16x32_bf16 v[120:123], v[148:151], v[156:159], v[120:123]
	v_mfma_f32_16x16x32_bf16 v[116:119], v[140:143], v[164:167], v[116:119]
	v_mfma_f32_16x16x32_bf16 v[112:115], v[148:151], v[164:167], v[112:115]
	v_mfma_f32_16x16x32_bf16 v[108:111], v[140:143], v[172:175], v[108:111]
	v_mfma_f32_16x16x32_bf16 v[100:103], v[140:143], v[180:183], v[100:103]
	v_mfma_f32_16x16x32_bf16 v[96:99], v[148:151], v[180:183], v[96:99]
	v_mfma_f32_16x16x32_bf16 v[124:127], v[144:147], v[160:163], v[124:127]
	v_mfma_f32_16x16x32_bf16 v[120:123], v[152:155], v[160:163], v[120:123]
	v_mfma_f32_16x16x32_bf16 v[116:119], v[144:147], v[168:171], v[116:119]
	v_mfma_f32_16x16x32_bf16 v[112:115], v[152:155], v[168:171], v[112:115]
	v_mfma_f32_16x16x32_bf16 v[108:111], v[144:147], v[176:179], v[108:111]
	v_mfma_f32_16x16x32_bf16 v[104:107], v[148:151], v[172:175], v[104:107]
	v_mfma_f32_16x16x32_bf16 v[100:103], v[144:147], v[184:187], v[100:103]
	v_mfma_f32_16x16x32_bf16 v[96:99], v[152:155], v[184:187], v[96:99]
	v_mfma_f32_16x16x32_bf16 v[188:191], v[152:155], v[176:179], v[104:107]
	s_setprio 0
	s_barrier
	s_nop 2
	ds_read_b128 v[104:107], v137
	ds_read_b128 v[192:195], v137 offset:1024
	ds_read_b128 v[202:205], v137 offset:2048
	ds_read_b128 v[206:209], v137 offset:3072
	s_barrier
	s_waitcnt lgkmcnt(0)
	s_setprio 1
	s_waitcnt lgkmcnt(0)
	v_mfma_f32_16x16x32_bf16 v[92:95], v[104:107], v[156:159], v[92:95]
	v_mfma_f32_16x16x32_bf16 v[88:91], v[202:205], v[156:159], v[88:91]
	v_mfma_f32_16x16x32_bf16 v[80:83], v[202:205], v[164:167], v[80:83]
	v_mfma_f32_16x16x32_bf16 v[72:75], v[202:205], v[172:175], v[72:75]
	v_mfma_f32_16x16x32_bf16 v[64:67], v[202:205], v[180:183], v[64:67]
	v_mfma_f32_16x16x32_bf16 v[92:95], v[192:195], v[160:163], v[92:95]
	v_mfma_f32_16x16x32_bf16 v[88:91], v[206:209], v[160:163], v[88:91]
	v_mfma_f32_16x16x32_bf16 v[84:87], v[104:107], v[164:167], v[84:87]
	v_mfma_f32_16x16x32_bf16 v[80:83], v[206:209], v[168:171], v[80:83]
	v_mfma_f32_16x16x32_bf16 v[76:79], v[104:107], v[172:175], v[76:79]
	v_mfma_f32_16x16x32_bf16 v[72:75], v[206:209], v[176:179], v[72:75]
	v_mfma_f32_16x16x32_bf16 v[68:71], v[104:107], v[180:183], v[68:71]
	v_mfma_f32_16x16x32_bf16 v[64:67], v[206:209], v[184:187], v[64:67]
	v_mfma_f32_16x16x32_bf16 v[156:159], v[192:195], v[168:171], v[84:87]
	v_mfma_f32_16x16x32_bf16 v[160:163], v[192:195], v[176:179], v[76:79]
	v_mfma_f32_16x16x32_bf16 v[164:167], v[192:195], v[184:187], v[68:71]
	s_setprio 0
	s_barrier
	s_nop 1
	ds_read_b128 v[68:71], v134 offset:16384
	ds_read_b128 v[76:79], v134 offset:17408
	ds_read_b128 v[84:87], v133 offset:16384
	ds_read_b128 v[168:171], v133 offset:17408
	ds_read_b128 v[172:175], v132 offset:16384
	ds_read_b128 v[176:179], v132 offset:17408
	ds_read_b128 v[180:183], v131 offset:16384
	ds_read_b128 v[184:187], v131 offset:17408
	s_waitcnt vmcnt(4)
	s_barrier
	s_waitcnt lgkmcnt(0)
	s_setprio 1
	s_waitcnt lgkmcnt(0)
	v_mfma_f32_16x16x32_bf16 v[60:63], v[140:143], v[68:71], v[60:63]
	v_mfma_f32_16x16x32_bf16 v[56:59], v[148:151], v[68:71], v[56:59]
	v_mfma_f32_16x16x32_bf16 v[48:51], v[148:151], v[84:87], v[48:51]
	v_mfma_f32_16x16x32_bf16 v[32:35], v[148:151], v[180:183], v[32:35]
	v_mfma_f32_16x16x32_bf16 v[60:63], v[144:147], v[76:79], v[60:63]
	v_mfma_f32_16x16x32_bf16 v[56:59], v[152:155], v[76:79], v[56:59]
	v_mfma_f32_16x16x32_bf16 v[52:55], v[140:143], v[84:87], v[52:55]
	v_mfma_f32_16x16x32_bf16 v[48:51], v[152:155], v[168:171], v[48:51]
	v_mfma_f32_16x16x32_bf16 v[44:47], v[140:143], v[172:175], v[44:47]
	v_mfma_f32_16x16x32_bf16 v[40:43], v[148:151], v[172:175], v[40:43]
	v_mfma_f32_16x16x32_bf16 v[36:39], v[140:143], v[180:183], v[36:39]
	v_mfma_f32_16x16x32_bf16 v[32:35], v[152:155], v[184:187], v[32:35]
	v_mfma_f32_16x16x32_bf16 v[210:213], v[144:147], v[168:171], v[52:55]
	v_mfma_f32_16x16x32_bf16 v[214:217], v[144:147], v[176:179], v[44:47]
	v_mfma_f32_16x16x32_bf16 v[218:221], v[152:155], v[176:179], v[40:43]
	v_mfma_f32_16x16x32_bf16 v[138:141], v[144:147], v[184:187], v[36:39]
	s_setprio 0
	s_setprio 1
	v_mfma_f32_16x16x32_bf16 v[24:27], v[202:205], v[68:71], v[24:27]
	v_mfma_f32_16x16x32_bf16 v[20:23], v[104:107], v[84:87], v[20:23]
	v_mfma_f32_16x16x32_bf16 v[28:31], v[104:107], v[68:71], v[28:31]
	v_mfma_f32_16x16x32_bf16 v[24:27], v[206:209], v[76:79], v[24:27]
	v_mfma_f32_16x16x32_bf16 v[20:23], v[192:195], v[168:171], v[20:23]
	v_mfma_f32_16x16x32_bf16 v[16:19], v[202:205], v[84:87], v[16:19]
	v_mfma_f32_16x16x32_bf16 v[12:15], v[104:107], v[172:175], v[12:15]
	v_mfma_f32_16x16x32_bf16 v[8:11], v[202:205], v[172:175], v[8:11]
	v_mfma_f32_16x16x32_bf16 v[4:7], v[104:107], v[180:183], v[4:7]
	v_mfma_f32_16x16x32_bf16 v[0:3], v[202:205], v[180:183], v[0:3]
	v_mfma_f32_16x16x32_bf16 v[142:145], v[192:195], v[76:79], v[28:31]
	v_mfma_f32_16x16x32_bf16 v[146:149], v[206:209], v[168:171], v[16:19]
	v_mfma_f32_16x16x32_bf16 v[150:153], v[192:195], v[176:179], v[12:15]
	v_mfma_f32_16x16x32_bf16 v[168:171], v[206:209], v[176:179], v[8:11]
	v_mfma_f32_16x16x32_bf16 v[172:175], v[192:195], v[184:187], v[4:7]
	v_mfma_f32_16x16x32_bf16 v[176:179], v[206:209], v[184:187], v[0:3]
	s_setprio 0
	s_barrier
	ds_read_b128 v[16:19], v136
	ds_read_b128 v[180:183], v136 offset:1024
	ds_read_b128 v[184:187], v136 offset:2048
	ds_read_b128 v[192:195], v136 offset:3072
	ds_read_b128 v[0:3], v134 offset:32768
	ds_read_b128 v[4:7], v134 offset:33792
	ds_read_b128 v[8:11], v133 offset:32768
	ds_read_b128 v[12:15], v133 offset:33792
	ds_read_b128 v[44:47], v132 offset:32768
	ds_read_b128 v[202:205], v132 offset:33792
	ds_read_b128 v[206:209], v131 offset:32768
	ds_read_b128 v[222:225], v131 offset:33792
	s_waitcnt vmcnt(2)
	s_barrier
	s_waitcnt lgkmcnt(0)
	s_setprio 1
	s_waitcnt lgkmcnt(0)
	v_mfma_f32_16x16x32_bf16 v[28:31], v[16:19], v[0:3], v[124:127]
	v_mfma_f32_16x16x32_bf16 v[52:55], v[180:183], v[4:7], v[28:31]
	v_mfma_f32_16x16x32_bf16 v[28:31], v[184:187], v[0:3], v[120:123]
	v_mfma_f32_16x16x32_bf16 v[104:107], v[192:195], v[4:7], v[28:31]
	v_mfma_f32_16x16x32_bf16 v[28:31], v[16:19], v[8:11], v[116:119]
	v_mfma_f32_16x16x32_bf16 v[68:71], v[180:183], v[12:15], v[28:31]
	v_mfma_f32_16x16x32_bf16 v[28:31], v[184:187], v[8:11], v[112:115]
	v_mfma_f32_16x16x32_bf16 v[116:119], v[192:195], v[12:15], v[28:31]
	v_mfma_f32_16x16x32_bf16 v[28:31], v[16:19], v[44:47], v[108:111]
	v_mfma_f32_16x16x32_bf16 v[76:79], v[180:183], v[202:205], v[28:31]
	v_mfma_f32_16x16x32_bf16 v[28:31], v[184:187], v[44:47], v[188:191]
	v_mfma_f32_16x16x32_bf16 v[108:111], v[192:195], v[202:205], v[28:31]
	v_mfma_f32_16x16x32_bf16 v[28:31], v[16:19], v[206:209], v[100:103]
	v_mfma_f32_16x16x32_bf16 v[84:87], v[180:183], v[222:225], v[28:31]
	v_mfma_f32_16x16x32_bf16 v[28:31], v[184:187], v[206:209], v[96:99]
	v_mfma_f32_16x16x32_bf16 v[96:99], v[192:195], v[222:225], v[28:31]
	s_setprio 0
	s_barrier
	ds_read_b128 v[188:191], v135
	ds_read_b128 v[228:231], v135 offset:1024
	ds_read_b128 v[232:235], v135 offset:2048
	ds_read_b128 v[236:239], v135 offset:3072
	s_waitcnt vmcnt(0)
	s_barrier
	s_waitcnt lgkmcnt(0)
	s_setprio 1
	s_waitcnt lgkmcnt(0)
	v_mfma_f32_16x16x32_bf16 v[28:31], v[188:191], v[0:3], v[92:95]
	v_mfma_f32_16x16x32_bf16 v[0:3], v[232:235], v[0:3], v[88:91]
	v_mfma_f32_16x16x32_bf16 v[28:31], v[228:231], v[4:7], v[28:31]
	v_mfma_f32_16x16x32_bf16 v[0:3], v[236:239], v[4:7], v[0:3]
	v_mfma_f32_16x16x32_bf16 v[4:7], v[188:191], v[8:11], v[156:159]
	v_mfma_f32_16x16x32_bf16 v[36:39], v[228:231], v[12:15], v[4:7]
	v_mfma_f32_16x16x32_bf16 v[4:7], v[232:235], v[8:11], v[80:83]
	v_mfma_f32_16x16x32_bf16 v[4:7], v[236:239], v[12:15], v[4:7]
	v_mfma_f32_16x16x32_bf16 v[8:11], v[188:191], v[44:47], v[160:163]
	v_mfma_f32_16x16x32_bf16 v[12:15], v[188:191], v[206:209], v[164:167]
	v_mfma_f32_16x16x32_bf16 v[40:43], v[228:231], v[202:205], v[8:11]
	v_mfma_f32_16x16x32_bf16 v[8:11], v[232:235], v[44:47], v[72:75]
	v_mfma_f32_16x16x32_bf16 v[44:47], v[228:231], v[222:225], v[12:15]
	v_mfma_f32_16x16x32_bf16 v[12:15], v[232:235], v[206:209], v[64:67]
	v_mfma_f32_16x16x32_bf16 v[8:11], v[236:239], v[202:205], v[8:11]
	v_mfma_f32_16x16x32_bf16 v[12:15], v[236:239], v[222:225], v[12:15]
	s_setprio 0
	s_barrier
	ds_read_b128 v[64:67], v134 offset:49152
	ds_read_b128 v[134:137], v134 offset:50176
	ds_read_b128 v[154:157], v133 offset:49152
	ds_read_b128 v[158:161], v133 offset:50176
	ds_read_b128 v[162:165], v132 offset:49152
	ds_read_b128 v[202:205], v132 offset:50176
	ds_read_b128 v[206:209], v131 offset:49152
	ds_read_b128 v[130:133], v131 offset:50176
	s_barrier
	s_waitcnt lgkmcnt(0)
	s_setprio 1
	s_waitcnt lgkmcnt(0)
	v_mfma_f32_16x16x32_bf16 v[56:59], v[184:187], v[64:67], v[56:59]
	v_mfma_f32_16x16x32_bf16 v[48:51], v[184:187], v[154:157], v[48:51]
	v_mfma_f32_16x16x32_bf16 v[60:63], v[16:19], v[64:67], v[60:63]
	v_mfma_f32_16x16x32_bf16 v[92:95], v[192:195], v[134:137], v[56:59]
	v_mfma_f32_16x16x32_bf16 v[56:59], v[16:19], v[154:157], v[210:213]
	v_mfma_f32_16x16x32_bf16 v[88:91], v[192:195], v[158:161], v[48:51]
	v_mfma_f32_16x16x32_bf16 v[48:51], v[16:19], v[162:165], v[214:217]
	v_mfma_f32_16x16x32_bf16 v[16:19], v[16:19], v[206:209], v[138:141]
	v_mfma_f32_16x16x32_bf16 v[120:123], v[180:183], v[202:205], v[48:51]
	v_mfma_f32_16x16x32_bf16 v[48:51], v[184:187], v[162:165], v[218:221]
	v_mfma_f32_16x16x32_bf16 v[124:127], v[180:183], v[130:133], v[16:19]
	v_mfma_f32_16x16x32_bf16 v[16:19], v[184:187], v[206:209], v[32:35]
	v_mfma_f32_16x16x32_bf16 v[100:103], v[180:183], v[134:137], v[60:63]
	v_mfma_f32_16x16x32_bf16 v[112:115], v[180:183], v[158:161], v[56:59]
	v_mfma_f32_16x16x32_bf16 v[80:83], v[192:195], v[202:205], v[48:51]
	v_mfma_f32_16x16x32_bf16 v[72:75], v[192:195], v[130:133], v[16:19]
	s_setprio 0
	s_setprio 1
	v_mfma_f32_16x16x32_bf16 v[16:19], v[188:191], v[64:67], v[142:145]
	v_mfma_f32_16x16x32_bf16 v[48:51], v[228:231], v[134:137], v[16:19]
	v_mfma_f32_16x16x32_bf16 v[16:19], v[232:235], v[64:67], v[24:27]
	v_mfma_f32_16x16x32_bf16 v[20:23], v[188:191], v[154:157], v[20:23]
	v_mfma_f32_16x16x32_bf16 v[24:27], v[188:191], v[162:165], v[150:153]
	v_mfma_f32_16x16x32_bf16 v[32:35], v[188:191], v[206:209], v[172:175]
	v_mfma_f32_16x16x32_bf16 v[56:59], v[228:231], v[158:161], v[20:23]
	v_mfma_f32_16x16x32_bf16 v[20:23], v[232:235], v[154:157], v[146:149]
	v_mfma_f32_16x16x32_bf16 v[60:63], v[228:231], v[202:205], v[24:27]
	v_mfma_f32_16x16x32_bf16 v[24:27], v[232:235], v[162:165], v[168:171]
	v_mfma_f32_16x16x32_bf16 v[64:67], v[228:231], v[130:133], v[32:35]
	v_mfma_f32_16x16x32_bf16 v[32:35], v[232:235], v[206:209], v[176:179]
	v_mfma_f32_16x16x32_bf16 v[16:19], v[236:239], v[134:137], v[16:19]
	v_mfma_f32_16x16x32_bf16 v[20:23], v[236:239], v[158:161], v[20:23]
	v_mfma_f32_16x16x32_bf16 v[24:27], v[236:239], v[202:205], v[24:27]
	v_mfma_f32_16x16x32_bf16 v[32:35], v[236:239], v[130:133], v[32:35]
	s_setprio 0
	s_movk_i32 s4, 0x100
	v_cmp_gt_u32_e32 vcc, s4, v128
	s_barrier
	s_and_saveexec_b64 s[4:5], vcc
	s_cbranch_execz .LBB0_95
	s_barrier
	s_branch .LBB0_95

.Lhf_192:
	ds_read_b128 v[140:143], v129
	ds_read_b128 v[144:147], v129 offset:1024
	ds_read_b128 v[148:151], v129 offset:2048
	ds_read_b128 v[152:155], v129 offset:3072
	s_add_u32 s28, s56, s4
	s_addc_u32 s29, s57, s5
	ds_read_b128 v[156:159], v136
	ds_read_b128 v[160:163], v136 offset:1024
	ds_read_b128 v[164:167], v135
	ds_read_b128 v[168:171], v135 offset:1024
	ds_read_b128 v[172:175], v134
	ds_read_b128 v[176:179], v134 offset:1024
	ds_read_b128 v[180:183], v133
	ds_read_b128 v[184:187], v133 offset:1024
	s_add_i32 s40, s52, 0xc000
	s_mov_b32 m0, s40
	s_add_i32 s39, s52, 0xe000
	s_mov_b32 m0, s39
	s_nop 0
	s_waitcnt lgkmcnt(8)
	s_barrier
	s_waitcnt lgkmcnt(0)
	s_setprio 0
	s_waitcnt lgkmcnt(0)
	v_mfma_f32_16x16x32_bf16 v[124:127], v[140:143], v[156:159], v[124:127]
	v_mfma_f32_16x16x32_bf16 v[120:123], v[148:151], v[156:159], v[120:123]
	v_mfma_f32_16x16x32_bf16 v[116:119], v[140:143], v[164:167], v[116:119]
	v_mfma_f32_16x16x32_bf16 v[112:115], v[148:151], v[164:167], v[112:115]
	v_mfma_f32_16x16x32_bf16 v[108:111], v[140:143], v[172:175], v[108:111]
	v_mfma_f32_16x16x32_bf16 v[104:107], v[148:151], v[172:175], v[104:107]
	v_mfma_f32_16x16x32_bf16 v[100:103], v[140:143], v[180:183], v[100:103]
	v_mfma_f32_16x16x32_bf16 v[96:99], v[148:151], v[180:183], v[96:99]
	v_mfma_f32_16x16x32_bf16 v[124:127], v[144:147], v[160:163], v[124:127]
	v_mfma_f32_16x16x32_bf16 v[120:123], v[152:155], v[160:163], v[120:123]
	v_mfma_f32_16x16x32_bf16 v[116:119], v[144:147], v[168:171], v[116:119]
	v_mfma_f32_16x16x32_bf16 v[112:115], v[152:155], v[168:171], v[112:115]
	v_mfma_f32_16x16x32_bf16 v[108:111], v[144:147], v[176:179], v[108:111]
	v_mfma_f32_16x16x32_bf16 v[104:107], v[152:155], v[176:179], v[104:107]
	v_mfma_f32_16x16x32_bf16 v[100:103], v[144:147], v[184:187], v[100:103]
	v_mfma_f32_16x16x32_bf16 v[96:99], v[152:155], v[184:187], v[96:99]
	s_setprio 1
	s_barrier
	s_add_u32 s58, s56, s36
	s_addc_u32 s59, s57, s37
	ds_read_b128 v[188:191], v139
	ds_read_b128 v[192:195], v139 offset:1024
	ds_read_b128 v[202:205], v139 offset:2048
	ds_read_b128 v[206:209], v139 offset:3072
	s_add_i32 m0, s52, 0x10000
	s_add_u32 s98, s58, s46
	s_addc_u32 s99, s59, s47
	global_load_lds_dwordx4 v128, s[98:99]
	s_add_i32 m0, s52, 0x12000
	s_nop 0
	global_load_lds_dwordx4 v130, s[98:99]
	s_barrier
	s_waitcnt lgkmcnt(0)
	s_setprio 0
	s_waitcnt lgkmcnt(0)
	v_mfma_f32_16x16x32_bf16 v[92:95], v[188:191], v[156:159], v[92:95]
	v_mfma_f32_16x16x32_bf16 v[88:91], v[202:205], v[156:159], v[88:91]
	v_mfma_f32_16x16x32_bf16 v[84:87], v[188:191], v[164:167], v[84:87]
	v_mfma_f32_16x16x32_bf16 v[80:83], v[202:205], v[164:167], v[80:83]
	v_mfma_f32_16x16x32_bf16 v[76:79], v[188:191], v[172:175], v[76:79]
	v_mfma_f32_16x16x32_bf16 v[72:75], v[202:205], v[172:175], v[72:75]
	v_mfma_f32_16x16x32_bf16 v[68:71], v[188:191], v[180:183], v[68:71]
	v_mfma_f32_16x16x32_bf16 v[64:67], v[202:205], v[180:183], v[64:67]
	v_mfma_f32_16x16x32_bf16 v[92:95], v[192:195], v[160:163], v[92:95]
	v_mfma_f32_16x16x32_bf16 v[88:91], v[206:209], v[160:163], v[88:91]
	v_mfma_f32_16x16x32_bf16 v[84:87], v[192:195], v[168:171], v[84:87]
	v_mfma_f32_16x16x32_bf16 v[80:83], v[206:209], v[168:171], v[80:83]
	v_mfma_f32_16x16x32_bf16 v[76:79], v[192:195], v[176:179], v[76:79]
	v_mfma_f32_16x16x32_bf16 v[72:75], v[206:209], v[176:179], v[72:75]
	v_mfma_f32_16x16x32_bf16 v[68:71], v[192:195], v[184:187], v[68:71]
	v_mfma_f32_16x16x32_bf16 v[64:67], v[206:209], v[184:187], v[64:67]
	s_setprio 1
	s_barrier
	s_mov_b32 m0, s52
	s_add_u32 s98, s28, s48
	s_addc_u32 s99, s29, s49
	global_load_lds_dwordx4 v128, s[98:99]
	s_add_i32 m0, s52, 0x2000
	s_nop 0
	global_load_lds_dwordx4 v130, s[98:99]
	s_waitcnt vmcnt(4)
	s_barrier
	s_add_i32 m0, s52, 0x14000
	s_add_u32 s98, s58, s50
	s_addc_u32 s99, s59, s51
	global_load_lds_dwordx4 v128, s[98:99]
	s_add_i32 m0, s52, 0x16000
	s_nop 0
	global_load_lds_dwordx4 v130, s[98:99]
	s_barrier
	ds_read_b128 v[140:143], v138
	ds_read_b128 v[144:147], v138 offset:1024
	ds_read_b128 v[148:151], v138 offset:2048
	ds_read_b128 v[152:155], v138 offset:3072
	ds_read_b128 v[156:159], v136 offset:32768
	ds_read_b128 v[160:163], v136 offset:33792
	ds_read_b128 v[164:167], v135 offset:32768
	ds_read_b128 v[168:171], v135 offset:33792
	ds_read_b128 v[172:175], v134 offset:32768
	ds_read_b128 v[176:179], v134 offset:33792
	ds_read_b128 v[180:183], v133 offset:32768
	ds_read_b128 v[184:187], v133 offset:33792
	s_add_i32 m0, s52, 0x4000
	s_add_i32 m0, s52, 0x6000
	s_nop 0
	s_waitcnt lgkmcnt(8)
	s_barrier
	s_waitcnt lgkmcnt(0)
	s_setprio 0
	s_waitcnt lgkmcnt(0)
	v_mfma_f32_16x16x32_bf16 v[124:127], v[140:143], v[156:159], v[124:127]
	v_mfma_f32_16x16x32_bf16 v[120:123], v[148:151], v[156:159], v[120:123]
	v_mfma_f32_16x16x32_bf16 v[116:119], v[140:143], v[164:167], v[116:119]
	v_mfma_f32_16x16x32_bf16 v[112:115], v[148:151], v[164:167], v[112:115]
	v_mfma_f32_16x16x32_bf16 v[108:111], v[140:143], v[172:175], v[108:111]
	v_mfma_f32_16x16x32_bf16 v[104:107], v[148:151], v[172:175], v[104:107]
	v_mfma_f32_16x16x32_bf16 v[100:103], v[140:143], v[180:183], v[100:103]
	v_mfma_f32_16x16x32_bf16 v[96:99], v[148:151], v[180:183], v[96:99]
	v_mfma_f32_16x16x32_bf16 v[124:127], v[144:147], v[160:163], v[124:127]
	v_mfma_f32_16x16x32_bf16 v[120:123], v[152:155], v[160:163], v[120:123]
	v_mfma_f32_16x16x32_bf16 v[116:119], v[144:147], v[168:171], v[116:119]
	v_mfma_f32_16x16x32_bf16 v[112:115], v[152:155], v[168:171], v[112:115]
	v_mfma_f32_16x16x32_bf16 v[108:111], v[144:147], v[176:179], v[108:111]
	v_mfma_f32_16x16x32_bf16 v[104:107], v[152:155], v[176:179], v[104:107]
	v_mfma_f32_16x16x32_bf16 v[100:103], v[144:147], v[184:187], v[100:103]
	v_mfma_f32_16x16x32_bf16 v[96:99], v[152:155], v[184:187], v[96:99]
	s_setprio 1
	s_barrier
	ds_read_b128 v[188:191], v137
	ds_read_b128 v[192:195], v137 offset:1024
	ds_read_b128 v[202:205], v137 offset:2048
	ds_read_b128 v[206:209], v137 offset:3072
	s_mov_b32 m0, s7
	s_add_u32 s98, s58, s68
	s_addc_u32 s99, s59, s69
	global_load_lds_dwordx4 v128, s[98:99]
	s_mov_b32 m0, s53
	s_nop 0
	global_load_lds_dwordx4 v130, s[98:99]
	s_barrier
	s_waitcnt lgkmcnt(0)
	s_setprio 0
	s_waitcnt lgkmcnt(0)
	v_mfma_f32_16x16x32_bf16 v[92:95], v[188:191], v[156:159], v[92:95]
	v_mfma_f32_16x16x32_bf16 v[88:91], v[202:205], v[156:159], v[88:91]
	v_mfma_f32_16x16x32_bf16 v[84:87], v[188:191], v[164:167], v[84:87]
	v_mfma_f32_16x16x32_bf16 v[80:83], v[202:205], v[164:167], v[80:83]
	v_mfma_f32_16x16x32_bf16 v[76:79], v[188:191], v[172:175], v[76:79]
	v_mfma_f32_16x16x32_bf16 v[72:75], v[202:205], v[172:175], v[72:75]
	v_mfma_f32_16x16x32_bf16 v[68:71], v[188:191], v[180:183], v[68:71]
	v_mfma_f32_16x16x32_bf16 v[64:67], v[202:205], v[180:183], v[64:67]
	v_mfma_f32_16x16x32_bf16 v[92:95], v[192:195], v[160:163], v[92:95]
	v_mfma_f32_16x16x32_bf16 v[88:91], v[206:209], v[160:163], v[88:91]
	v_mfma_f32_16x16x32_bf16 v[84:87], v[192:195], v[168:171], v[84:87]
	v_mfma_f32_16x16x32_bf16 v[80:83], v[206:209], v[168:171], v[80:83]
	v_mfma_f32_16x16x32_bf16 v[76:79], v[192:195], v[176:179], v[76:79]
	v_mfma_f32_16x16x32_bf16 v[72:75], v[206:209], v[176:179], v[72:75]
	v_mfma_f32_16x16x32_bf16 v[68:71], v[192:195], v[184:187], v[68:71]
	v_mfma_f32_16x16x32_bf16 v[64:67], v[206:209], v[184:187], v[64:67]
	s_setprio 1
	v_mov_b32_e32 v210, v130
	s_barrier
	v_mov_b32_e32 v211, v197
	s_mov_b32 m0, s9
	s_add_u32 s98, s28, s70
	s_addc_u32 s99, s29, s71
	global_load_lds_dwordx4 v128, s[98:99]
	s_mov_b32 m0, s33
	s_nop 0
	global_load_lds_dwordx4 v130, s[98:99]
	s_waitcnt vmcnt(4)
	s_barrier
	v_mov_b32_e32 v196, v128
	s_mov_b32 m0, s65
	s_add_u32 s98, s58, s72
	s_addc_u32 s99, s59, s73
	global_load_lds_dwordx4 v128, s[98:99]
	s_mov_b32 m0, s66
	s_nop 0
	global_load_lds_dwordx4 v130, s[98:99]
	s_barrier
	s_add_i32 s38, s38, 2
	s_add_u32 s56, s56, 0x100
	s_addc_u32 s57, s57, 0
	s_cmp_lt_u32 s38, 28
	s_cbranch_scc1 .Lhf_192
	s_setprio 0
	s_lshl_b64 s[4:5], s[10:11], 12
	v_readlane_b32 s10, v254, 12
	v_readlane_b32 s11, v254, 13
	s_add_u32 s4, s10, s4
	s_addc_u32 s5, s11, s5
	ds_read_b128 v[140:143], v129
	ds_read_b128 v[144:147], v129 offset:1024
	ds_read_b128 v[148:151], v129 offset:2048
	ds_read_b128 v[152:155], v129 offset:3072
	ds_read_b128 v[156:159], v136
	ds_read_b128 v[160:163], v136 offset:1024
	ds_read_b128 v[164:167], v135
	ds_read_b128 v[168:171], v135 offset:1024
	ds_read_b128 v[172:175], v134
	ds_read_b128 v[176:179], v134 offset:1024
	ds_read_b128 v[180:183], v133
	ds_read_b128 v[184:187], v133 offset:1024
	v_mov_b32_e32 v129, v197
	v_lshl_add_u64 v[128:129], s[4:5], 0, v[128:129]
	s_mov_b64 s[10:11], 0xf80
	s_mov_b32 m0, s40
	v_lshl_add_u64 v[128:129], v[128:129], 0, s[10:11]
	v_mov_b32_e32 v131, v197
	v_lshl_add_u64 v[128:129], s[4:5], 0, v[130:131]
	v_lshl_add_u64 v[128:129], v[128:129], 0, s[10:11]
	s_mov_b32 m0, s39
	s_nop 0
	s_barrier
	s_waitcnt lgkmcnt(0)
	s_setprio 1
	s_waitcnt lgkmcnt(0)
	v_mfma_f32_16x16x32_bf16 v[124:127], v[140:143], v[156:159], v[124:127]
	v_mfma_f32_16x16x32_bf16 v[116:119], v[140:143], v[164:167], v[116:119]
	v_mfma_f32_16x16x32_bf16 v[112:115], v[148:151], v[164:167], v[112:115]
	v_mfma_f32_16x16x32_bf16 v[108:111], v[140:143], v[172:175], v[108:111]
	v_mfma_f32_16x16x32_bf16 v[104:107], v[148:151], v[172:175], v[104:107]
	v_mfma_f32_16x16x32_bf16 v[100:103], v[140:143], v[180:183], v[100:103]
	v_mfma_f32_16x16x32_bf16 v[96:99], v[148:151], v[180:183], v[96:99]
	v_mfma_f32_16x16x32_bf16 v[124:127], v[144:147], v[160:163], v[124:127]
	v_mfma_f32_16x16x32_bf16 v[120:123], v[148:151], v[156:159], v[120:123]
	v_mfma_f32_16x16x32_bf16 v[116:119], v[144:147], v[168:171], v[116:119]
	v_mfma_f32_16x16x32_bf16 v[112:115], v[152:155], v[168:171], v[112:115]
	v_mfma_f32_16x16x32_bf16 v[108:111], v[144:147], v[176:179], v[108:111]
	v_mfma_f32_16x16x32_bf16 v[104:107], v[152:155], v[176:179], v[104:107]
	v_mfma_f32_16x16x32_bf16 v[100:103], v[144:147], v[184:187], v[100:103]
	v_mfma_f32_16x16x32_bf16 v[96:99], v[152:155], v[184:187], v[96:99]
	v_mfma_f32_16x16x32_bf16 v[128:131], v[152:155], v[160:163], v[120:123]
	s_setprio 0
	s_barrier
	s_nop 0
	ds_read_b128 v[120:123], v139
	ds_read_b128 v[188:191], v139 offset:1024
	ds_read_b128 v[192:195], v139 offset:2048
	ds_read_b128 v[202:205], v139 offset:3072
	s_barrier
	s_waitcnt lgkmcnt(0)
	s_setprio 1
	s_waitcnt lgkmcnt(0)
	v_mfma_f32_16x16x32_bf16 v[76:79], v[120:123], v[172:175], v[76:79]
	v_mfma_f32_16x16x32_bf16 v[68:71], v[120:123], v[180:183], v[68:71]
	v_mfma_f32_16x16x32_bf16 v[64:67], v[192:195], v[180:183], v[64:67]
	v_mfma_f32_16x16x32_bf16 v[92:95], v[120:123], v[156:159], v[92:95]
	v_mfma_f32_16x16x32_bf16 v[88:91], v[192:195], v[156:159], v[88:91]
	v_mfma_f32_16x16x32_bf16 v[84:87], v[120:123], v[164:167], v[84:87]
	v_mfma_f32_16x16x32_bf16 v[80:83], v[192:195], v[164:167], v[80:83]
	v_mfma_f32_16x16x32_bf16 v[76:79], v[188:191], v[176:179], v[76:79]
	v_mfma_f32_16x16x32_bf16 v[72:75], v[192:195], v[172:175], v[72:75]
	v_mfma_f32_16x16x32_bf16 v[68:71], v[188:191], v[184:187], v[68:71]
	v_mfma_f32_16x16x32_bf16 v[64:67], v[202:205], v[184:187], v[64:67]
	v_mfma_f32_16x16x32_bf16 v[206:209], v[188:191], v[160:163], v[92:95]
	v_mfma_f32_16x16x32_bf16 v[156:159], v[202:205], v[160:163], v[88:91]
	v_mfma_f32_16x16x32_bf16 v[160:163], v[188:191], v[168:171], v[84:87]
	v_mfma_f32_16x16x32_bf16 v[164:167], v[202:205], v[168:171], v[80:83]
	v_mfma_f32_16x16x32_bf16 v[168:171], v[202:205], v[176:179], v[72:75]
	s_setprio 0
	s_barrier
	s_nop 0
	s_waitcnt vmcnt(2)
	s_barrier
	s_waitcnt lgkmcnt(0)
	s_setprio 1
	s_waitcnt lgkmcnt(0)
	s_setprio 0
	s_setprio 1
	s_setprio 0
	s_barrier
	s_nop 0
	ds_read_b128 v[8:11], v138
	ds_read_b128 v[16:19], v138 offset:1024
	ds_read_b128 v[176:179], v138 offset:2048
	ds_read_b128 v[180:183], v138 offset:3072
	ds_read_b128 v[20:23], v136 offset:32768
	ds_read_b128 v[24:27], v136 offset:33792
	ds_read_b128 v[28:31], v135 offset:32768
	ds_read_b128 v[56:59], v135 offset:33792
	ds_read_b128 v[188:191], v134 offset:32768
	ds_read_b128 v[192:195], v134 offset:33792
	ds_read_b128 v[202:205], v133 offset:32768
	ds_read_b128 v[210:213], v133 offset:33792
	s_waitcnt vmcnt(0)
	s_barrier
	s_waitcnt lgkmcnt(0)
	s_setprio 1
	s_waitcnt lgkmcnt(0)
	v_mfma_f32_16x16x32_bf16 v[72:75], v[8:11], v[20:23], v[124:127]
	v_mfma_f32_16x16x32_bf16 v[120:123], v[16:19], v[24:27], v[72:75]
	v_mfma_f32_16x16x32_bf16 v[72:75], v[176:179], v[20:23], v[128:131]
	v_mfma_f32_16x16x32_bf16 v[124:127], v[180:183], v[24:27], v[72:75]
	v_mfma_f32_16x16x32_bf16 v[72:75], v[8:11], v[28:31], v[116:119]
	v_mfma_f32_16x16x32_bf16 v[116:119], v[16:19], v[56:59], v[72:75]
	v_mfma_f32_16x16x32_bf16 v[72:75], v[176:179], v[28:31], v[112:115]
	v_mfma_f32_16x16x32_bf16 v[112:115], v[180:183], v[56:59], v[72:75]
	v_mfma_f32_16x16x32_bf16 v[72:75], v[8:11], v[188:191], v[108:111]
	v_mfma_f32_16x16x32_bf16 v[88:91], v[16:19], v[192:195], v[72:75]
	v_mfma_f32_16x16x32_bf16 v[72:75], v[176:179], v[188:191], v[104:107]
	v_mfma_f32_16x16x32_bf16 v[92:95], v[180:183], v[192:195], v[72:75]
	v_mfma_f32_16x16x32_bf16 v[72:75], v[8:11], v[202:205], v[100:103]
	v_mfma_f32_16x16x32_bf16 v[84:87], v[16:19], v[210:213], v[72:75]
	v_mfma_f32_16x16x32_bf16 v[72:75], v[176:179], v[202:205], v[96:99]
	v_mfma_f32_16x16x32_bf16 v[80:83], v[180:183], v[210:213], v[72:75]
	s_setprio 0
	s_barrier
	ds_read_b128 v[128:131], v137
	ds_read_b128 v[214:217], v137 offset:1024
	ds_read_b128 v[218:221], v137 offset:2048
	ds_read_b128 v[222:225], v137 offset:3072
	s_waitcnt vmcnt(0)
	s_barrier
	s_waitcnt lgkmcnt(0)
	s_setprio 1
	s_waitcnt lgkmcnt(0)
	v_mfma_f32_16x16x32_bf16 v[72:75], v[128:131], v[20:23], v[206:209]
	v_mfma_f32_16x16x32_bf16 v[20:23], v[218:221], v[20:23], v[156:159]
	v_mfma_f32_16x16x32_bf16 v[108:111], v[222:225], v[24:27], v[20:23]
	v_mfma_f32_16x16x32_bf16 v[20:23], v[128:131], v[28:31], v[160:163]
	v_mfma_f32_16x16x32_bf16 v[100:103], v[214:217], v[56:59], v[20:23]
	v_mfma_f32_16x16x32_bf16 v[20:23], v[218:221], v[28:31], v[164:167]
	v_mfma_f32_16x16x32_bf16 v[96:99], v[222:225], v[56:59], v[20:23]
	v_mfma_f32_16x16x32_bf16 v[20:23], v[128:131], v[188:191], v[76:79]
	v_mfma_f32_16x16x32_bf16 v[104:107], v[214:217], v[24:27], v[72:75]
	v_mfma_f32_16x16x32_bf16 v[72:75], v[214:217], v[192:195], v[20:23]
	v_mfma_f32_16x16x32_bf16 v[20:23], v[218:221], v[188:191], v[168:171]
	v_mfma_f32_16x16x32_bf16 v[76:79], v[222:225], v[192:195], v[20:23]
	v_mfma_f32_16x16x32_bf16 v[20:23], v[128:131], v[202:205], v[68:71]
	v_mfma_f32_16x16x32_bf16 v[68:71], v[214:217], v[210:213], v[20:23]
	v_mfma_f32_16x16x32_bf16 v[20:23], v[218:221], v[202:205], v[64:67]
	v_mfma_f32_16x16x32_bf16 v[64:67], v[222:225], v[210:213], v[20:23]
	s_setprio 0
	s_barrier
	s_barrier
	s_waitcnt lgkmcnt(0)
	s_setprio 1
	s_waitcnt lgkmcnt(0)
	s_setprio 0
	s_setprio 1
	s_setprio 0
	s_movk_i32 s4, 0x100
	v_cmp_gt_u32_e32 vcc, s4, v132
	s_barrier
	s_and_saveexec_b64 s[4:5], vcc
	s_cbranch_execz .Lhf_195
	s_barrier

.LBB0_192:
	ds_read_b128 v[140:143], v129
	ds_read_b128 v[144:147], v129 offset:1024
	ds_read_b128 v[148:151], v129 offset:2048
	ds_read_b128 v[152:155], v129 offset:3072
	s_add_u32 s28, s56, s4
	s_addc_u32 s29, s57, s5
	ds_read_b128 v[156:159], v136
	ds_read_b128 v[160:163], v136 offset:1024
	ds_read_b128 v[164:167], v135
	ds_read_b128 v[168:171], v135 offset:1024
	ds_read_b128 v[172:175], v134
	ds_read_b128 v[176:179], v134 offset:1024
	ds_read_b128 v[180:183], v133
	ds_read_b128 v[184:187], v133 offset:1024
	s_add_i32 s40, s52, 0xc000
	s_mov_b32 m0, s40
	s_add_i32 s39, s52, 0xe000
	s_add_u32 s98, s28, s44
	s_addc_u32 s99, s29, s45
	global_load_lds_dwordx4 v128, s[98:99]
	s_mov_b32 m0, s39
	s_nop 0
	global_load_lds_dwordx4 v130, s[98:99]
	s_waitcnt lgkmcnt(8)
	s_barrier
	s_waitcnt lgkmcnt(0)
	s_setprio 0
	s_waitcnt lgkmcnt(0)
	v_mfma_f32_16x16x32_bf16 v[124:127], v[140:143], v[156:159], v[124:127]
	v_mfma_f32_16x16x32_bf16 v[120:123], v[148:151], v[156:159], v[120:123]
	v_mfma_f32_16x16x32_bf16 v[116:119], v[140:143], v[164:167], v[116:119]
	v_mfma_f32_16x16x32_bf16 v[112:115], v[148:151], v[164:167], v[112:115]
	v_mfma_f32_16x16x32_bf16 v[108:111], v[140:143], v[172:175], v[108:111]
	v_mfma_f32_16x16x32_bf16 v[104:107], v[148:151], v[172:175], v[104:107]
	v_mfma_f32_16x16x32_bf16 v[100:103], v[140:143], v[180:183], v[100:103]
	v_mfma_f32_16x16x32_bf16 v[96:99], v[148:151], v[180:183], v[96:99]
	v_mfma_f32_16x16x32_bf16 v[124:127], v[144:147], v[160:163], v[124:127]
	v_mfma_f32_16x16x32_bf16 v[120:123], v[152:155], v[160:163], v[120:123]
	v_mfma_f32_16x16x32_bf16 v[116:119], v[144:147], v[168:171], v[116:119]
	v_mfma_f32_16x16x32_bf16 v[112:115], v[152:155], v[168:171], v[112:115]
	v_mfma_f32_16x16x32_bf16 v[108:111], v[144:147], v[176:179], v[108:111]
	v_mfma_f32_16x16x32_bf16 v[104:107], v[152:155], v[176:179], v[104:107]
	v_mfma_f32_16x16x32_bf16 v[100:103], v[144:147], v[184:187], v[100:103]
	v_mfma_f32_16x16x32_bf16 v[96:99], v[152:155], v[184:187], v[96:99]
	s_setprio 1
	s_barrier
	s_add_u32 s58, s56, s36
	s_addc_u32 s59, s57, s37
	ds_read_b128 v[188:191], v139
	ds_read_b128 v[192:195], v139 offset:1024
	ds_read_b128 v[202:205], v139 offset:2048
	ds_read_b128 v[206:209], v139 offset:3072
	s_add_i32 m0, s52, 0x10000
	s_add_u32 s98, s58, s46
	s_addc_u32 s99, s59, s47
	global_load_lds_dwordx4 v128, s[98:99]
	s_add_i32 m0, s52, 0x12000
	s_nop 0
	global_load_lds_dwordx4 v130, s[98:99]
	s_barrier
	s_waitcnt lgkmcnt(0)
	s_setprio 0
	s_waitcnt lgkmcnt(0)
	v_mfma_f32_16x16x32_bf16 v[92:95], v[188:191], v[156:159], v[92:95]
	v_mfma_f32_16x16x32_bf16 v[88:91], v[202:205], v[156:159], v[88:91]
	v_mfma_f32_16x16x32_bf16 v[84:87], v[188:191], v[164:167], v[84:87]
	v_mfma_f32_16x16x32_bf16 v[80:83], v[202:205], v[164:167], v[80:83]
	v_mfma_f32_16x16x32_bf16 v[76:79], v[188:191], v[172:175], v[76:79]
	v_mfma_f32_16x16x32_bf16 v[72:75], v[202:205], v[172:175], v[72:75]
	v_mfma_f32_16x16x32_bf16 v[68:71], v[188:191], v[180:183], v[68:71]
	v_mfma_f32_16x16x32_bf16 v[64:67], v[202:205], v[180:183], v[64:67]
	v_mfma_f32_16x16x32_bf16 v[92:95], v[192:195], v[160:163], v[92:95]
	v_mfma_f32_16x16x32_bf16 v[88:91], v[206:209], v[160:163], v[88:91]
	v_mfma_f32_16x16x32_bf16 v[84:87], v[192:195], v[168:171], v[84:87]
	v_mfma_f32_16x16x32_bf16 v[80:83], v[206:209], v[168:171], v[80:83]
	v_mfma_f32_16x16x32_bf16 v[76:79], v[192:195], v[176:179], v[76:79]
	v_mfma_f32_16x16x32_bf16 v[72:75], v[206:209], v[176:179], v[72:75]
	v_mfma_f32_16x16x32_bf16 v[68:71], v[192:195], v[184:187], v[68:71]
	v_mfma_f32_16x16x32_bf16 v[64:67], v[206:209], v[184:187], v[64:67]
	s_setprio 1
	s_barrier
	ds_read_b128 v[156:159], v136 offset:16384
	ds_read_b128 v[160:163], v136 offset:17408
	ds_read_b128 v[164:167], v135 offset:16384
	ds_read_b128 v[168:171], v135 offset:17408
	ds_read_b128 v[172:175], v134 offset:16384
	ds_read_b128 v[176:179], v134 offset:17408
	ds_read_b128 v[180:183], v133 offset:16384
	ds_read_b128 v[184:187], v133 offset:17408
	s_mov_b32 m0, s52
	s_add_u32 s98, s28, s48
	s_addc_u32 s99, s29, s49
	global_load_lds_dwordx4 v128, s[98:99]
	s_add_i32 m0, s52, 0x2000
	s_nop 0
	global_load_lds_dwordx4 v130, s[98:99]
	s_barrier
	s_waitcnt lgkmcnt(0)
	s_setprio 0
	s_waitcnt lgkmcnt(0)
	v_mfma_f32_16x16x32_bf16 v[60:63], v[140:143], v[156:159], v[60:63]
	v_mfma_f32_16x16x32_bf16 v[56:59], v[148:151], v[156:159], v[56:59]
	v_mfma_f32_16x16x32_bf16 v[52:55], v[140:143], v[164:167], v[52:55]
	v_mfma_f32_16x16x32_bf16 v[48:51], v[148:151], v[164:167], v[48:51]
	v_mfma_f32_16x16x32_bf16 v[44:47], v[140:143], v[172:175], v[44:47]
	v_mfma_f32_16x16x32_bf16 v[40:43], v[148:151], v[172:175], v[40:43]
	v_mfma_f32_16x16x32_bf16 v[36:39], v[140:143], v[180:183], v[36:39]
	v_mfma_f32_16x16x32_bf16 v[32:35], v[148:151], v[180:183], v[32:35]
	v_mfma_f32_16x16x32_bf16 v[60:63], v[144:147], v[160:163], v[60:63]
	v_mfma_f32_16x16x32_bf16 v[56:59], v[152:155], v[160:163], v[56:59]
	v_mfma_f32_16x16x32_bf16 v[52:55], v[144:147], v[168:171], v[52:55]
	v_mfma_f32_16x16x32_bf16 v[48:51], v[152:155], v[168:171], v[48:51]
	v_mfma_f32_16x16x32_bf16 v[44:47], v[144:147], v[176:179], v[44:47]
	v_mfma_f32_16x16x32_bf16 v[40:43], v[152:155], v[176:179], v[40:43]
	v_mfma_f32_16x16x32_bf16 v[36:39], v[144:147], v[184:187], v[36:39]
	v_mfma_f32_16x16x32_bf16 v[32:35], v[152:155], v[184:187], v[32:35]
	s_setprio 1
	s_barrier
	s_add_i32 m0, s52, 0x14000
	s_add_u32 s98, s58, s50
	s_addc_u32 s99, s59, s51
	global_load_lds_dwordx4 v128, s[98:99]
	s_add_i32 m0, s52, 0x16000
	s_nop 0
	global_load_lds_dwordx4 v130, s[98:99]
	s_waitcnt vmcnt(6)
	s_barrier
	s_setprio 0
	v_mfma_f32_16x16x32_bf16 v[28:31], v[188:191], v[156:159], v[28:31]
	v_mfma_f32_16x16x32_bf16 v[24:27], v[202:205], v[156:159], v[24:27]
	v_mfma_f32_16x16x32_bf16 v[20:23], v[188:191], v[164:167], v[20:23]
	v_mfma_f32_16x16x32_bf16 v[16:19], v[202:205], v[164:167], v[16:19]
	v_mfma_f32_16x16x32_bf16 v[12:15], v[188:191], v[172:175], v[12:15]
	v_mfma_f32_16x16x32_bf16 v[8:11], v[202:205], v[172:175], v[8:11]
	v_mfma_f32_16x16x32_bf16 v[4:7], v[188:191], v[180:183], v[4:7]
	v_mfma_f32_16x16x32_bf16 v[0:3], v[202:205], v[180:183], v[0:3]
	v_mfma_f32_16x16x32_bf16 v[28:31], v[192:195], v[160:163], v[28:31]
	v_mfma_f32_16x16x32_bf16 v[24:27], v[206:209], v[160:163], v[24:27]
	v_mfma_f32_16x16x32_bf16 v[20:23], v[192:195], v[168:171], v[20:23]
	v_mfma_f32_16x16x32_bf16 v[16:19], v[206:209], v[168:171], v[16:19]
	v_mfma_f32_16x16x32_bf16 v[12:15], v[192:195], v[176:179], v[12:15]
	v_mfma_f32_16x16x32_bf16 v[8:11], v[206:209], v[176:179], v[8:11]
	v_mfma_f32_16x16x32_bf16 v[4:7], v[192:195], v[184:187], v[4:7]
	v_mfma_f32_16x16x32_bf16 v[0:3], v[206:209], v[184:187], v[0:3]
	s_setprio 1
	s_barrier
	ds_read_b128 v[140:143], v138
	ds_read_b128 v[144:147], v138 offset:1024
	ds_read_b128 v[148:151], v138 offset:2048
	ds_read_b128 v[152:155], v138 offset:3072
	ds_read_b128 v[156:159], v136 offset:32768
	ds_read_b128 v[160:163], v136 offset:33792
	ds_read_b128 v[164:167], v135 offset:32768
	ds_read_b128 v[168:171], v135 offset:33792
	ds_read_b128 v[172:175], v134 offset:32768
	ds_read_b128 v[176:179], v134 offset:33792
	ds_read_b128 v[180:183], v133 offset:32768
	ds_read_b128 v[184:187], v133 offset:33792
	s_add_i32 m0, s52, 0x4000
	s_add_u32 s98, s28, s54
	s_addc_u32 s99, s29, s55
	global_load_lds_dwordx4 v128, s[98:99]
	s_add_i32 m0, s52, 0x6000
	s_nop 0
	global_load_lds_dwordx4 v130, s[98:99]
	s_waitcnt lgkmcnt(8)
	s_barrier
	s_waitcnt lgkmcnt(0)
	s_setprio 0
	s_waitcnt lgkmcnt(0)
	v_mfma_f32_16x16x32_bf16 v[124:127], v[140:143], v[156:159], v[124:127]
	v_mfma_f32_16x16x32_bf16 v[120:123], v[148:151], v[156:159], v[120:123]
	v_mfma_f32_16x16x32_bf16 v[116:119], v[140:143], v[164:167], v[116:119]
	v_mfma_f32_16x16x32_bf16 v[112:115], v[148:151], v[164:167], v[112:115]
	v_mfma_f32_16x16x32_bf16 v[108:111], v[140:143], v[172:175], v[108:111]
	v_mfma_f32_16x16x32_bf16 v[104:107], v[148:151], v[172:175], v[104:107]
	v_mfma_f32_16x16x32_bf16 v[100:103], v[140:143], v[180:183], v[100:103]
	v_mfma_f32_16x16x32_bf16 v[96:99], v[148:151], v[180:183], v[96:99]
	v_mfma_f32_16x16x32_bf16 v[124:127], v[144:147], v[160:163], v[124:127]
	v_mfma_f32_16x16x32_bf16 v[120:123], v[152:155], v[160:163], v[120:123]
	v_mfma_f32_16x16x32_bf16 v[116:119], v[144:147], v[168:171], v[116:119]
	v_mfma_f32_16x16x32_bf16 v[112:115], v[152:155], v[168:171], v[112:115]
	v_mfma_f32_16x16x32_bf16 v[108:111], v[144:147], v[176:179], v[108:111]
	v_mfma_f32_16x16x32_bf16 v[104:107], v[152:155], v[176:179], v[104:107]
	v_mfma_f32_16x16x32_bf16 v[100:103], v[144:147], v[184:187], v[100:103]
	v_mfma_f32_16x16x32_bf16 v[96:99], v[152:155], v[184:187], v[96:99]
	s_setprio 1
	s_barrier
	ds_read_b128 v[188:191], v137
	ds_read_b128 v[192:195], v137 offset:1024
	ds_read_b128 v[202:205], v137 offset:2048
	ds_read_b128 v[206:209], v137 offset:3072
	s_mov_b32 m0, s7
	s_add_u32 s98, s58, s68
	s_addc_u32 s99, s59, s69
	global_load_lds_dwordx4 v128, s[98:99]
	s_mov_b32 m0, s53
	s_nop 0
	global_load_lds_dwordx4 v130, s[98:99]
	s_barrier
	s_waitcnt lgkmcnt(0)
	s_setprio 0
	s_waitcnt lgkmcnt(0)
	v_mfma_f32_16x16x32_bf16 v[92:95], v[188:191], v[156:159], v[92:95]
	v_mfma_f32_16x16x32_bf16 v[88:91], v[202:205], v[156:159], v[88:91]
	v_mfma_f32_16x16x32_bf16 v[84:87], v[188:191], v[164:167], v[84:87]
	v_mfma_f32_16x16x32_bf16 v[80:83], v[202:205], v[164:167], v[80:83]
	v_mfma_f32_16x16x32_bf16 v[76:79], v[188:191], v[172:175], v[76:79]
	v_mfma_f32_16x16x32_bf16 v[72:75], v[202:205], v[172:175], v[72:75]
	v_mfma_f32_16x16x32_bf16 v[68:71], v[188:191], v[180:183], v[68:71]
	v_mfma_f32_16x16x32_bf16 v[64:67], v[202:205], v[180:183], v[64:67]
	v_mfma_f32_16x16x32_bf16 v[92:95], v[192:195], v[160:163], v[92:95]
	v_mfma_f32_16x16x32_bf16 v[88:91], v[206:209], v[160:163], v[88:91]
	v_mfma_f32_16x16x32_bf16 v[84:87], v[192:195], v[168:171], v[84:87]
	v_mfma_f32_16x16x32_bf16 v[80:83], v[206:209], v[168:171], v[80:83]
	v_mfma_f32_16x16x32_bf16 v[76:79], v[192:195], v[176:179], v[76:79]
	v_mfma_f32_16x16x32_bf16 v[72:75], v[206:209], v[176:179], v[72:75]
	v_mfma_f32_16x16x32_bf16 v[68:71], v[192:195], v[184:187], v[68:71]
	v_mfma_f32_16x16x32_bf16 v[64:67], v[206:209], v[184:187], v[64:67]
	s_setprio 1
	v_mov_b32_e32 v210, v130
	s_barrier
	ds_read_b128 v[156:159], v136 offset:49152
	ds_read_b128 v[160:163], v136 offset:50176
	ds_read_b128 v[164:167], v135 offset:49152
	ds_read_b128 v[168:171], v135 offset:50176
	ds_read_b128 v[172:175], v134 offset:49152
	ds_read_b128 v[176:179], v134 offset:50176
	ds_read_b128 v[180:183], v133 offset:49152
	ds_read_b128 v[184:187], v133 offset:50176
	v_mov_b32_e32 v211, v197
	s_mov_b32 m0, s9
	s_add_u32 s98, s28, s70
	s_addc_u32 s99, s29, s71
	global_load_lds_dwordx4 v128, s[98:99]
	s_mov_b32 m0, s33
	s_nop 0
	global_load_lds_dwordx4 v130, s[98:99]
	s_barrier
	s_waitcnt lgkmcnt(0)
	s_setprio 0
	s_waitcnt lgkmcnt(0)
	v_mfma_f32_16x16x32_bf16 v[60:63], v[140:143], v[156:159], v[60:63]
	v_mfma_f32_16x16x32_bf16 v[56:59], v[148:151], v[156:159], v[56:59]
	v_mfma_f32_16x16x32_bf16 v[52:55], v[140:143], v[164:167], v[52:55]
	v_mfma_f32_16x16x32_bf16 v[48:51], v[148:151], v[164:167], v[48:51]
	v_mfma_f32_16x16x32_bf16 v[44:47], v[140:143], v[172:175], v[44:47]
	v_mfma_f32_16x16x32_bf16 v[40:43], v[148:151], v[172:175], v[40:43]
	v_mfma_f32_16x16x32_bf16 v[36:39], v[140:143], v[180:183], v[36:39]
	v_mfma_f32_16x16x32_bf16 v[32:35], v[148:151], v[180:183], v[32:35]
	v_mfma_f32_16x16x32_bf16 v[60:63], v[144:147], v[160:163], v[60:63]
	v_mfma_f32_16x16x32_bf16 v[56:59], v[152:155], v[160:163], v[56:59]
	v_mfma_f32_16x16x32_bf16 v[52:55], v[144:147], v[168:171], v[52:55]
	v_mfma_f32_16x16x32_bf16 v[48:51], v[152:155], v[168:171], v[48:51]
	v_mfma_f32_16x16x32_bf16 v[44:47], v[144:147], v[176:179], v[44:47]
	v_mfma_f32_16x16x32_bf16 v[40:43], v[152:155], v[176:179], v[40:43]
	v_mfma_f32_16x16x32_bf16 v[36:39], v[144:147], v[184:187], v[36:39]
	v_mfma_f32_16x16x32_bf16 v[32:35], v[152:155], v[184:187], v[32:35]
	s_setprio 1
	s_barrier
	v_mov_b32_e32 v196, v128
	s_mov_b32 m0, s65
	s_add_u32 s98, s58, s72
	s_addc_u32 s99, s59, s73
	global_load_lds_dwordx4 v128, s[98:99]
	s_mov_b32 m0, s66
	s_nop 0
	global_load_lds_dwordx4 v130, s[98:99]
	s_waitcnt vmcnt(6)
	s_barrier
	s_setprio 0
	v_mfma_f32_16x16x32_bf16 v[28:31], v[188:191], v[156:159], v[28:31]
	v_mfma_f32_16x16x32_bf16 v[24:27], v[202:205], v[156:159], v[24:27]
	v_mfma_f32_16x16x32_bf16 v[20:23], v[188:191], v[164:167], v[20:23]
	v_mfma_f32_16x16x32_bf16 v[16:19], v[202:205], v[164:167], v[16:19]
	v_mfma_f32_16x16x32_bf16 v[12:15], v[188:191], v[172:175], v[12:15]
	v_mfma_f32_16x16x32_bf16 v[8:11], v[202:205], v[172:175], v[8:11]
	v_mfma_f32_16x16x32_bf16 v[4:7], v[188:191], v[180:183], v[4:7]
	v_mfma_f32_16x16x32_bf16 v[0:3], v[202:205], v[180:183], v[0:3]
	v_mfma_f32_16x16x32_bf16 v[28:31], v[192:195], v[160:163], v[28:31]
	v_mfma_f32_16x16x32_bf16 v[24:27], v[206:209], v[160:163], v[24:27]
	v_mfma_f32_16x16x32_bf16 v[20:23], v[192:195], v[168:171], v[20:23]
	v_mfma_f32_16x16x32_bf16 v[16:19], v[206:209], v[168:171], v[16:19]
	v_mfma_f32_16x16x32_bf16 v[12:15], v[192:195], v[176:179], v[12:15]
	v_mfma_f32_16x16x32_bf16 v[8:11], v[206:209], v[176:179], v[8:11]
	v_mfma_f32_16x16x32_bf16 v[4:7], v[192:195], v[184:187], v[4:7]
	v_mfma_f32_16x16x32_bf16 v[0:3], v[206:209], v[184:187], v[0:3]
	s_setprio 1
	s_add_i32 s38, s38, 2
	s_add_u32 s56, s56, 0x100
	s_addc_u32 s57, s57, 0
	s_cmp_lt_u32 s38, 28
	s_barrier
	s_cbranch_scc1 .LBB0_192
	s_setprio 0
	s_lshl_b64 s[4:5], s[10:11], 12
	v_readlane_b32 s10, v254, 12
	v_readlane_b32 s11, v254, 13
	s_add_u32 s4, s10, s4
	s_addc_u32 s5, s11, s5
	ds_read_b128 v[140:143], v129
	ds_read_b128 v[144:147], v129 offset:1024
	ds_read_b128 v[148:151], v129 offset:2048
	ds_read_b128 v[152:155], v129 offset:3072
	ds_read_b128 v[156:159], v136
	ds_read_b128 v[160:163], v136 offset:1024
	ds_read_b128 v[164:167], v135
	ds_read_b128 v[168:171], v135 offset:1024
	ds_read_b128 v[172:175], v134
	ds_read_b128 v[176:179], v134 offset:1024
	ds_read_b128 v[180:183], v133
	ds_read_b128 v[184:187], v133 offset:1024
	v_mov_b32_e32 v129, v197
	v_lshl_add_u64 v[128:129], s[4:5], 0, v[128:129]
	s_mov_b64 s[10:11], 0xf80
	s_mov_b32 m0, s40
	v_lshl_add_u64 v[128:129], v[128:129], 0, s[10:11]
	v_mov_b32_e32 v131, v197
	global_load_lds_dwordx4 v[128:129], off
	v_lshl_add_u64 v[128:129], s[4:5], 0, v[130:131]
	v_lshl_add_u64 v[128:129], v[128:129], 0, s[10:11]
	s_mov_b32 m0, s39
	s_nop 0
	global_load_lds_dwordx4 v[128:129], off
	s_barrier
	s_waitcnt lgkmcnt(0)
	s_setprio 1
	s_waitcnt lgkmcnt(0)
	v_mfma_f32_16x16x32_bf16 v[124:127], v[140:143], v[156:159], v[124:127]
	v_mfma_f32_16x16x32_bf16 v[116:119], v[140:143], v[164:167], v[116:119]
	v_mfma_f32_16x16x32_bf16 v[112:115], v[148:151], v[164:167], v[112:115]
	v_mfma_f32_16x16x32_bf16 v[108:111], v[140:143], v[172:175], v[108:111]
	v_mfma_f32_16x16x32_bf16 v[104:107], v[148:151], v[172:175], v[104:107]
	v_mfma_f32_16x16x32_bf16 v[100:103], v[140:143], v[180:183], v[100:103]
	v_mfma_f32_16x16x32_bf16 v[96:99], v[148:151], v[180:183], v[96:99]
	v_mfma_f32_16x16x32_bf16 v[124:127], v[144:147], v[160:163], v[124:127]
	v_mfma_f32_16x16x32_bf16 v[120:123], v[148:151], v[156:159], v[120:123]
	v_mfma_f32_16x16x32_bf16 v[116:119], v[144:147], v[168:171], v[116:119]
	v_mfma_f32_16x16x32_bf16 v[112:115], v[152:155], v[168:171], v[112:115]
	v_mfma_f32_16x16x32_bf16 v[108:111], v[144:147], v[176:179], v[108:111]
	v_mfma_f32_16x16x32_bf16 v[104:107], v[152:155], v[176:179], v[104:107]
	v_mfma_f32_16x16x32_bf16 v[100:103], v[144:147], v[184:187], v[100:103]
	v_mfma_f32_16x16x32_bf16 v[96:99], v[152:155], v[184:187], v[96:99]
	v_mfma_f32_16x16x32_bf16 v[128:131], v[152:155], v[160:163], v[120:123]
	s_setprio 0
	s_barrier
	s_nop 0
	ds_read_b128 v[120:123], v139
	ds_read_b128 v[188:191], v139 offset:1024
	ds_read_b128 v[192:195], v139 offset:2048
	ds_read_b128 v[202:205], v139 offset:3072
	s_barrier
	s_waitcnt lgkmcnt(0)
	s_setprio 1
	s_waitcnt lgkmcnt(0)
	v_mfma_f32_16x16x32_bf16 v[76:79], v[120:123], v[172:175], v[76:79]
	v_mfma_f32_16x16x32_bf16 v[68:71], v[120:123], v[180:183], v[68:71]
	v_mfma_f32_16x16x32_bf16 v[64:67], v[192:195], v[180:183], v[64:67]
	v_mfma_f32_16x16x32_bf16 v[92:95], v[120:123], v[156:159], v[92:95]
	v_mfma_f32_16x16x32_bf16 v[88:91], v[192:195], v[156:159], v[88:91]
	v_mfma_f32_16x16x32_bf16 v[84:87], v[120:123], v[164:167], v[84:87]
	v_mfma_f32_16x16x32_bf16 v[80:83], v[192:195], v[164:167], v[80:83]
	v_mfma_f32_16x16x32_bf16 v[76:79], v[188:191], v[176:179], v[76:79]
	v_mfma_f32_16x16x32_bf16 v[72:75], v[192:195], v[172:175], v[72:75]
	v_mfma_f32_16x16x32_bf16 v[68:71], v[188:191], v[184:187], v[68:71]
	v_mfma_f32_16x16x32_bf16 v[64:67], v[202:205], v[184:187], v[64:67]
	v_mfma_f32_16x16x32_bf16 v[206:209], v[188:191], v[160:163], v[92:95]
	v_mfma_f32_16x16x32_bf16 v[156:159], v[202:205], v[160:163], v[88:91]
	v_mfma_f32_16x16x32_bf16 v[160:163], v[188:191], v[168:171], v[84:87]
	v_mfma_f32_16x16x32_bf16 v[164:167], v[202:205], v[168:171], v[80:83]
	v_mfma_f32_16x16x32_bf16 v[168:171], v[202:205], v[176:179], v[72:75]
	s_setprio 0
	s_barrier
	s_nop 0
	ds_read_b128 v[72:75], v136 offset:16384
	ds_read_b128 v[80:83], v136 offset:17408
	ds_read_b128 v[84:87], v135 offset:16384
	ds_read_b128 v[88:91], v135 offset:17408
	ds_read_b128 v[92:95], v134 offset:16384
	ds_read_b128 v[172:175], v134 offset:17408
	ds_read_b128 v[176:179], v133 offset:16384
	ds_read_b128 v[180:183], v133 offset:17408
	s_waitcnt vmcnt(4)
	s_barrier
	s_waitcnt lgkmcnt(0)
	s_setprio 1
	s_waitcnt lgkmcnt(0)
	v_mfma_f32_16x16x32_bf16 v[60:63], v[140:143], v[72:75], v[60:63]
	v_mfma_f32_16x16x32_bf16 v[52:55], v[140:143], v[84:87], v[52:55]
	v_mfma_f32_16x16x32_bf16 v[48:51], v[148:151], v[84:87], v[48:51]
	v_mfma_f32_16x16x32_bf16 v[44:47], v[140:143], v[92:95], v[44:47]
	v_mfma_f32_16x16x32_bf16 v[40:43], v[148:151], v[92:95], v[40:43]
	v_mfma_f32_16x16x32_bf16 v[36:39], v[140:143], v[176:179], v[36:39]
	v_mfma_f32_16x16x32_bf16 v[32:35], v[148:151], v[176:179], v[32:35]
	v_mfma_f32_16x16x32_bf16 v[60:63], v[144:147], v[80:83], v[60:63]
	v_mfma_f32_16x16x32_bf16 v[56:59], v[148:151], v[72:75], v[56:59]
	v_mfma_f32_16x16x32_bf16 v[52:55], v[144:147], v[88:91], v[52:55]
	v_mfma_f32_16x16x32_bf16 v[48:51], v[152:155], v[88:91], v[48:51]
	v_mfma_f32_16x16x32_bf16 v[44:47], v[144:147], v[172:175], v[44:47]
	v_mfma_f32_16x16x32_bf16 v[40:43], v[152:155], v[172:175], v[40:43]
	v_mfma_f32_16x16x32_bf16 v[36:39], v[144:147], v[180:183], v[36:39]
	v_mfma_f32_16x16x32_bf16 v[32:35], v[152:155], v[180:183], v[32:35]
	v_mfma_f32_16x16x32_bf16 v[184:187], v[152:155], v[80:83], v[56:59]
	s_setprio 0
	s_setprio 1
	v_mfma_f32_16x16x32_bf16 v[12:15], v[120:123], v[92:95], v[12:15]
	v_mfma_f32_16x16x32_bf16 v[4:7], v[120:123], v[176:179], v[4:7]
	v_mfma_f32_16x16x32_bf16 v[0:3], v[192:195], v[176:179], v[0:3]
	v_mfma_f32_16x16x32_bf16 v[28:31], v[120:123], v[72:75], v[28:31]
	v_mfma_f32_16x16x32_bf16 v[24:27], v[192:195], v[72:75], v[24:27]
	v_mfma_f32_16x16x32_bf16 v[20:23], v[120:123], v[84:87], v[20:23]
	v_mfma_f32_16x16x32_bf16 v[16:19], v[192:195], v[84:87], v[16:19]
	v_mfma_f32_16x16x32_bf16 v[12:15], v[188:191], v[172:175], v[12:15]
	v_mfma_f32_16x16x32_bf16 v[8:11], v[192:195], v[92:95], v[8:11]
	v_mfma_f32_16x16x32_bf16 v[4:7], v[188:191], v[180:183], v[4:7]
	v_mfma_f32_16x16x32_bf16 v[0:3], v[202:205], v[180:183], v[0:3]
	v_mfma_f32_16x16x32_bf16 v[140:143], v[188:191], v[80:83], v[28:31]
	v_mfma_f32_16x16x32_bf16 v[144:147], v[202:205], v[80:83], v[24:27]
	v_mfma_f32_16x16x32_bf16 v[148:151], v[188:191], v[88:91], v[20:23]
	v_mfma_f32_16x16x32_bf16 v[152:155], v[202:205], v[88:91], v[16:19]
	v_mfma_f32_16x16x32_bf16 v[172:175], v[202:205], v[172:175], v[8:11]
	s_setprio 0
	s_barrier
	s_nop 0
	ds_read_b128 v[8:11], v138
	ds_read_b128 v[16:19], v138 offset:1024
	ds_read_b128 v[176:179], v138 offset:2048
	ds_read_b128 v[180:183], v138 offset:3072
	ds_read_b128 v[20:23], v136 offset:32768
	ds_read_b128 v[24:27], v136 offset:33792
	ds_read_b128 v[28:31], v135 offset:32768
	ds_read_b128 v[56:59], v135 offset:33792
	ds_read_b128 v[188:191], v134 offset:32768
	ds_read_b128 v[192:195], v134 offset:33792
	ds_read_b128 v[202:205], v133 offset:32768
	ds_read_b128 v[210:213], v133 offset:33792
	s_waitcnt vmcnt(2)
	s_barrier
	s_waitcnt lgkmcnt(0)
	s_setprio 1
	s_waitcnt lgkmcnt(0)
	v_mfma_f32_16x16x32_bf16 v[72:75], v[8:11], v[20:23], v[124:127]
	v_mfma_f32_16x16x32_bf16 v[120:123], v[16:19], v[24:27], v[72:75]
	v_mfma_f32_16x16x32_bf16 v[72:75], v[176:179], v[20:23], v[128:131]
	v_mfma_f32_16x16x32_bf16 v[124:127], v[180:183], v[24:27], v[72:75]
	v_mfma_f32_16x16x32_bf16 v[72:75], v[8:11], v[28:31], v[116:119]
	v_mfma_f32_16x16x32_bf16 v[116:119], v[16:19], v[56:59], v[72:75]
	v_mfma_f32_16x16x32_bf16 v[72:75], v[176:179], v[28:31], v[112:115]
	v_mfma_f32_16x16x32_bf16 v[112:115], v[180:183], v[56:59], v[72:75]
	v_mfma_f32_16x16x32_bf16 v[72:75], v[8:11], v[188:191], v[108:111]
	v_mfma_f32_16x16x32_bf16 v[88:91], v[16:19], v[192:195], v[72:75]
	v_mfma_f32_16x16x32_bf16 v[72:75], v[176:179], v[188:191], v[104:107]
	v_mfma_f32_16x16x32_bf16 v[92:95], v[180:183], v[192:195], v[72:75]
	v_mfma_f32_16x16x32_bf16 v[72:75], v[8:11], v[202:205], v[100:103]
	v_mfma_f32_16x16x32_bf16 v[84:87], v[16:19], v[210:213], v[72:75]
	v_mfma_f32_16x16x32_bf16 v[72:75], v[176:179], v[202:205], v[96:99]
	v_mfma_f32_16x16x32_bf16 v[80:83], v[180:183], v[210:213], v[72:75]
	s_setprio 0
	s_barrier
	ds_read_b128 v[128:131], v137
	ds_read_b128 v[214:217], v137 offset:1024
	ds_read_b128 v[218:221], v137 offset:2048
	ds_read_b128 v[222:225], v137 offset:3072
	s_waitcnt vmcnt(0)
	s_barrier
	s_waitcnt lgkmcnt(0)
	s_setprio 1
	s_waitcnt lgkmcnt(0)
	v_mfma_f32_16x16x32_bf16 v[72:75], v[128:131], v[20:23], v[206:209]
	v_mfma_f32_16x16x32_bf16 v[20:23], v[218:221], v[20:23], v[156:159]
	v_mfma_f32_16x16x32_bf16 v[108:111], v[222:225], v[24:27], v[20:23]
	v_mfma_f32_16x16x32_bf16 v[20:23], v[128:131], v[28:31], v[160:163]
	v_mfma_f32_16x16x32_bf16 v[100:103], v[214:217], v[56:59], v[20:23]
	v_mfma_f32_16x16x32_bf16 v[20:23], v[218:221], v[28:31], v[164:167]
	v_mfma_f32_16x16x32_bf16 v[96:99], v[222:225], v[56:59], v[20:23]
	v_mfma_f32_16x16x32_bf16 v[20:23], v[128:131], v[188:191], v[76:79]
	v_mfma_f32_16x16x32_bf16 v[104:107], v[214:217], v[24:27], v[72:75]
	v_mfma_f32_16x16x32_bf16 v[72:75], v[214:217], v[192:195], v[20:23]
	v_mfma_f32_16x16x32_bf16 v[20:23], v[218:221], v[188:191], v[168:171]
	v_mfma_f32_16x16x32_bf16 v[76:79], v[222:225], v[192:195], v[20:23]
	v_mfma_f32_16x16x32_bf16 v[20:23], v[128:131], v[202:205], v[68:71]
	v_mfma_f32_16x16x32_bf16 v[68:71], v[214:217], v[210:213], v[20:23]
	v_mfma_f32_16x16x32_bf16 v[20:23], v[218:221], v[202:205], v[64:67]
	v_mfma_f32_16x16x32_bf16 v[64:67], v[222:225], v[210:213], v[20:23]
	s_setprio 0
	s_barrier
	ds_read_b128 v[156:159], v136 offset:49152
	ds_read_b128 v[136:139], v136 offset:50176
	ds_read_b128 v[160:163], v135 offset:49152
	ds_read_b128 v[164:167], v135 offset:50176
	ds_read_b128 v[168:171], v134 offset:49152
	ds_read_b128 v[188:191], v134 offset:50176
	ds_read_b128 v[192:195], v133 offset:49152
	ds_read_b128 v[202:205], v133 offset:50176
	s_barrier
	s_waitcnt lgkmcnt(0)
	s_setprio 1
	s_waitcnt lgkmcnt(0)
	v_mfma_f32_16x16x32_bf16 v[20:23], v[8:11], v[156:159], v[60:63]
	v_mfma_f32_16x16x32_bf16 v[56:59], v[16:19], v[136:139], v[20:23]
	v_mfma_f32_16x16x32_bf16 v[20:23], v[176:179], v[156:159], v[184:187]
	v_mfma_f32_16x16x32_bf16 v[60:63], v[180:183], v[136:139], v[20:23]
	v_mfma_f32_16x16x32_bf16 v[20:23], v[8:11], v[160:163], v[52:55]
	v_mfma_f32_16x16x32_bf16 v[52:55], v[16:19], v[164:167], v[20:23]
	v_mfma_f32_16x16x32_bf16 v[20:23], v[176:179], v[160:163], v[48:51]
	v_mfma_f32_16x16x32_bf16 v[48:51], v[180:183], v[164:167], v[20:23]
	v_mfma_f32_16x16x32_bf16 v[20:23], v[8:11], v[168:171], v[44:47]
	v_mfma_f32_16x16x32_bf16 v[24:27], v[16:19], v[188:191], v[20:23]
	v_mfma_f32_16x16x32_bf16 v[20:23], v[176:179], v[168:171], v[40:43]
	v_mfma_f32_16x16x32_bf16 v[8:11], v[8:11], v[192:195], v[36:39]
	v_mfma_f32_16x16x32_bf16 v[28:31], v[180:183], v[188:191], v[20:23]
	v_mfma_f32_16x16x32_bf16 v[20:23], v[16:19], v[202:205], v[8:11]
	v_mfma_f32_16x16x32_bf16 v[8:11], v[176:179], v[192:195], v[32:35]
	v_mfma_f32_16x16x32_bf16 v[16:19], v[180:183], v[202:205], v[8:11]
	s_setprio 0
	s_setprio 1
	v_mfma_f32_16x16x32_bf16 v[8:11], v[128:131], v[156:159], v[140:143]
	v_mfma_f32_16x16x32_bf16 v[40:43], v[214:217], v[136:139], v[8:11]
	v_mfma_f32_16x16x32_bf16 v[8:11], v[218:221], v[156:159], v[144:147]
	v_mfma_f32_16x16x32_bf16 v[44:47], v[222:225], v[136:139], v[8:11]
	v_mfma_f32_16x16x32_bf16 v[8:11], v[128:131], v[160:163], v[148:151]
	v_mfma_f32_16x16x32_bf16 v[36:39], v[214:217], v[164:167], v[8:11]
	v_mfma_f32_16x16x32_bf16 v[8:11], v[218:221], v[160:163], v[152:155]
	v_mfma_f32_16x16x32_bf16 v[32:35], v[222:225], v[164:167], v[8:11]
	v_mfma_f32_16x16x32_bf16 v[8:11], v[128:131], v[168:171], v[12:15]
	v_mfma_f32_16x16x32_bf16 v[12:15], v[218:221], v[168:171], v[172:175]
	v_mfma_f32_16x16x32_bf16 v[4:7], v[128:131], v[192:195], v[4:7]
	v_mfma_f32_16x16x32_bf16 v[0:3], v[218:221], v[192:195], v[0:3]
	v_mfma_f32_16x16x32_bf16 v[8:11], v[214:217], v[188:191], v[8:11]
	v_mfma_f32_16x16x32_bf16 v[12:15], v[222:225], v[188:191], v[12:15]
	v_mfma_f32_16x16x32_bf16 v[4:7], v[214:217], v[202:205], v[4:7]
	v_mfma_f32_16x16x32_bf16 v[0:3], v[222:225], v[202:205], v[0:3]
	s_setprio 0
	s_movk_i32 s4, 0x100
	v_cmp_gt_u32_e32 vcc, s4, v132
	s_barrier
	s_and_saveexec_b64 s[4:5], vcc
	s_cbranch_execz .LBB0_195
	s_barrier

.Lh1_loop:
	ds_read_b128 v[140:143], v129
	ds_read_b128 v[144:147], v129 offset:1024
	ds_read_b128 v[148:151], v129 offset:2048
	ds_read_b128 v[152:155], v129 offset:3072
	s_add_u32 s28, s60, s56
	s_addc_u32 s29, s61, s57
	ds_read_b128 v[156:159], v136
	ds_read_b128 v[160:163], v136 offset:1024
	ds_read_b128 v[164:167], v135
	ds_read_b128 v[168:171], v135 offset:1024
	ds_read_b128 v[172:175], v134
	ds_read_b128 v[176:179], v134 offset:1024
	ds_read_b128 v[180:183], v133
	ds_read_b128 v[184:187], v133 offset:1024
	s_add_i32 s40, s53, 0xc000
	s_mov_b32 m0, s40
	s_add_i32 s39, s53, 0xe000
	s_mov_b32 m0, s39
	s_nop 0
	s_waitcnt lgkmcnt(8)
	s_barrier
	s_waitcnt lgkmcnt(0)
	s_setprio 0
	s_waitcnt lgkmcnt(0)
	v_mfma_f32_16x16x32_bf16 v[124:127], v[140:143], v[156:159], v[124:127]
	v_mfma_f32_16x16x32_bf16 v[120:123], v[148:151], v[156:159], v[120:123]
	v_mfma_f32_16x16x32_bf16 v[116:119], v[140:143], v[164:167], v[116:119]
	v_mfma_f32_16x16x32_bf16 v[112:115], v[148:151], v[164:167], v[112:115]
	v_mfma_f32_16x16x32_bf16 v[108:111], v[140:143], v[172:175], v[108:111]
	v_mfma_f32_16x16x32_bf16 v[104:107], v[148:151], v[172:175], v[104:107]
	v_mfma_f32_16x16x32_bf16 v[100:103], v[140:143], v[180:183], v[100:103]
	v_mfma_f32_16x16x32_bf16 v[96:99], v[148:151], v[180:183], v[96:99]
	v_mfma_f32_16x16x32_bf16 v[124:127], v[144:147], v[160:163], v[124:127]
	v_mfma_f32_16x16x32_bf16 v[120:123], v[152:155], v[160:163], v[120:123]
	v_mfma_f32_16x16x32_bf16 v[116:119], v[144:147], v[168:171], v[116:119]
	v_mfma_f32_16x16x32_bf16 v[112:115], v[152:155], v[168:171], v[112:115]
	v_mfma_f32_16x16x32_bf16 v[108:111], v[144:147], v[176:179], v[108:111]
	v_mfma_f32_16x16x32_bf16 v[104:107], v[152:155], v[176:179], v[104:107]
	v_mfma_f32_16x16x32_bf16 v[100:103], v[144:147], v[184:187], v[100:103]
	v_mfma_f32_16x16x32_bf16 v[96:99], v[152:155], v[184:187], v[96:99]
	s_setprio 1
	s_barrier
	s_add_u32 s62, s60, s36
	s_addc_u32 s63, s61, s37
	ds_read_b128 v[188:191], v139
	ds_read_b128 v[192:195], v139 offset:1024
	ds_read_b128 v[202:205], v139 offset:2048
	ds_read_b128 v[206:209], v139 offset:3072
	s_mov_b32 m0, s68
	s_add_u32 s98, s62, s46
	s_addc_u32 s99, s63, s47
	global_load_lds_dwordx4 v128, s[98:99]
	s_mov_b32 m0, s69
	s_nop 0
	global_load_lds_dwordx4 v130, s[98:99]
	s_barrier
	s_waitcnt lgkmcnt(0)
	s_setprio 0
	s_waitcnt lgkmcnt(0)
	v_mfma_f32_16x16x32_bf16 v[92:95], v[188:191], v[156:159], v[92:95]
	v_mfma_f32_16x16x32_bf16 v[88:91], v[202:205], v[156:159], v[88:91]
	v_mfma_f32_16x16x32_bf16 v[84:87], v[188:191], v[164:167], v[84:87]
	v_mfma_f32_16x16x32_bf16 v[80:83], v[202:205], v[164:167], v[80:83]
	v_mfma_f32_16x16x32_bf16 v[76:79], v[188:191], v[172:175], v[76:79]
	v_mfma_f32_16x16x32_bf16 v[72:75], v[202:205], v[172:175], v[72:75]
	v_mfma_f32_16x16x32_bf16 v[68:71], v[188:191], v[180:183], v[68:71]
	v_mfma_f32_16x16x32_bf16 v[64:67], v[202:205], v[180:183], v[64:67]
	v_mfma_f32_16x16x32_bf16 v[92:95], v[192:195], v[160:163], v[92:95]
	v_mfma_f32_16x16x32_bf16 v[88:91], v[206:209], v[160:163], v[88:91]
	v_mfma_f32_16x16x32_bf16 v[84:87], v[192:195], v[168:171], v[84:87]
	v_mfma_f32_16x16x32_bf16 v[80:83], v[206:209], v[168:171], v[80:83]
	v_mfma_f32_16x16x32_bf16 v[76:79], v[192:195], v[176:179], v[76:79]
	v_mfma_f32_16x16x32_bf16 v[72:75], v[206:209], v[176:179], v[72:75]
	v_mfma_f32_16x16x32_bf16 v[68:71], v[192:195], v[184:187], v[68:71]
	v_mfma_f32_16x16x32_bf16 v[64:67], v[206:209], v[184:187], v[64:67]
	s_setprio 1
	s_barrier
	s_mov_b32 m0, s53
	s_add_u32 s98, s28, s48
	s_addc_u32 s99, s29, s49
	global_load_lds_dwordx4 v128, s[98:99]
	s_mov_b32 m0, s11
	s_nop 0
	global_load_lds_dwordx4 v130, s[98:99]
	s_waitcnt vmcnt(4)
	s_barrier
	s_mov_b32 m0, s9
	s_add_u32 s98, s62, s50
	s_addc_u32 s99, s63, s51
	global_load_lds_dwordx4 v128, s[98:99]
	s_mov_b32 m0, s70
	s_nop 0
	global_load_lds_dwordx4 v130, s[98:99]
	s_barrier
	ds_read_b128 v[140:143], v138
	ds_read_b128 v[144:147], v138 offset:1024
	ds_read_b128 v[148:151], v138 offset:2048
	ds_read_b128 v[152:155], v138 offset:3072
	ds_read_b128 v[156:159], v136 offset:32768
	ds_read_b128 v[160:163], v136 offset:33792
	ds_read_b128 v[164:167], v135 offset:32768
	ds_read_b128 v[168:171], v135 offset:33792
	ds_read_b128 v[172:175], v134 offset:32768
	ds_read_b128 v[176:179], v134 offset:33792
	ds_read_b128 v[180:183], v133 offset:32768
	ds_read_b128 v[184:187], v133 offset:33792
	s_mov_b32 m0, s71
	s_mov_b32 m0, s72
	s_nop 0
	s_waitcnt lgkmcnt(8)
	s_barrier
	s_waitcnt lgkmcnt(0)
	s_setprio 0
	s_waitcnt lgkmcnt(0)
	v_mfma_f32_16x16x32_bf16 v[124:127], v[140:143], v[156:159], v[124:127]
	v_mfma_f32_16x16x32_bf16 v[120:123], v[148:151], v[156:159], v[120:123]
	v_mfma_f32_16x16x32_bf16 v[116:119], v[140:143], v[164:167], v[116:119]
	v_mfma_f32_16x16x32_bf16 v[112:115], v[148:151], v[164:167], v[112:115]
	v_mfma_f32_16x16x32_bf16 v[108:111], v[140:143], v[172:175], v[108:111]
	v_mfma_f32_16x16x32_bf16 v[104:107], v[148:151], v[172:175], v[104:107]
	v_mfma_f32_16x16x32_bf16 v[100:103], v[140:143], v[180:183], v[100:103]
	v_mfma_f32_16x16x32_bf16 v[96:99], v[148:151], v[180:183], v[96:99]
	v_mfma_f32_16x16x32_bf16 v[124:127], v[144:147], v[160:163], v[124:127]
	v_mfma_f32_16x16x32_bf16 v[120:123], v[152:155], v[160:163], v[120:123]
	v_mfma_f32_16x16x32_bf16 v[116:119], v[144:147], v[168:171], v[116:119]
	v_mfma_f32_16x16x32_bf16 v[112:115], v[152:155], v[168:171], v[112:115]
	v_mfma_f32_16x16x32_bf16 v[108:111], v[144:147], v[176:179], v[108:111]
	v_mfma_f32_16x16x32_bf16 v[104:107], v[152:155], v[176:179], v[104:107]
	v_mfma_f32_16x16x32_bf16 v[100:103], v[144:147], v[184:187], v[100:103]
	v_mfma_f32_16x16x32_bf16 v[96:99], v[152:155], v[184:187], v[96:99]
	s_setprio 1
	s_barrier
	ds_read_b128 v[188:191], v137
	ds_read_b128 v[192:195], v137 offset:1024
	ds_read_b128 v[202:205], v137 offset:2048
	ds_read_b128 v[206:209], v137 offset:3072
	s_mov_b32 m0, s66
	s_add_u32 s98, s62, s90
	s_addc_u32 s99, s63, s91
	global_load_lds_dwordx4 v128, s[98:99]
	s_mov_b32 m0, s64
	s_nop 0
	global_load_lds_dwordx4 v130, s[98:99]
	s_barrier
	s_waitcnt lgkmcnt(0)
	s_setprio 0
	s_waitcnt lgkmcnt(0)
	v_mfma_f32_16x16x32_bf16 v[92:95], v[188:191], v[156:159], v[92:95]
	v_mfma_f32_16x16x32_bf16 v[88:91], v[202:205], v[156:159], v[88:91]
	v_mfma_f32_16x16x32_bf16 v[84:87], v[188:191], v[164:167], v[84:87]
	v_mfma_f32_16x16x32_bf16 v[80:83], v[202:205], v[164:167], v[80:83]
	v_mfma_f32_16x16x32_bf16 v[76:79], v[188:191], v[172:175], v[76:79]
	v_mfma_f32_16x16x32_bf16 v[72:75], v[202:205], v[172:175], v[72:75]
	v_mfma_f32_16x16x32_bf16 v[68:71], v[188:191], v[180:183], v[68:71]
	v_mfma_f32_16x16x32_bf16 v[64:67], v[202:205], v[180:183], v[64:67]
	v_mfma_f32_16x16x32_bf16 v[92:95], v[192:195], v[160:163], v[92:95]
	v_mfma_f32_16x16x32_bf16 v[88:91], v[206:209], v[160:163], v[88:91]
	v_mfma_f32_16x16x32_bf16 v[84:87], v[192:195], v[168:171], v[84:87]
	v_mfma_f32_16x16x32_bf16 v[80:83], v[206:209], v[168:171], v[80:83]
	v_mfma_f32_16x16x32_bf16 v[76:79], v[192:195], v[176:179], v[76:79]
	v_mfma_f32_16x16x32_bf16 v[72:75], v[206:209], v[176:179], v[72:75]
	v_mfma_f32_16x16x32_bf16 v[68:71], v[192:195], v[184:187], v[68:71]
	v_mfma_f32_16x16x32_bf16 v[64:67], v[206:209], v[184:187], v[64:67]
	s_setprio 1
	v_mov_b32_e32 v210, v130
	s_barrier
	v_mov_b32_e32 v211, v197
	s_mov_b32 m0, s65
	s_add_u32 s98, s28, s92
	s_addc_u32 s99, s29, s93
	global_load_lds_dwordx4 v128, s[98:99]
	s_mov_b32 m0, s67
	s_nop 0
	global_load_lds_dwordx4 v130, s[98:99]
	s_waitcnt vmcnt(4)
	s_barrier
	v_mov_b32_e32 v196, v128
	s_mov_b32 m0, s33
	s_add_u32 s98, s62, s96
	s_addc_u32 s99, s63, s97
	global_load_lds_dwordx4 v128, s[98:99]
	s_mov_b32 m0, s73
	s_nop 0
	global_load_lds_dwordx4 v130, s[98:99]
	s_barrier
	s_add_i32 s38, s38, 2
	s_add_u32 s60, s60, 0x100
	s_addc_u32 s61, s61, 0
	s_cmp_lt_u32 s38, 28
	s_cbranch_scc1 .Lh1_loop
	s_setprio 0
	ds_read_b128 v[140:143], v129
	ds_read_b128 v[144:147], v129 offset:1024
	ds_read_b128 v[148:151], v129 offset:2048
	ds_read_b128 v[152:155], v129 offset:3072
	ds_read_b128 v[156:159], v136
	ds_read_b128 v[160:163], v136 offset:1024
	ds_read_b128 v[164:167], v135
	ds_read_b128 v[168:171], v135 offset:1024
	ds_read_b128 v[172:175], v134
	ds_read_b128 v[176:179], v134 offset:1024
	ds_read_b128 v[180:183], v133
	ds_read_b128 v[184:187], v133 offset:1024
	v_mov_b32_e32 v129, v197
	v_lshl_add_u64 v[128:129], s[58:59], 0, v[128:129]
	s_mov_b64 s[28:29], 0xf80
	s_mov_b32 m0, s40
	v_lshl_add_u64 v[128:129], v[128:129], 0, s[28:29]
	v_mov_b32_e32 v131, v197
	v_lshl_add_u64 v[128:129], s[58:59], 0, v[130:131]
	v_lshl_add_u64 v[128:129], v[128:129], 0, s[28:29]
	s_mov_b32 m0, s39
	s_nop 0
	s_barrier
	s_waitcnt lgkmcnt(0)
	s_setprio 1
	s_waitcnt lgkmcnt(0)
	v_mfma_f32_16x16x32_bf16 v[124:127], v[140:143], v[156:159], v[124:127]
	v_mfma_f32_16x16x32_bf16 v[120:123], v[148:151], v[156:159], v[120:123]
	v_mfma_f32_16x16x32_bf16 v[116:119], v[140:143], v[164:167], v[116:119]
	v_mfma_f32_16x16x32_bf16 v[112:115], v[148:151], v[164:167], v[112:115]
	v_mfma_f32_16x16x32_bf16 v[108:111], v[140:143], v[172:175], v[108:111]
	v_mfma_f32_16x16x32_bf16 v[100:103], v[140:143], v[180:183], v[100:103]
	v_mfma_f32_16x16x32_bf16 v[96:99], v[148:151], v[180:183], v[96:99]
	v_mfma_f32_16x16x32_bf16 v[124:127], v[144:147], v[160:163], v[124:127]
	v_mfma_f32_16x16x32_bf16 v[120:123], v[152:155], v[160:163], v[120:123]
	v_mfma_f32_16x16x32_bf16 v[116:119], v[144:147], v[168:171], v[116:119]
	v_mfma_f32_16x16x32_bf16 v[112:115], v[152:155], v[168:171], v[112:115]
	v_mfma_f32_16x16x32_bf16 v[108:111], v[144:147], v[176:179], v[108:111]
	v_mfma_f32_16x16x32_bf16 v[104:107], v[148:151], v[172:175], v[104:107]
	v_mfma_f32_16x16x32_bf16 v[100:103], v[144:147], v[184:187], v[100:103]
	v_mfma_f32_16x16x32_bf16 v[96:99], v[152:155], v[184:187], v[96:99]
	v_mfma_f32_16x16x32_bf16 v[128:131], v[152:155], v[176:179], v[104:107]
	s_setprio 0
	s_barrier
	s_nop 2
	ds_read_b128 v[104:107], v139
	ds_read_b128 v[188:191], v139 offset:1024
	ds_read_b128 v[192:195], v139 offset:2048
	ds_read_b128 v[202:205], v139 offset:3072
	s_barrier
	s_waitcnt lgkmcnt(0)
	s_setprio 1
	s_waitcnt lgkmcnt(0)
	v_mfma_f32_16x16x32_bf16 v[92:95], v[104:107], v[156:159], v[92:95]
	v_mfma_f32_16x16x32_bf16 v[84:87], v[104:107], v[164:167], v[84:87]
	v_mfma_f32_16x16x32_bf16 v[76:79], v[104:107], v[172:175], v[76:79]
	v_mfma_f32_16x16x32_bf16 v[68:71], v[104:107], v[180:183], v[68:71]
	v_mfma_f32_16x16x32_bf16 v[64:67], v[192:195], v[180:183], v[64:67]
	v_mfma_f32_16x16x32_bf16 v[92:95], v[188:191], v[160:163], v[92:95]
	v_mfma_f32_16x16x32_bf16 v[88:91], v[192:195], v[156:159], v[88:91]
	v_mfma_f32_16x16x32_bf16 v[84:87], v[188:191], v[168:171], v[84:87]
	v_mfma_f32_16x16x32_bf16 v[80:83], v[192:195], v[164:167], v[80:83]
	v_mfma_f32_16x16x32_bf16 v[76:79], v[188:191], v[176:179], v[76:79]
	v_mfma_f32_16x16x32_bf16 v[72:75], v[192:195], v[172:175], v[72:75]
	v_mfma_f32_16x16x32_bf16 v[68:71], v[188:191], v[184:187], v[68:71]
	v_mfma_f32_16x16x32_bf16 v[64:67], v[202:205], v[184:187], v[64:67]
	v_mfma_f32_16x16x32_bf16 v[156:159], v[202:205], v[160:163], v[88:91]
	v_mfma_f32_16x16x32_bf16 v[160:163], v[202:205], v[168:171], v[80:83]
	v_mfma_f32_16x16x32_bf16 v[164:167], v[202:205], v[176:179], v[72:75]
	s_setprio 0
	s_barrier
	s_nop 0
	s_waitcnt vmcnt(2)
	s_barrier
	s_waitcnt lgkmcnt(0)
	s_setprio 1
	s_waitcnt lgkmcnt(0)
	s_setprio 0
	s_setprio 1
	s_setprio 0
	s_barrier
	ds_read_b128 v[16:19], v138
	ds_read_b128 v[180:183], v138 offset:1024
	ds_read_b128 v[184:187], v138 offset:2048
	ds_read_b128 v[188:191], v138 offset:3072
	ds_read_b128 v[0:3], v136 offset:32768
	ds_read_b128 v[4:7], v136 offset:33792
	ds_read_b128 v[8:11], v135 offset:32768
	ds_read_b128 v[12:15], v135 offset:33792
	ds_read_b128 v[44:47], v134 offset:32768
	ds_read_b128 v[192:195], v134 offset:33792
	ds_read_b128 v[202:205], v133 offset:32768
	ds_read_b128 v[218:221], v133 offset:33792
	s_waitcnt vmcnt(0)
	s_barrier
	s_waitcnt lgkmcnt(0)
	s_setprio 1
	s_waitcnt lgkmcnt(0)
	v_mfma_f32_16x16x32_bf16 v[28:31], v[16:19], v[0:3], v[124:127]
	v_mfma_f32_16x16x32_bf16 v[52:55], v[180:183], v[4:7], v[28:31]
	v_mfma_f32_16x16x32_bf16 v[28:31], v[184:187], v[0:3], v[120:123]
	v_mfma_f32_16x16x32_bf16 v[104:107], v[188:191], v[4:7], v[28:31]
	v_mfma_f32_16x16x32_bf16 v[28:31], v[16:19], v[8:11], v[116:119]
	v_mfma_f32_16x16x32_bf16 v[72:75], v[180:183], v[12:15], v[28:31]
	v_mfma_f32_16x16x32_bf16 v[28:31], v[184:187], v[8:11], v[112:115]
	v_mfma_f32_16x16x32_bf16 v[116:119], v[188:191], v[12:15], v[28:31]
	v_mfma_f32_16x16x32_bf16 v[28:31], v[16:19], v[44:47], v[108:111]
	v_mfma_f32_16x16x32_bf16 v[80:83], v[180:183], v[192:195], v[28:31]
	v_mfma_f32_16x16x32_bf16 v[28:31], v[184:187], v[44:47], v[128:131]
	v_mfma_f32_16x16x32_bf16 v[108:111], v[188:191], v[192:195], v[28:31]
	v_mfma_f32_16x16x32_bf16 v[28:31], v[16:19], v[202:205], v[100:103]
	v_mfma_f32_16x16x32_bf16 v[88:91], v[180:183], v[218:221], v[28:31]
	v_mfma_f32_16x16x32_bf16 v[28:31], v[184:187], v[202:205], v[96:99]
	v_mfma_f32_16x16x32_bf16 v[96:99], v[188:191], v[218:221], v[28:31]
	s_setprio 0
	s_barrier
	ds_read_b128 v[128:131], v137
	ds_read_b128 v[222:225], v137 offset:1024
	ds_read_b128 v[228:231], v137 offset:2048
	ds_read_b128 v[232:235], v137 offset:3072
	s_waitcnt vmcnt(0)
	s_barrier
	s_waitcnt lgkmcnt(0)
	s_setprio 1
	s_waitcnt lgkmcnt(0)
	v_mfma_f32_16x16x32_bf16 v[28:31], v[128:131], v[0:3], v[92:95]
	v_mfma_f32_16x16x32_bf16 v[0:3], v[228:231], v[0:3], v[156:159]
	v_mfma_f32_16x16x32_bf16 v[28:31], v[222:225], v[4:7], v[28:31]
	v_mfma_f32_16x16x32_bf16 v[0:3], v[232:235], v[4:7], v[0:3]
	v_mfma_f32_16x16x32_bf16 v[4:7], v[128:131], v[8:11], v[84:87]
	v_mfma_f32_16x16x32_bf16 v[36:39], v[222:225], v[12:15], v[4:7]
	v_mfma_f32_16x16x32_bf16 v[4:7], v[228:231], v[8:11], v[160:163]
	v_mfma_f32_16x16x32_bf16 v[4:7], v[232:235], v[12:15], v[4:7]
	v_mfma_f32_16x16x32_bf16 v[8:11], v[128:131], v[44:47], v[76:79]
	v_mfma_f32_16x16x32_bf16 v[12:15], v[128:131], v[202:205], v[68:71]
	v_mfma_f32_16x16x32_bf16 v[40:43], v[222:225], v[192:195], v[8:11]
	v_mfma_f32_16x16x32_bf16 v[8:11], v[228:231], v[44:47], v[164:167]
	v_mfma_f32_16x16x32_bf16 v[44:47], v[222:225], v[218:221], v[12:15]
	v_mfma_f32_16x16x32_bf16 v[12:15], v[228:231], v[202:205], v[64:67]
	v_mfma_f32_16x16x32_bf16 v[8:11], v[232:235], v[192:195], v[8:11]
	v_mfma_f32_16x16x32_bf16 v[12:15], v[232:235], v[218:221], v[12:15]
	s_setprio 0
	s_barrier
	s_barrier
	s_waitcnt lgkmcnt(0)
	s_setprio 1
	s_waitcnt lgkmcnt(0)
	s_setprio 0
	s_setprio 1
	s_setprio 0
	s_movk_i32 s9, 0x100
	v_cmp_gt_u32_e32 vcc, s9, v132
	s_barrier
	s_and_saveexec_b64 s[28:29], vcc
	s_cbranch_execz .Lh1_epi
	s_barrier

.LBB0_255:
	ds_read_b128 v[140:143], v129
	ds_read_b128 v[144:147], v129 offset:1024
	ds_read_b128 v[148:151], v129 offset:2048
	ds_read_b128 v[152:155], v129 offset:3072
	s_add_u32 s28, s60, s56
	s_addc_u32 s29, s61, s57
	ds_read_b128 v[156:159], v136
	ds_read_b128 v[160:163], v136 offset:1024
	ds_read_b128 v[164:167], v135
	ds_read_b128 v[168:171], v135 offset:1024
	ds_read_b128 v[172:175], v134
	ds_read_b128 v[176:179], v134 offset:1024
	ds_read_b128 v[180:183], v133
	ds_read_b128 v[184:187], v133 offset:1024
	s_add_i32 s40, s53, 0xc000
	s_mov_b32 m0, s40
	s_add_i32 s39, s53, 0xe000
	s_add_u32 s98, s28, s44
	s_addc_u32 s99, s29, s45
	global_load_lds_dwordx4 v128, s[98:99]
	s_mov_b32 m0, s39
	s_nop 0
	global_load_lds_dwordx4 v130, s[98:99]
	s_waitcnt lgkmcnt(8)
	s_barrier
	s_waitcnt lgkmcnt(0)
	s_setprio 0
	s_waitcnt lgkmcnt(0)
	v_mfma_f32_16x16x32_bf16 v[124:127], v[140:143], v[156:159], v[124:127]
	v_mfma_f32_16x16x32_bf16 v[120:123], v[148:151], v[156:159], v[120:123]
	v_mfma_f32_16x16x32_bf16 v[116:119], v[140:143], v[164:167], v[116:119]
	v_mfma_f32_16x16x32_bf16 v[112:115], v[148:151], v[164:167], v[112:115]
	v_mfma_f32_16x16x32_bf16 v[108:111], v[140:143], v[172:175], v[108:111]
	v_mfma_f32_16x16x32_bf16 v[104:107], v[148:151], v[172:175], v[104:107]
	v_mfma_f32_16x16x32_bf16 v[100:103], v[140:143], v[180:183], v[100:103]
	v_mfma_f32_16x16x32_bf16 v[96:99], v[148:151], v[180:183], v[96:99]
	v_mfma_f32_16x16x32_bf16 v[124:127], v[144:147], v[160:163], v[124:127]
	v_mfma_f32_16x16x32_bf16 v[120:123], v[152:155], v[160:163], v[120:123]
	v_mfma_f32_16x16x32_bf16 v[116:119], v[144:147], v[168:171], v[116:119]
	v_mfma_f32_16x16x32_bf16 v[112:115], v[152:155], v[168:171], v[112:115]
	v_mfma_f32_16x16x32_bf16 v[108:111], v[144:147], v[176:179], v[108:111]
	v_mfma_f32_16x16x32_bf16 v[104:107], v[152:155], v[176:179], v[104:107]
	v_mfma_f32_16x16x32_bf16 v[100:103], v[144:147], v[184:187], v[100:103]
	v_mfma_f32_16x16x32_bf16 v[96:99], v[152:155], v[184:187], v[96:99]
	s_setprio 1
	s_barrier
	s_add_u32 s62, s60, s36
	s_addc_u32 s63, s61, s37
	ds_read_b128 v[188:191], v139
	ds_read_b128 v[192:195], v139 offset:1024
	ds_read_b128 v[202:205], v139 offset:2048
	ds_read_b128 v[206:209], v139 offset:3072
	s_mov_b32 m0, s68
	s_add_u32 s98, s62, s46
	s_addc_u32 s99, s63, s47
	global_load_lds_dwordx4 v128, s[98:99]
	s_mov_b32 m0, s69
	s_nop 0
	global_load_lds_dwordx4 v130, s[98:99]
	s_barrier
	s_waitcnt lgkmcnt(0)
	s_setprio 0
	s_waitcnt lgkmcnt(0)
	v_mfma_f32_16x16x32_bf16 v[92:95], v[188:191], v[156:159], v[92:95]
	v_mfma_f32_16x16x32_bf16 v[88:91], v[202:205], v[156:159], v[88:91]
	v_mfma_f32_16x16x32_bf16 v[84:87], v[188:191], v[164:167], v[84:87]
	v_mfma_f32_16x16x32_bf16 v[80:83], v[202:205], v[164:167], v[80:83]
	v_mfma_f32_16x16x32_bf16 v[76:79], v[188:191], v[172:175], v[76:79]
	v_mfma_f32_16x16x32_bf16 v[72:75], v[202:205], v[172:175], v[72:75]
	v_mfma_f32_16x16x32_bf16 v[68:71], v[188:191], v[180:183], v[68:71]
	v_mfma_f32_16x16x32_bf16 v[64:67], v[202:205], v[180:183], v[64:67]
	v_mfma_f32_16x16x32_bf16 v[92:95], v[192:195], v[160:163], v[92:95]
	v_mfma_f32_16x16x32_bf16 v[88:91], v[206:209], v[160:163], v[88:91]
	v_mfma_f32_16x16x32_bf16 v[84:87], v[192:195], v[168:171], v[84:87]
	v_mfma_f32_16x16x32_bf16 v[80:83], v[206:209], v[168:171], v[80:83]
	v_mfma_f32_16x16x32_bf16 v[76:79], v[192:195], v[176:179], v[76:79]
	v_mfma_f32_16x16x32_bf16 v[72:75], v[206:209], v[176:179], v[72:75]
	v_mfma_f32_16x16x32_bf16 v[68:71], v[192:195], v[184:187], v[68:71]
	v_mfma_f32_16x16x32_bf16 v[64:67], v[206:209], v[184:187], v[64:67]
	s_setprio 1
	s_barrier
	ds_read_b128 v[156:159], v136 offset:16384
	ds_read_b128 v[160:163], v136 offset:17408
	ds_read_b128 v[164:167], v135 offset:16384
	ds_read_b128 v[168:171], v135 offset:17408
	ds_read_b128 v[172:175], v134 offset:16384
	ds_read_b128 v[176:179], v134 offset:17408
	ds_read_b128 v[180:183], v133 offset:16384
	ds_read_b128 v[184:187], v133 offset:17408
	s_mov_b32 m0, s53
	s_add_u32 s98, s28, s48
	s_addc_u32 s99, s29, s49
	global_load_lds_dwordx4 v128, s[98:99]
	s_mov_b32 m0, s11
	s_nop 0
	global_load_lds_dwordx4 v130, s[98:99]
	s_barrier
	s_waitcnt lgkmcnt(0)
	s_setprio 0
	s_waitcnt lgkmcnt(0)
	v_mfma_f32_16x16x32_bf16 v[60:63], v[140:143], v[156:159], v[60:63]
	v_mfma_f32_16x16x32_bf16 v[56:59], v[148:151], v[156:159], v[56:59]
	v_mfma_f32_16x16x32_bf16 v[52:55], v[140:143], v[164:167], v[52:55]
	v_mfma_f32_16x16x32_bf16 v[48:51], v[148:151], v[164:167], v[48:51]
	v_mfma_f32_16x16x32_bf16 v[44:47], v[140:143], v[172:175], v[44:47]
	v_mfma_f32_16x16x32_bf16 v[40:43], v[148:151], v[172:175], v[40:43]
	v_mfma_f32_16x16x32_bf16 v[36:39], v[140:143], v[180:183], v[36:39]
	v_mfma_f32_16x16x32_bf16 v[32:35], v[148:151], v[180:183], v[32:35]
	v_mfma_f32_16x16x32_bf16 v[60:63], v[144:147], v[160:163], v[60:63]
	v_mfma_f32_16x16x32_bf16 v[56:59], v[152:155], v[160:163], v[56:59]
	v_mfma_f32_16x16x32_bf16 v[52:55], v[144:147], v[168:171], v[52:55]
	v_mfma_f32_16x16x32_bf16 v[48:51], v[152:155], v[168:171], v[48:51]
	v_mfma_f32_16x16x32_bf16 v[44:47], v[144:147], v[176:179], v[44:47]
	v_mfma_f32_16x16x32_bf16 v[40:43], v[152:155], v[176:179], v[40:43]
	v_mfma_f32_16x16x32_bf16 v[36:39], v[144:147], v[184:187], v[36:39]
	v_mfma_f32_16x16x32_bf16 v[32:35], v[152:155], v[184:187], v[32:35]
	s_setprio 1
	s_barrier
	s_mov_b32 m0, s9
	s_add_u32 s98, s62, s50
	s_addc_u32 s99, s63, s51
	global_load_lds_dwordx4 v128, s[98:99]
	s_mov_b32 m0, s70
	s_nop 0
	global_load_lds_dwordx4 v130, s[98:99]
	s_waitcnt vmcnt(6)
	s_barrier
	s_setprio 0
	v_mfma_f32_16x16x32_bf16 v[28:31], v[188:191], v[156:159], v[28:31]
	v_mfma_f32_16x16x32_bf16 v[24:27], v[202:205], v[156:159], v[24:27]
	v_mfma_f32_16x16x32_bf16 v[20:23], v[188:191], v[164:167], v[20:23]
	v_mfma_f32_16x16x32_bf16 v[16:19], v[202:205], v[164:167], v[16:19]
	v_mfma_f32_16x16x32_bf16 v[12:15], v[188:191], v[172:175], v[12:15]
	v_mfma_f32_16x16x32_bf16 v[8:11], v[202:205], v[172:175], v[8:11]
	v_mfma_f32_16x16x32_bf16 v[4:7], v[188:191], v[180:183], v[4:7]
	v_mfma_f32_16x16x32_bf16 v[0:3], v[202:205], v[180:183], v[0:3]
	v_mfma_f32_16x16x32_bf16 v[28:31], v[192:195], v[160:163], v[28:31]
	v_mfma_f32_16x16x32_bf16 v[24:27], v[206:209], v[160:163], v[24:27]
	v_mfma_f32_16x16x32_bf16 v[20:23], v[192:195], v[168:171], v[20:23]
	v_mfma_f32_16x16x32_bf16 v[16:19], v[206:209], v[168:171], v[16:19]
	v_mfma_f32_16x16x32_bf16 v[12:15], v[192:195], v[176:179], v[12:15]
	v_mfma_f32_16x16x32_bf16 v[8:11], v[206:209], v[176:179], v[8:11]
	v_mfma_f32_16x16x32_bf16 v[4:7], v[192:195], v[184:187], v[4:7]
	v_mfma_f32_16x16x32_bf16 v[0:3], v[206:209], v[184:187], v[0:3]
	s_setprio 1
	s_barrier
	ds_read_b128 v[140:143], v138
	ds_read_b128 v[144:147], v138 offset:1024
	ds_read_b128 v[148:151], v138 offset:2048
	ds_read_b128 v[152:155], v138 offset:3072
	ds_read_b128 v[156:159], v136 offset:32768
	ds_read_b128 v[160:163], v136 offset:33792
	ds_read_b128 v[164:167], v135 offset:32768
	ds_read_b128 v[168:171], v135 offset:33792
	ds_read_b128 v[172:175], v134 offset:32768
	ds_read_b128 v[176:179], v134 offset:33792
	ds_read_b128 v[180:183], v133 offset:32768
	ds_read_b128 v[184:187], v133 offset:33792
	s_mov_b32 m0, s71
	s_add_u32 s98, s28, s74
	s_addc_u32 s99, s29, s75
	global_load_lds_dwordx4 v128, s[98:99]
	s_mov_b32 m0, s72
	s_nop 0
	global_load_lds_dwordx4 v130, s[98:99]
	s_waitcnt lgkmcnt(8)
	s_barrier
	s_waitcnt lgkmcnt(0)
	s_setprio 0
	s_waitcnt lgkmcnt(0)
	v_mfma_f32_16x16x32_bf16 v[124:127], v[140:143], v[156:159], v[124:127]
	v_mfma_f32_16x16x32_bf16 v[120:123], v[148:151], v[156:159], v[120:123]
	v_mfma_f32_16x16x32_bf16 v[116:119], v[140:143], v[164:167], v[116:119]
	v_mfma_f32_16x16x32_bf16 v[112:115], v[148:151], v[164:167], v[112:115]
	v_mfma_f32_16x16x32_bf16 v[108:111], v[140:143], v[172:175], v[108:111]
	v_mfma_f32_16x16x32_bf16 v[104:107], v[148:151], v[172:175], v[104:107]
	v_mfma_f32_16x16x32_bf16 v[100:103], v[140:143], v[180:183], v[100:103]
	v_mfma_f32_16x16x32_bf16 v[96:99], v[148:151], v[180:183], v[96:99]
	v_mfma_f32_16x16x32_bf16 v[124:127], v[144:147], v[160:163], v[124:127]
	v_mfma_f32_16x16x32_bf16 v[120:123], v[152:155], v[160:163], v[120:123]
	v_mfma_f32_16x16x32_bf16 v[116:119], v[144:147], v[168:171], v[116:119]
	v_mfma_f32_16x16x32_bf16 v[112:115], v[152:155], v[168:171], v[112:115]
	v_mfma_f32_16x16x32_bf16 v[108:111], v[144:147], v[176:179], v[108:111]
	v_mfma_f32_16x16x32_bf16 v[104:107], v[152:155], v[176:179], v[104:107]
	v_mfma_f32_16x16x32_bf16 v[100:103], v[144:147], v[184:187], v[100:103]
	v_mfma_f32_16x16x32_bf16 v[96:99], v[152:155], v[184:187], v[96:99]
	s_setprio 1
	s_barrier
	ds_read_b128 v[188:191], v137
	ds_read_b128 v[192:195], v137 offset:1024
	ds_read_b128 v[202:205], v137 offset:2048
	ds_read_b128 v[206:209], v137 offset:3072
	s_mov_b32 m0, s66
	s_add_u32 s98, s62, s90
	s_addc_u32 s99, s63, s91
	global_load_lds_dwordx4 v128, s[98:99]
	s_mov_b32 m0, s64
	s_nop 0
	global_load_lds_dwordx4 v130, s[98:99]
	s_barrier
	s_waitcnt lgkmcnt(0)
	s_setprio 0
	s_waitcnt lgkmcnt(0)
	v_mfma_f32_16x16x32_bf16 v[92:95], v[188:191], v[156:159], v[92:95]
	v_mfma_f32_16x16x32_bf16 v[88:91], v[202:205], v[156:159], v[88:91]
	v_mfma_f32_16x16x32_bf16 v[84:87], v[188:191], v[164:167], v[84:87]
	v_mfma_f32_16x16x32_bf16 v[80:83], v[202:205], v[164:167], v[80:83]
	v_mfma_f32_16x16x32_bf16 v[76:79], v[188:191], v[172:175], v[76:79]
	v_mfma_f32_16x16x32_bf16 v[72:75], v[202:205], v[172:175], v[72:75]
	v_mfma_f32_16x16x32_bf16 v[68:71], v[188:191], v[180:183], v[68:71]
	v_mfma_f32_16x16x32_bf16 v[64:67], v[202:205], v[180:183], v[64:67]
	v_mfma_f32_16x16x32_bf16 v[92:95], v[192:195], v[160:163], v[92:95]
	v_mfma_f32_16x16x32_bf16 v[88:91], v[206:209], v[160:163], v[88:91]
	v_mfma_f32_16x16x32_bf16 v[84:87], v[192:195], v[168:171], v[84:87]
	v_mfma_f32_16x16x32_bf16 v[80:83], v[206:209], v[168:171], v[80:83]
	v_mfma_f32_16x16x32_bf16 v[76:79], v[192:195], v[176:179], v[76:79]
	v_mfma_f32_16x16x32_bf16 v[72:75], v[206:209], v[176:179], v[72:75]
	v_mfma_f32_16x16x32_bf16 v[68:71], v[192:195], v[184:187], v[68:71]
	v_mfma_f32_16x16x32_bf16 v[64:67], v[206:209], v[184:187], v[64:67]
	s_setprio 1
	v_mov_b32_e32 v210, v130
	s_barrier
	ds_read_b128 v[156:159], v136 offset:49152
	ds_read_b128 v[160:163], v136 offset:50176
	ds_read_b128 v[164:167], v135 offset:49152
	ds_read_b128 v[168:171], v135 offset:50176
	ds_read_b128 v[172:175], v134 offset:49152
	ds_read_b128 v[176:179], v134 offset:50176
	ds_read_b128 v[180:183], v133 offset:49152
	ds_read_b128 v[184:187], v133 offset:50176
	v_mov_b32_e32 v211, v197
	s_mov_b32 m0, s65
	s_add_u32 s98, s28, s92
	s_addc_u32 s99, s29, s93
	global_load_lds_dwordx4 v128, s[98:99]
	s_mov_b32 m0, s67
	s_nop 0
	global_load_lds_dwordx4 v130, s[98:99]
	s_barrier
	s_waitcnt lgkmcnt(0)
	s_setprio 0
	s_waitcnt lgkmcnt(0)
	v_mfma_f32_16x16x32_bf16 v[60:63], v[140:143], v[156:159], v[60:63]
	v_mfma_f32_16x16x32_bf16 v[56:59], v[148:151], v[156:159], v[56:59]
	v_mfma_f32_16x16x32_bf16 v[52:55], v[140:143], v[164:167], v[52:55]
	v_mfma_f32_16x16x32_bf16 v[48:51], v[148:151], v[164:167], v[48:51]
	v_mfma_f32_16x16x32_bf16 v[44:47], v[140:143], v[172:175], v[44:47]
	v_mfma_f32_16x16x32_bf16 v[40:43], v[148:151], v[172:175], v[40:43]
	v_mfma_f32_16x16x32_bf16 v[36:39], v[140:143], v[180:183], v[36:39]
	v_mfma_f32_16x16x32_bf16 v[32:35], v[148:151], v[180:183], v[32:35]
	v_mfma_f32_16x16x32_bf16 v[60:63], v[144:147], v[160:163], v[60:63]
	v_mfma_f32_16x16x32_bf16 v[56:59], v[152:155], v[160:163], v[56:59]
	v_mfma_f32_16x16x32_bf16 v[52:55], v[144:147], v[168:171], v[52:55]
	v_mfma_f32_16x16x32_bf16 v[48:51], v[152:155], v[168:171], v[48:51]
	v_mfma_f32_16x16x32_bf16 v[44:47], v[144:147], v[176:179], v[44:47]
	v_mfma_f32_16x16x32_bf16 v[40:43], v[152:155], v[176:179], v[40:43]
	v_mfma_f32_16x16x32_bf16 v[36:39], v[144:147], v[184:187], v[36:39]
	v_mfma_f32_16x16x32_bf16 v[32:35], v[152:155], v[184:187], v[32:35]
	s_setprio 1
	s_barrier
	v_mov_b32_e32 v196, v128
	s_mov_b32 m0, s33
	s_add_u32 s98, s62, s96
	s_addc_u32 s99, s63, s97
	global_load_lds_dwordx4 v128, s[98:99]
	s_mov_b32 m0, s73
	s_nop 0
	global_load_lds_dwordx4 v130, s[98:99]
	s_waitcnt vmcnt(6)
	s_barrier
	s_setprio 0
	v_mfma_f32_16x16x32_bf16 v[28:31], v[188:191], v[156:159], v[28:31]
	v_mfma_f32_16x16x32_bf16 v[24:27], v[202:205], v[156:159], v[24:27]
	v_mfma_f32_16x16x32_bf16 v[20:23], v[188:191], v[164:167], v[20:23]
	v_mfma_f32_16x16x32_bf16 v[16:19], v[202:205], v[164:167], v[16:19]
	v_mfma_f32_16x16x32_bf16 v[12:15], v[188:191], v[172:175], v[12:15]
	v_mfma_f32_16x16x32_bf16 v[8:11], v[202:205], v[172:175], v[8:11]
	v_mfma_f32_16x16x32_bf16 v[4:7], v[188:191], v[180:183], v[4:7]
	v_mfma_f32_16x16x32_bf16 v[0:3], v[202:205], v[180:183], v[0:3]
	v_mfma_f32_16x16x32_bf16 v[28:31], v[192:195], v[160:163], v[28:31]
	v_mfma_f32_16x16x32_bf16 v[24:27], v[206:209], v[160:163], v[24:27]
	v_mfma_f32_16x16x32_bf16 v[20:23], v[192:195], v[168:171], v[20:23]
	v_mfma_f32_16x16x32_bf16 v[16:19], v[206:209], v[168:171], v[16:19]
	v_mfma_f32_16x16x32_bf16 v[12:15], v[192:195], v[176:179], v[12:15]
	v_mfma_f32_16x16x32_bf16 v[8:11], v[206:209], v[176:179], v[8:11]
	v_mfma_f32_16x16x32_bf16 v[4:7], v[192:195], v[184:187], v[4:7]
	v_mfma_f32_16x16x32_bf16 v[0:3], v[206:209], v[184:187], v[0:3]
	s_setprio 1
	s_add_i32 s38, s38, 2
	s_add_u32 s60, s60, 0x100
	s_addc_u32 s61, s61, 0
	s_cmp_lt_u32 s38, 28
	s_barrier
	s_cbranch_scc1 .LBB0_255
	s_setprio 0
	ds_read_b128 v[140:143], v129
	ds_read_b128 v[144:147], v129 offset:1024
	ds_read_b128 v[148:151], v129 offset:2048
	ds_read_b128 v[152:155], v129 offset:3072
	ds_read_b128 v[156:159], v136
	ds_read_b128 v[160:163], v136 offset:1024
	ds_read_b128 v[164:167], v135
	ds_read_b128 v[168:171], v135 offset:1024
	ds_read_b128 v[172:175], v134
	ds_read_b128 v[176:179], v134 offset:1024
	ds_read_b128 v[180:183], v133
	ds_read_b128 v[184:187], v133 offset:1024
	v_mov_b32_e32 v129, v197
	v_lshl_add_u64 v[128:129], s[58:59], 0, v[128:129]
	s_mov_b64 s[28:29], 0xf80
	s_mov_b32 m0, s40
	v_lshl_add_u64 v[128:129], v[128:129], 0, s[28:29]
	v_mov_b32_e32 v131, v197
	global_load_lds_dwordx4 v[128:129], off
	v_lshl_add_u64 v[128:129], s[58:59], 0, v[130:131]
	v_lshl_add_u64 v[128:129], v[128:129], 0, s[28:29]
	s_mov_b32 m0, s39
	s_nop 0
	global_load_lds_dwordx4 v[128:129], off
	s_barrier
	s_waitcnt lgkmcnt(0)
	s_setprio 1
	s_waitcnt lgkmcnt(0)
	v_mfma_f32_16x16x32_bf16 v[124:127], v[140:143], v[156:159], v[124:127]
	v_mfma_f32_16x16x32_bf16 v[120:123], v[148:151], v[156:159], v[120:123]
	v_mfma_f32_16x16x32_bf16 v[116:119], v[140:143], v[164:167], v[116:119]
	v_mfma_f32_16x16x32_bf16 v[112:115], v[148:151], v[164:167], v[112:115]
	v_mfma_f32_16x16x32_bf16 v[108:111], v[140:143], v[172:175], v[108:111]
	v_mfma_f32_16x16x32_bf16 v[100:103], v[140:143], v[180:183], v[100:103]
	v_mfma_f32_16x16x32_bf16 v[96:99], v[148:151], v[180:183], v[96:99]
	v_mfma_f32_16x16x32_bf16 v[124:127], v[144:147], v[160:163], v[124:127]
	v_mfma_f32_16x16x32_bf16 v[120:123], v[152:155], v[160:163], v[120:123]
	v_mfma_f32_16x16x32_bf16 v[116:119], v[144:147], v[168:171], v[116:119]
	v_mfma_f32_16x16x32_bf16 v[112:115], v[152:155], v[168:171], v[112:115]
	v_mfma_f32_16x16x32_bf16 v[108:111], v[144:147], v[176:179], v[108:111]
	v_mfma_f32_16x16x32_bf16 v[104:107], v[148:151], v[172:175], v[104:107]
	v_mfma_f32_16x16x32_bf16 v[100:103], v[144:147], v[184:187], v[100:103]
	v_mfma_f32_16x16x32_bf16 v[96:99], v[152:155], v[184:187], v[96:99]
	v_mfma_f32_16x16x32_bf16 v[128:131], v[152:155], v[176:179], v[104:107]
	s_setprio 0
	s_barrier
	s_nop 2
	ds_read_b128 v[104:107], v139
	ds_read_b128 v[188:191], v139 offset:1024
	ds_read_b128 v[192:195], v139 offset:2048
	ds_read_b128 v[202:205], v139 offset:3072
	s_barrier
	s_waitcnt lgkmcnt(0)
	s_setprio 1
	s_waitcnt lgkmcnt(0)
	v_mfma_f32_16x16x32_bf16 v[92:95], v[104:107], v[156:159], v[92:95]
	v_mfma_f32_16x16x32_bf16 v[84:87], v[104:107], v[164:167], v[84:87]
	v_mfma_f32_16x16x32_bf16 v[76:79], v[104:107], v[172:175], v[76:79]
	v_mfma_f32_16x16x32_bf16 v[68:71], v[104:107], v[180:183], v[68:71]
	v_mfma_f32_16x16x32_bf16 v[64:67], v[192:195], v[180:183], v[64:67]
	v_mfma_f32_16x16x32_bf16 v[92:95], v[188:191], v[160:163], v[92:95]
	v_mfma_f32_16x16x32_bf16 v[88:91], v[192:195], v[156:159], v[88:91]
	v_mfma_f32_16x16x32_bf16 v[84:87], v[188:191], v[168:171], v[84:87]
	v_mfma_f32_16x16x32_bf16 v[80:83], v[192:195], v[164:167], v[80:83]
	v_mfma_f32_16x16x32_bf16 v[76:79], v[188:191], v[176:179], v[76:79]
	v_mfma_f32_16x16x32_bf16 v[72:75], v[192:195], v[172:175], v[72:75]
	v_mfma_f32_16x16x32_bf16 v[68:71], v[188:191], v[184:187], v[68:71]
	v_mfma_f32_16x16x32_bf16 v[64:67], v[202:205], v[184:187], v[64:67]
	v_mfma_f32_16x16x32_bf16 v[156:159], v[202:205], v[160:163], v[88:91]
	v_mfma_f32_16x16x32_bf16 v[160:163], v[202:205], v[168:171], v[80:83]
	v_mfma_f32_16x16x32_bf16 v[164:167], v[202:205], v[176:179], v[72:75]
	s_setprio 0
	s_barrier
	s_nop 0
	ds_read_b128 v[72:75], v136 offset:16384
	ds_read_b128 v[80:83], v136 offset:17408
	ds_read_b128 v[88:91], v135 offset:16384
	ds_read_b128 v[168:171], v135 offset:17408
	ds_read_b128 v[172:175], v134 offset:16384
	ds_read_b128 v[176:179], v134 offset:17408
	ds_read_b128 v[180:183], v133 offset:16384
	ds_read_b128 v[184:187], v133 offset:17408
	s_waitcnt vmcnt(4)
	s_barrier
	s_waitcnt lgkmcnt(0)
	s_setprio 1
	s_waitcnt lgkmcnt(0)
	v_mfma_f32_16x16x32_bf16 v[60:63], v[140:143], v[72:75], v[60:63]
	v_mfma_f32_16x16x32_bf16 v[56:59], v[148:151], v[72:75], v[56:59]
	v_mfma_f32_16x16x32_bf16 v[48:51], v[148:151], v[88:91], v[48:51]
	v_mfma_f32_16x16x32_bf16 v[32:35], v[148:151], v[180:183], v[32:35]
	v_mfma_f32_16x16x32_bf16 v[60:63], v[144:147], v[80:83], v[60:63]
	v_mfma_f32_16x16x32_bf16 v[56:59], v[152:155], v[80:83], v[56:59]
	v_mfma_f32_16x16x32_bf16 v[52:55], v[140:143], v[88:91], v[52:55]
	v_mfma_f32_16x16x32_bf16 v[48:51], v[152:155], v[168:171], v[48:51]
	v_mfma_f32_16x16x32_bf16 v[44:47], v[140:143], v[172:175], v[44:47]
	v_mfma_f32_16x16x32_bf16 v[40:43], v[148:151], v[172:175], v[40:43]
	v_mfma_f32_16x16x32_bf16 v[36:39], v[140:143], v[180:183], v[36:39]
	v_mfma_f32_16x16x32_bf16 v[32:35], v[152:155], v[184:187], v[32:35]
	v_mfma_f32_16x16x32_bf16 v[206:209], v[144:147], v[168:171], v[52:55]
	v_mfma_f32_16x16x32_bf16 v[210:213], v[144:147], v[176:179], v[44:47]
	v_mfma_f32_16x16x32_bf16 v[214:217], v[152:155], v[176:179], v[40:43]
	v_mfma_f32_16x16x32_bf16 v[140:143], v[144:147], v[184:187], v[36:39]
	s_setprio 0
	s_setprio 1
	v_mfma_f32_16x16x32_bf16 v[24:27], v[192:195], v[72:75], v[24:27]
	v_mfma_f32_16x16x32_bf16 v[20:23], v[104:107], v[88:91], v[20:23]
	v_mfma_f32_16x16x32_bf16 v[28:31], v[104:107], v[72:75], v[28:31]
	v_mfma_f32_16x16x32_bf16 v[24:27], v[202:205], v[80:83], v[24:27]
	v_mfma_f32_16x16x32_bf16 v[20:23], v[188:191], v[168:171], v[20:23]
	v_mfma_f32_16x16x32_bf16 v[16:19], v[192:195], v[88:91], v[16:19]
	v_mfma_f32_16x16x32_bf16 v[12:15], v[104:107], v[172:175], v[12:15]
	v_mfma_f32_16x16x32_bf16 v[8:11], v[192:195], v[172:175], v[8:11]
	v_mfma_f32_16x16x32_bf16 v[4:7], v[104:107], v[180:183], v[4:7]
	v_mfma_f32_16x16x32_bf16 v[0:3], v[192:195], v[180:183], v[0:3]
	v_mfma_f32_16x16x32_bf16 v[144:147], v[188:191], v[80:83], v[28:31]
	v_mfma_f32_16x16x32_bf16 v[148:151], v[202:205], v[168:171], v[16:19]
	v_mfma_f32_16x16x32_bf16 v[152:155], v[188:191], v[176:179], v[12:15]
	v_mfma_f32_16x16x32_bf16 v[168:171], v[202:205], v[176:179], v[8:11]
	v_mfma_f32_16x16x32_bf16 v[172:175], v[188:191], v[184:187], v[4:7]
	v_mfma_f32_16x16x32_bf16 v[176:179], v[202:205], v[184:187], v[0:3]
	s_setprio 0
	s_barrier
	ds_read_b128 v[16:19], v138
	ds_read_b128 v[180:183], v138 offset:1024
	ds_read_b128 v[184:187], v138 offset:2048
	ds_read_b128 v[188:191], v138 offset:3072
	ds_read_b128 v[0:3], v136 offset:32768
	ds_read_b128 v[4:7], v136 offset:33792
	ds_read_b128 v[8:11], v135 offset:32768
	ds_read_b128 v[12:15], v135 offset:33792
	ds_read_b128 v[44:47], v134 offset:32768
	ds_read_b128 v[192:195], v134 offset:33792
	ds_read_b128 v[202:205], v133 offset:32768
	ds_read_b128 v[218:221], v133 offset:33792
	s_waitcnt vmcnt(2)
	s_barrier
	s_waitcnt lgkmcnt(0)
	s_setprio 1
	s_waitcnt lgkmcnt(0)
	v_mfma_f32_16x16x32_bf16 v[28:31], v[16:19], v[0:3], v[124:127]
	v_mfma_f32_16x16x32_bf16 v[52:55], v[180:183], v[4:7], v[28:31]
	v_mfma_f32_16x16x32_bf16 v[28:31], v[184:187], v[0:3], v[120:123]
	v_mfma_f32_16x16x32_bf16 v[104:107], v[188:191], v[4:7], v[28:31]
	v_mfma_f32_16x16x32_bf16 v[28:31], v[16:19], v[8:11], v[116:119]
	v_mfma_f32_16x16x32_bf16 v[72:75], v[180:183], v[12:15], v[28:31]
	v_mfma_f32_16x16x32_bf16 v[28:31], v[184:187], v[8:11], v[112:115]
	v_mfma_f32_16x16x32_bf16 v[116:119], v[188:191], v[12:15], v[28:31]
	v_mfma_f32_16x16x32_bf16 v[28:31], v[16:19], v[44:47], v[108:111]
	v_mfma_f32_16x16x32_bf16 v[80:83], v[180:183], v[192:195], v[28:31]
	v_mfma_f32_16x16x32_bf16 v[28:31], v[184:187], v[44:47], v[128:131]
	v_mfma_f32_16x16x32_bf16 v[108:111], v[188:191], v[192:195], v[28:31]
	v_mfma_f32_16x16x32_bf16 v[28:31], v[16:19], v[202:205], v[100:103]
	v_mfma_f32_16x16x32_bf16 v[88:91], v[180:183], v[218:221], v[28:31]
	v_mfma_f32_16x16x32_bf16 v[28:31], v[184:187], v[202:205], v[96:99]
	v_mfma_f32_16x16x32_bf16 v[96:99], v[188:191], v[218:221], v[28:31]
	s_setprio 0
	s_barrier
	ds_read_b128 v[128:131], v137
	ds_read_b128 v[222:225], v137 offset:1024
	ds_read_b128 v[228:231], v137 offset:2048
	ds_read_b128 v[232:235], v137 offset:3072
	s_waitcnt vmcnt(0)
	s_barrier
	s_waitcnt lgkmcnt(0)
	s_setprio 1
	s_waitcnt lgkmcnt(0)
	v_mfma_f32_16x16x32_bf16 v[28:31], v[128:131], v[0:3], v[92:95]
	v_mfma_f32_16x16x32_bf16 v[0:3], v[228:231], v[0:3], v[156:159]
	v_mfma_f32_16x16x32_bf16 v[28:31], v[222:225], v[4:7], v[28:31]
	v_mfma_f32_16x16x32_bf16 v[0:3], v[232:235], v[4:7], v[0:3]
	v_mfma_f32_16x16x32_bf16 v[4:7], v[128:131], v[8:11], v[84:87]
	v_mfma_f32_16x16x32_bf16 v[36:39], v[222:225], v[12:15], v[4:7]
	v_mfma_f32_16x16x32_bf16 v[4:7], v[228:231], v[8:11], v[160:163]
	v_mfma_f32_16x16x32_bf16 v[4:7], v[232:235], v[12:15], v[4:7]
	v_mfma_f32_16x16x32_bf16 v[8:11], v[128:131], v[44:47], v[76:79]
	v_mfma_f32_16x16x32_bf16 v[12:15], v[128:131], v[202:205], v[68:71]
	v_mfma_f32_16x16x32_bf16 v[40:43], v[222:225], v[192:195], v[8:11]
	v_mfma_f32_16x16x32_bf16 v[8:11], v[228:231], v[44:47], v[164:167]
	v_mfma_f32_16x16x32_bf16 v[44:47], v[222:225], v[218:221], v[12:15]
	v_mfma_f32_16x16x32_bf16 v[12:15], v[228:231], v[202:205], v[64:67]
	v_mfma_f32_16x16x32_bf16 v[8:11], v[232:235], v[192:195], v[8:11]
	v_mfma_f32_16x16x32_bf16 v[12:15], v[232:235], v[218:221], v[12:15]
	s_setprio 0
	s_barrier
	ds_read_b128 v[64:67], v136 offset:49152
	ds_read_b128 v[136:139], v136 offset:50176
	ds_read_b128 v[156:159], v135 offset:49152
	ds_read_b128 v[160:163], v135 offset:50176
	ds_read_b128 v[164:167], v134 offset:49152
	ds_read_b128 v[192:195], v134 offset:50176
	ds_read_b128 v[202:205], v133 offset:49152
	ds_read_b128 v[218:221], v133 offset:50176
	s_barrier
	s_waitcnt lgkmcnt(0)
	s_setprio 1
	s_waitcnt lgkmcnt(0)
	v_mfma_f32_16x16x32_bf16 v[56:59], v[184:187], v[64:67], v[56:59]
	v_mfma_f32_16x16x32_bf16 v[48:51], v[184:187], v[156:159], v[48:51]
	v_mfma_f32_16x16x32_bf16 v[60:63], v[16:19], v[64:67], v[60:63]
	v_mfma_f32_16x16x32_bf16 v[92:95], v[188:191], v[136:139], v[56:59]
	v_mfma_f32_16x16x32_bf16 v[56:59], v[16:19], v[156:159], v[206:209]
	v_mfma_f32_16x16x32_bf16 v[84:87], v[188:191], v[160:163], v[48:51]
	v_mfma_f32_16x16x32_bf16 v[48:51], v[16:19], v[164:167], v[210:213]
	v_mfma_f32_16x16x32_bf16 v[16:19], v[16:19], v[202:205], v[140:143]
	v_mfma_f32_16x16x32_bf16 v[120:123], v[180:183], v[192:195], v[48:51]
	v_mfma_f32_16x16x32_bf16 v[48:51], v[184:187], v[164:167], v[214:217]
	v_mfma_f32_16x16x32_bf16 v[124:127], v[180:183], v[218:221], v[16:19]
	v_mfma_f32_16x16x32_bf16 v[16:19], v[184:187], v[202:205], v[32:35]
	v_mfma_f32_16x16x32_bf16 v[100:103], v[180:183], v[136:139], v[60:63]
	v_mfma_f32_16x16x32_bf16 v[112:115], v[180:183], v[160:163], v[56:59]
	v_mfma_f32_16x16x32_bf16 v[76:79], v[188:191], v[192:195], v[48:51]
	v_mfma_f32_16x16x32_bf16 v[68:71], v[188:191], v[218:221], v[16:19]
	s_setprio 0
	s_setprio 1
	v_mfma_f32_16x16x32_bf16 v[16:19], v[128:131], v[64:67], v[144:147]
	v_mfma_f32_16x16x32_bf16 v[48:51], v[222:225], v[136:139], v[16:19]
	v_mfma_f32_16x16x32_bf16 v[16:19], v[228:231], v[64:67], v[24:27]
	v_mfma_f32_16x16x32_bf16 v[20:23], v[128:131], v[156:159], v[20:23]
	v_mfma_f32_16x16x32_bf16 v[24:27], v[128:131], v[164:167], v[152:155]
	v_mfma_f32_16x16x32_bf16 v[32:35], v[128:131], v[202:205], v[172:175]
	v_mfma_f32_16x16x32_bf16 v[56:59], v[222:225], v[160:163], v[20:23]
	v_mfma_f32_16x16x32_bf16 v[20:23], v[228:231], v[156:159], v[148:151]
	v_mfma_f32_16x16x32_bf16 v[60:63], v[222:225], v[192:195], v[24:27]
	v_mfma_f32_16x16x32_bf16 v[24:27], v[228:231], v[164:167], v[168:171]
	v_mfma_f32_16x16x32_bf16 v[64:67], v[222:225], v[218:221], v[32:35]
	v_mfma_f32_16x16x32_bf16 v[32:35], v[228:231], v[202:205], v[176:179]
	v_mfma_f32_16x16x32_bf16 v[16:19], v[232:235], v[136:139], v[16:19]
	v_mfma_f32_16x16x32_bf16 v[20:23], v[232:235], v[160:163], v[20:23]
	v_mfma_f32_16x16x32_bf16 v[24:27], v[232:235], v[192:195], v[24:27]
	v_mfma_f32_16x16x32_bf16 v[32:35], v[232:235], v[218:221], v[32:35]
	s_setprio 0
	s_movk_i32 s9, 0x100
	v_cmp_gt_u32_e32 vcc, s9, v132
	s_barrier
	s_and_saveexec_b64 s[28:29], vcc
	s_cbranch_execz .LBB0_212
	s_barrier
	s_branch .LBB0_212

.LBB0_314:
	ds_read_b128 v[172:175], v170
	ds_read_b128 v[176:179], v170 offset:1024
	ds_read_b128 v[180:183], v170 offset:2048
	ds_read_b128 v[184:187], v170 offset:3072
	s_add_u32 s8, s37, vcc_lo
	s_addc_u32 s9, s38, vcc_hi
	ds_read_b128 v[188:191], v166
	ds_read_b128 v[192:195], v166 offset:1024
	ds_read_b128 v[202:205], v165
	ds_read_b128 v[206:209], v165 offset:1024
	ds_read_b128 v[210:213], v163
	ds_read_b128 v[214:217], v163 offset:1024
	ds_read_b128 v[218:221], v162
	ds_read_b128 v[236:239], v162 offset:1024
	s_add_i32 s40, s34, 0xc000
	s_mov_b32 m0, s40
	s_add_i32 s41, s34, 0xe000
	s_add_u32 s98, s8, s94
	s_addc_u32 s99, s9, s95
	global_load_lds_dwordx4 v160, s[98:99]
	s_mov_b32 m0, s41
	s_nop 0
	global_load_lds_dwordx4 v161, s[98:99]
	s_waitcnt lgkmcnt(8)
	s_barrier
	s_waitcnt lgkmcnt(0)
	s_setprio 0
	s_waitcnt lgkmcnt(0)
	v_mfma_f32_16x16x32_bf16 v[44:47], v[172:175], v[188:191], v[44:47]
	v_mfma_f32_16x16x32_bf16 v[40:43], v[180:183], v[188:191], v[40:43]
	v_mfma_f32_16x16x32_bf16 v[60:63], v[172:175], v[202:205], v[60:63]
	v_mfma_f32_16x16x32_bf16 v[56:59], v[180:183], v[202:205], v[56:59]
	v_mfma_f32_16x16x32_bf16 v[76:79], v[172:175], v[210:213], v[76:79]
	v_mfma_f32_16x16x32_bf16 v[72:75], v[180:183], v[210:213], v[72:75]
	v_mfma_f32_16x16x32_bf16 v[92:95], v[172:175], v[218:221], v[92:95]
	v_mfma_f32_16x16x32_bf16 v[88:91], v[180:183], v[218:221], v[88:91]
	v_mfma_f32_16x16x32_bf16 v[44:47], v[176:179], v[192:195], v[44:47]
	v_mfma_f32_16x16x32_bf16 v[40:43], v[184:187], v[192:195], v[40:43]
	v_mfma_f32_16x16x32_bf16 v[60:63], v[176:179], v[206:209], v[60:63]
	v_mfma_f32_16x16x32_bf16 v[56:59], v[184:187], v[206:209], v[56:59]
	v_mfma_f32_16x16x32_bf16 v[76:79], v[176:179], v[214:217], v[76:79]
	v_mfma_f32_16x16x32_bf16 v[72:75], v[184:187], v[214:217], v[72:75]
	v_mfma_f32_16x16x32_bf16 v[92:95], v[176:179], v[236:239], v[92:95]
	v_mfma_f32_16x16x32_bf16 v[88:91], v[184:187], v[236:239], v[88:91]
	s_setprio 1
	s_barrier
	s_add_i32 s39, s39, 2
	s_add_u32 s28, s6, vcc_lo
	s_addc_u32 s29, s7, vcc_hi
	ds_read_b128 v[240:243], v169
	ds_read_b128 v[244:247], v169 offset:1024
	ds_read_b128 v[248:251], v169 offset:2048
	ds_read_b128 v[228:231], v169 offset:3072
	s_mov_b32 m0, s59
	s_add_u32 s98, s28, s0
	s_addc_u32 s99, s29, s1
	global_load_lds_dwordx4 v160, s[98:99]
	s_mov_b32 m0, s61
	s_nop 0
	global_load_lds_dwordx4 v161, s[98:99]
	s_barrier
	s_waitcnt lgkmcnt(0)
	s_setprio 0
	s_waitcnt lgkmcnt(0)
	v_mfma_f32_16x16x32_bf16 v[32:35], v[240:243], v[188:191], v[32:35]
	v_mfma_f32_16x16x32_bf16 v[36:39], v[248:251], v[188:191], v[36:39]
	v_mfma_f32_16x16x32_bf16 v[48:51], v[240:243], v[202:205], v[48:51]
	v_mfma_f32_16x16x32_bf16 v[52:55], v[248:251], v[202:205], v[52:55]
	v_mfma_f32_16x16x32_bf16 v[64:67], v[240:243], v[210:213], v[64:67]
	v_mfma_f32_16x16x32_bf16 v[68:71], v[248:251], v[210:213], v[68:71]
	v_mfma_f32_16x16x32_bf16 v[80:83], v[240:243], v[218:221], v[80:83]
	v_mfma_f32_16x16x32_bf16 v[84:87], v[248:251], v[218:221], v[84:87]
	v_mfma_f32_16x16x32_bf16 v[32:35], v[244:247], v[192:195], v[32:35]
	v_mfma_f32_16x16x32_bf16 v[36:39], v[228:231], v[192:195], v[36:39]
	v_mfma_f32_16x16x32_bf16 v[48:51], v[244:247], v[206:209], v[48:51]
	v_mfma_f32_16x16x32_bf16 v[52:55], v[228:231], v[206:209], v[52:55]
	v_mfma_f32_16x16x32_bf16 v[64:67], v[244:247], v[214:217], v[64:67]
	v_mfma_f32_16x16x32_bf16 v[68:71], v[228:231], v[214:217], v[68:71]
	v_mfma_f32_16x16x32_bf16 v[80:83], v[244:247], v[236:239], v[80:83]
	v_mfma_f32_16x16x32_bf16 v[84:87], v[228:231], v[236:239], v[84:87]
	s_setprio 1
	s_add_u32 s92, s90, vcc_lo
	s_addc_u32 s93, s91, vcc_hi
	s_barrier
	ds_read_b128 v[188:191], v166 offset:16384
	ds_read_b128 v[192:195], v166 offset:17408
	ds_read_b128 v[202:205], v165 offset:16384
	ds_read_b128 v[206:209], v165 offset:17408
	ds_read_b128 v[210:213], v163 offset:16384
	ds_read_b128 v[214:217], v163 offset:17408
	ds_read_b128 v[218:221], v162 offset:16384
	ds_read_b128 v[236:239], v162 offset:17408
	s_mov_b32 m0, s34
	s_add_u32 s98, s92, s0
	s_addc_u32 s99, s93, s1
	global_load_lds_dwordx4 v160, s[98:99]
	s_mov_b32 m0, s79
	s_nop 0
	global_load_lds_dwordx4 v161, s[98:99]
	s_barrier
	s_waitcnt lgkmcnt(0)
	s_setprio 0
	s_waitcnt lgkmcnt(0)
	v_mfma_f32_16x16x32_bf16 v[108:111], v[172:175], v[188:191], v[108:111]
	v_mfma_f32_16x16x32_bf16 v[104:107], v[180:183], v[188:191], v[104:107]
	v_mfma_f32_16x16x32_bf16 v[124:127], v[172:175], v[202:205], v[124:127]
	v_mfma_f32_16x16x32_bf16 v[120:123], v[180:183], v[202:205], v[120:123]
	v_mfma_f32_16x16x32_bf16 v[140:143], v[172:175], v[210:213], v[140:143]
	v_mfma_f32_16x16x32_bf16 v[136:139], v[180:183], v[210:213], v[136:139]
	v_mfma_f32_16x16x32_bf16 v[156:159], v[172:175], v[218:221], v[156:159]
	v_mfma_f32_16x16x32_bf16 v[152:155], v[180:183], v[218:221], v[152:155]
	v_mfma_f32_16x16x32_bf16 v[108:111], v[176:179], v[192:195], v[108:111]
	v_mfma_f32_16x16x32_bf16 v[104:107], v[184:187], v[192:195], v[104:107]
	v_mfma_f32_16x16x32_bf16 v[124:127], v[176:179], v[206:209], v[124:127]
	v_mfma_f32_16x16x32_bf16 v[120:123], v[184:187], v[206:209], v[120:123]
	v_mfma_f32_16x16x32_bf16 v[140:143], v[176:179], v[214:217], v[140:143]
	v_mfma_f32_16x16x32_bf16 v[136:139], v[184:187], v[214:217], v[136:139]
	v_mfma_f32_16x16x32_bf16 v[156:159], v[176:179], v[236:239], v[156:159]
	v_mfma_f32_16x16x32_bf16 v[152:155], v[184:187], v[236:239], v[152:155]
	s_setprio 1
	s_barrier
	s_add_u32 s96, s82, vcc_lo
	s_addc_u32 s97, s36, vcc_hi
	s_mov_b32 m0, s52
	s_add_u32 s98, s96, s0
	s_addc_u32 s99, s97, s1
	global_load_lds_dwordx4 v160, s[98:99]
	s_mov_b32 m0, s53
	s_nop 0
	global_load_lds_dwordx4 v161, s[98:99]
	s_waitcnt vmcnt(6)
	s_barrier
	s_setprio 0
	v_mfma_f32_16x16x32_bf16 v[96:99], v[240:243], v[188:191], v[96:99]
	v_mfma_f32_16x16x32_bf16 v[100:103], v[248:251], v[188:191], v[100:103]
	v_mfma_f32_16x16x32_bf16 v[112:115], v[240:243], v[202:205], v[112:115]
	v_mfma_f32_16x16x32_bf16 v[116:119], v[248:251], v[202:205], v[116:119]
	v_mfma_f32_16x16x32_bf16 v[128:131], v[240:243], v[210:213], v[128:131]
	v_mfma_f32_16x16x32_bf16 v[132:135], v[248:251], v[210:213], v[132:135]
	v_mfma_f32_16x16x32_bf16 v[144:147], v[240:243], v[218:221], v[144:147]
	v_mfma_f32_16x16x32_bf16 v[148:151], v[248:251], v[218:221], v[148:151]
	v_mfma_f32_16x16x32_bf16 v[96:99], v[244:247], v[192:195], v[96:99]
	v_mfma_f32_16x16x32_bf16 v[100:103], v[228:231], v[192:195], v[100:103]
	v_mfma_f32_16x16x32_bf16 v[112:115], v[244:247], v[206:209], v[112:115]
	v_mfma_f32_16x16x32_bf16 v[116:119], v[228:231], v[206:209], v[116:119]
	v_mfma_f32_16x16x32_bf16 v[128:131], v[244:247], v[214:217], v[128:131]
	v_mfma_f32_16x16x32_bf16 v[132:135], v[228:231], v[214:217], v[132:135]
	v_mfma_f32_16x16x32_bf16 v[144:147], v[244:247], v[236:239], v[144:147]
	v_mfma_f32_16x16x32_bf16 v[148:151], v[228:231], v[236:239], v[148:151]
	s_setprio 1
	s_barrier
	ds_read_b128 v[172:175], v168
	ds_read_b128 v[176:179], v168 offset:1024
	ds_read_b128 v[180:183], v168 offset:2048
	ds_read_b128 v[184:187], v168 offset:3072
	ds_read_b128 v[188:191], v166 offset:32768
	ds_read_b128 v[192:195], v166 offset:33792
	ds_read_b128 v[202:205], v165 offset:32768
	ds_read_b128 v[206:209], v165 offset:33792
	ds_read_b128 v[210:213], v163 offset:32768
	ds_read_b128 v[214:217], v163 offset:33792
	ds_read_b128 v[218:221], v162 offset:32768
	ds_read_b128 v[228:231], v162 offset:33792
	s_mov_b32 m0, s68
	s_add_u32 s98, s8, s0
	s_addc_u32 s99, s9, s1
	global_load_lds_dwordx4 v160, s[98:99]
	s_mov_b32 m0, s69
	s_nop 0
	global_load_lds_dwordx4 v161, s[98:99]
	s_waitcnt lgkmcnt(8)
	s_barrier
	s_waitcnt lgkmcnt(0)
	s_setprio 0
	s_waitcnt lgkmcnt(0)
	v_mfma_f32_16x16x32_bf16 v[44:47], v[172:175], v[188:191], v[44:47]
	v_mfma_f32_16x16x32_bf16 v[40:43], v[180:183], v[188:191], v[40:43]
	v_mfma_f32_16x16x32_bf16 v[60:63], v[172:175], v[202:205], v[60:63]
	v_mfma_f32_16x16x32_bf16 v[56:59], v[180:183], v[202:205], v[56:59]
	v_mfma_f32_16x16x32_bf16 v[76:79], v[172:175], v[210:213], v[76:79]
	v_mfma_f32_16x16x32_bf16 v[72:75], v[180:183], v[210:213], v[72:75]
	v_mfma_f32_16x16x32_bf16 v[92:95], v[172:175], v[218:221], v[92:95]
	v_mfma_f32_16x16x32_bf16 v[88:91], v[180:183], v[218:221], v[88:91]
	v_mfma_f32_16x16x32_bf16 v[44:47], v[176:179], v[192:195], v[44:47]
	v_mfma_f32_16x16x32_bf16 v[40:43], v[184:187], v[192:195], v[40:43]
	v_mfma_f32_16x16x32_bf16 v[60:63], v[176:179], v[206:209], v[60:63]
	v_mfma_f32_16x16x32_bf16 v[56:59], v[184:187], v[206:209], v[56:59]
	v_mfma_f32_16x16x32_bf16 v[76:79], v[176:179], v[214:217], v[76:79]
	v_mfma_f32_16x16x32_bf16 v[72:75], v[184:187], v[214:217], v[72:75]
	v_mfma_f32_16x16x32_bf16 v[92:95], v[176:179], v[228:231], v[92:95]
	v_mfma_f32_16x16x32_bf16 v[88:91], v[184:187], v[228:231], v[88:91]
	s_setprio 1
	s_barrier
	ds_read_b128 v[236:239], v167
	ds_read_b128 v[240:243], v167 offset:1024
	ds_read_b128 v[244:247], v167 offset:2048
	ds_read_b128 v[248:251], v167 offset:3072
	s_mov_b32 m0, s70
	s_add_u32 s98, s28, s30
	s_addc_u32 s99, s29, s31
	global_load_lds_dwordx4 v160, s[98:99]
	s_mov_b32 m0, s71
	s_nop 0
	global_load_lds_dwordx4 v161, s[98:99]
	s_barrier
	s_waitcnt lgkmcnt(0)
	s_setprio 0
	s_waitcnt lgkmcnt(0)
	v_mfma_f32_16x16x32_bf16 v[32:35], v[236:239], v[188:191], v[32:35]
	v_mfma_f32_16x16x32_bf16 v[36:39], v[244:247], v[188:191], v[36:39]
	v_mfma_f32_16x16x32_bf16 v[48:51], v[236:239], v[202:205], v[48:51]
	v_mfma_f32_16x16x32_bf16 v[52:55], v[244:247], v[202:205], v[52:55]
	v_mfma_f32_16x16x32_bf16 v[64:67], v[236:239], v[210:213], v[64:67]
	v_mfma_f32_16x16x32_bf16 v[68:71], v[244:247], v[210:213], v[68:71]
	v_mfma_f32_16x16x32_bf16 v[80:83], v[236:239], v[218:221], v[80:83]
	v_mfma_f32_16x16x32_bf16 v[84:87], v[244:247], v[218:221], v[84:87]
	v_mfma_f32_16x16x32_bf16 v[32:35], v[240:243], v[192:195], v[32:35]
	v_mfma_f32_16x16x32_bf16 v[36:39], v[248:251], v[192:195], v[36:39]
	v_mfma_f32_16x16x32_bf16 v[48:51], v[240:243], v[206:209], v[48:51]
	v_mfma_f32_16x16x32_bf16 v[52:55], v[248:251], v[206:209], v[52:55]
	v_mfma_f32_16x16x32_bf16 v[64:67], v[240:243], v[214:217], v[64:67]
	v_mfma_f32_16x16x32_bf16 v[68:71], v[248:251], v[214:217], v[68:71]
	v_mfma_f32_16x16x32_bf16 v[80:83], v[240:243], v[228:231], v[80:83]
	v_mfma_f32_16x16x32_bf16 v[84:87], v[248:251], v[228:231], v[84:87]
	s_setprio 1
	v_mov_b32_e32 v222, v161
	s_barrier
	ds_read_b128 v[188:191], v166 offset:49152
	ds_read_b128 v[192:195], v166 offset:50176
	ds_read_b128 v[202:205], v165 offset:49152
	ds_read_b128 v[206:209], v165 offset:50176
	ds_read_b128 v[210:213], v163 offset:49152
	ds_read_b128 v[214:217], v163 offset:50176
	ds_read_b128 v[218:221], v162 offset:49152
	ds_read_b128 v[228:231], v162 offset:50176
	v_mov_b32_e32 v223, v197
	s_mov_b32 m0, s72
	s_add_u32 s98, s92, s30
	s_addc_u32 s99, s93, s31
	global_load_lds_dwordx4 v160, s[98:99]
	s_mov_b32 m0, s73
	s_nop 0
	global_load_lds_dwordx4 v161, s[98:99]
	s_barrier
	s_waitcnt lgkmcnt(0)
	s_setprio 0
	s_waitcnt lgkmcnt(0)
	v_mfma_f32_16x16x32_bf16 v[108:111], v[172:175], v[188:191], v[108:111]
	v_mfma_f32_16x16x32_bf16 v[104:107], v[180:183], v[188:191], v[104:107]
	v_mfma_f32_16x16x32_bf16 v[124:127], v[172:175], v[202:205], v[124:127]
	v_mfma_f32_16x16x32_bf16 v[120:123], v[180:183], v[202:205], v[120:123]
	v_mfma_f32_16x16x32_bf16 v[140:143], v[172:175], v[210:213], v[140:143]
	v_mfma_f32_16x16x32_bf16 v[136:139], v[180:183], v[210:213], v[136:139]
	v_mfma_f32_16x16x32_bf16 v[156:159], v[172:175], v[218:221], v[156:159]
	v_mfma_f32_16x16x32_bf16 v[152:155], v[180:183], v[218:221], v[152:155]
	v_mfma_f32_16x16x32_bf16 v[108:111], v[176:179], v[192:195], v[108:111]
	v_mfma_f32_16x16x32_bf16 v[104:107], v[184:187], v[192:195], v[104:107]
	v_mfma_f32_16x16x32_bf16 v[124:127], v[176:179], v[206:209], v[124:127]
	v_mfma_f32_16x16x32_bf16 v[120:123], v[184:187], v[206:209], v[120:123]
	v_mfma_f32_16x16x32_bf16 v[140:143], v[176:179], v[214:217], v[140:143]
	v_mfma_f32_16x16x32_bf16 v[136:139], v[184:187], v[214:217], v[136:139]
	v_mfma_f32_16x16x32_bf16 v[156:159], v[176:179], v[228:231], v[156:159]
	v_mfma_f32_16x16x32_bf16 v[152:155], v[184:187], v[228:231], v[152:155]
	s_setprio 1
	s_barrier
	v_mov_b32_e32 v196, v160
	s_mov_b32 m0, s75
	s_add_u32 s98, s96, s30
	s_addc_u32 s99, s97, s31
	global_load_lds_dwordx4 v160, s[98:99]
	s_mov_b32 m0, s89
	s_nop 0
	global_load_lds_dwordx4 v161, s[98:99]
	s_waitcnt vmcnt(6)
	s_barrier
	s_setprio 0
	v_mfma_f32_16x16x32_bf16 v[96:99], v[236:239], v[188:191], v[96:99]
	v_mfma_f32_16x16x32_bf16 v[100:103], v[244:247], v[188:191], v[100:103]
	v_mfma_f32_16x16x32_bf16 v[112:115], v[236:239], v[202:205], v[112:115]
	v_mfma_f32_16x16x32_bf16 v[116:119], v[244:247], v[202:205], v[116:119]
	v_mfma_f32_16x16x32_bf16 v[128:131], v[236:239], v[210:213], v[128:131]
	v_mfma_f32_16x16x32_bf16 v[132:135], v[244:247], v[210:213], v[132:135]
	v_mfma_f32_16x16x32_bf16 v[144:147], v[236:239], v[218:221], v[144:147]
	v_mfma_f32_16x16x32_bf16 v[148:151], v[244:247], v[218:221], v[148:151]
	v_mfma_f32_16x16x32_bf16 v[96:99], v[240:243], v[192:195], v[96:99]
	v_mfma_f32_16x16x32_bf16 v[100:103], v[248:251], v[192:195], v[100:103]
	v_mfma_f32_16x16x32_bf16 v[112:115], v[240:243], v[206:209], v[112:115]
	v_mfma_f32_16x16x32_bf16 v[116:119], v[248:251], v[206:209], v[116:119]
	v_mfma_f32_16x16x32_bf16 v[128:131], v[240:243], v[214:217], v[128:131]
	v_mfma_f32_16x16x32_bf16 v[132:135], v[248:251], v[214:217], v[132:135]
	v_mfma_f32_16x16x32_bf16 v[144:147], v[240:243], v[228:231], v[144:147]
	v_mfma_f32_16x16x32_bf16 v[148:151], v[248:251], v[228:231], v[148:151]
	s_setprio 1
	s_add_u32 vcc_lo, vcc_lo, 0x100
	s_addc_u32 vcc_hi, vcc_hi, 0
	s_cmp_lt_u32 s39, s74
	s_barrier
	s_cbranch_scc1 .LBB0_314
	s_setprio 0
	s_add_i32 s34, s33, -1
	s_lshl_b64 s[6:7], s[34:35], 7
	s_add_u32 s6, s84, s6
	s_addc_u32 s7, s85, s7
	s_mov_b32 m0, s40
	ds_read_b128 v[172:175], v170
	ds_read_b128 v[176:179], v170 offset:1024
	ds_read_b128 v[180:183], v170 offset:2048
	ds_read_b128 v[184:187], v170 offset:3072
	ds_read_b128 v[188:191], v166
	ds_read_b128 v[192:195], v166 offset:1024
	ds_read_b128 v[202:205], v165
	ds_read_b128 v[206:209], v165 offset:1024
	ds_read_b128 v[210:213], v163
	ds_read_b128 v[214:217], v163 offset:1024
	ds_read_b128 v[218:221], v162
	ds_read_b128 v[228:231], v162 offset:1024
	s_nop 0
	global_load_lds_dwordx4 v160, s[6:7]
	s_mov_b32 m0, s41
	s_nop 0
	global_load_lds_dwordx4 v161, s[6:7]
	s_barrier
	s_waitcnt lgkmcnt(0)
	s_setprio 1
	s_waitcnt lgkmcnt(0)
	v_mfma_f32_16x16x32_bf16 v[40:43], v[180:183], v[188:191], v[40:43]
	v_mfma_f32_16x16x32_bf16 v[56:59], v[180:183], v[202:205], v[56:59]
	v_mfma_f32_16x16x32_bf16 v[72:75], v[180:183], v[210:213], v[72:75]
	v_mfma_f32_16x16x32_bf16 v[92:95], v[172:175], v[218:221], v[92:95]
	v_mfma_f32_16x16x32_bf16 v[88:91], v[180:183], v[218:221], v[88:91]
	v_mfma_f32_16x16x32_bf16 v[44:47], v[172:175], v[188:191], v[44:47]
	v_mfma_f32_16x16x32_bf16 v[40:43], v[184:187], v[192:195], v[40:43]
	v_mfma_f32_16x16x32_bf16 v[60:63], v[172:175], v[202:205], v[60:63]
	v_mfma_f32_16x16x32_bf16 v[56:59], v[184:187], v[206:209], v[56:59]
	v_mfma_f32_16x16x32_bf16 v[76:79], v[172:175], v[210:213], v[76:79]
	v_mfma_f32_16x16x32_bf16 v[72:75], v[184:187], v[214:217], v[72:75]
	v_mfma_f32_16x16x32_bf16 v[92:95], v[176:179], v[228:231], v[92:95]
	v_mfma_f32_16x16x32_bf16 v[88:91], v[184:187], v[228:231], v[88:91]
	v_mfma_f32_16x16x32_bf16 v[44:47], v[176:179], v[192:195], v[44:47]
	v_mfma_f32_16x16x32_bf16 v[60:63], v[176:179], v[206:209], v[60:63]
	v_mfma_f32_16x16x32_bf16 v[76:79], v[176:179], v[214:217], v[76:79]
	s_setprio 0
	s_barrier
	ds_read_b128 v[236:239], v169
	ds_read_b128 v[240:243], v169 offset:1024
	ds_read_b128 v[244:247], v169 offset:2048
	ds_read_b128 v[248:251], v169 offset:3072
	s_barrier
	s_waitcnt lgkmcnt(0)
	s_setprio 1
	s_waitcnt lgkmcnt(0)
	v_mfma_f32_16x16x32_bf16 v[36:39], v[244:247], v[188:191], v[36:39]
	v_mfma_f32_16x16x32_bf16 v[32:35], v[236:239], v[188:191], v[32:35]
	v_mfma_f32_16x16x32_bf16 v[188:191], v[248:251], v[192:195], v[36:39]
	v_mfma_f32_16x16x32_bf16 v[36:39], v[236:239], v[202:205], v[48:51]
	v_mfma_f32_16x16x32_bf16 v[48:51], v[240:243], v[206:209], v[36:39]
	v_mfma_f32_16x16x32_bf16 v[36:39], v[244:247], v[202:205], v[52:55]
	v_mfma_f32_16x16x32_bf16 v[32:35], v[240:243], v[192:195], v[32:35]
	v_mfma_f32_16x16x32_bf16 v[192:195], v[248:251], v[206:209], v[36:39]
	v_mfma_f32_16x16x32_bf16 v[36:39], v[236:239], v[210:213], v[64:67]
	v_mfma_f32_16x16x32_bf16 v[64:67], v[240:243], v[214:217], v[36:39]
	v_mfma_f32_16x16x32_bf16 v[36:39], v[244:247], v[210:213], v[68:71]
	v_mfma_f32_16x16x32_bf16 v[202:205], v[248:251], v[214:217], v[36:39]
	v_mfma_f32_16x16x32_bf16 v[36:39], v[236:239], v[218:221], v[80:83]
	v_mfma_f32_16x16x32_bf16 v[80:83], v[240:243], v[228:231], v[36:39]
	v_mfma_f32_16x16x32_bf16 v[36:39], v[244:247], v[218:221], v[84:87]
	v_mfma_f32_16x16x32_bf16 v[206:209], v[248:251], v[228:231], v[36:39]
	s_setprio 0
	s_barrier
	s_nop 4
	ds_read_b128 v[36:39], v166 offset:16384
	ds_read_b128 v[52:55], v166 offset:17408
	ds_read_b128 v[68:71], v165 offset:16384
	ds_read_b128 v[84:87], v165 offset:17408
	ds_read_b128 v[210:213], v163 offset:16384
	ds_read_b128 v[214:217], v163 offset:17408
	ds_read_b128 v[218:221], v162 offset:16384
	ds_read_b128 v[228:231], v162 offset:17408
	s_waitcnt vmcnt(4)
	s_barrier
	s_waitcnt lgkmcnt(0)
	s_setprio 1
	s_waitcnt lgkmcnt(0)
	v_mfma_f32_16x16x32_bf16 v[108:111], v[172:175], v[36:39], v[108:111]
	v_mfma_f32_16x16x32_bf16 v[222:225], v[176:179], v[52:55], v[108:111]
	v_mfma_f32_16x16x32_bf16 v[108:111], v[172:175], v[68:71], v[124:127]
	v_mfma_f32_16x16x32_bf16 v[124:127], v[176:179], v[84:87], v[108:111]
	v_mfma_f32_16x16x32_bf16 v[108:111], v[180:183], v[68:71], v[120:123]
	v_mfma_f32_16x16x32_bf16 v[120:123], v[184:187], v[84:87], v[108:111]
	v_mfma_f32_16x16x32_bf16 v[108:111], v[172:175], v[210:213], v[140:143]
	v_mfma_f32_16x16x32_bf16 v[140:143], v[176:179], v[214:217], v[108:111]
	v_mfma_f32_16x16x32_bf16 v[108:111], v[180:183], v[210:213], v[136:139]
	v_mfma_f32_16x16x32_bf16 v[136:139], v[184:187], v[214:217], v[108:111]
	v_mfma_f32_16x16x32_bf16 v[108:111], v[172:175], v[218:221], v[156:159]
	v_mfma_f32_16x16x32_bf16 v[104:107], v[180:183], v[36:39], v[104:107]
	v_mfma_f32_16x16x32_bf16 v[156:159], v[176:179], v[228:231], v[108:111]
	v_mfma_f32_16x16x32_bf16 v[108:111], v[180:183], v[218:221], v[152:155]
	v_mfma_f32_16x16x32_bf16 v[104:107], v[184:187], v[52:55], v[104:107]
	v_mfma_f32_16x16x32_bf16 v[152:155], v[184:187], v[228:231], v[108:111]
	s_setprio 0
	s_setprio 1
	v_mfma_f32_16x16x32_bf16 v[96:99], v[236:239], v[36:39], v[96:99]
	v_mfma_f32_16x16x32_bf16 v[36:39], v[244:247], v[36:39], v[100:103]
	v_mfma_f32_16x16x32_bf16 v[172:175], v[248:251], v[52:55], v[36:39]
	v_mfma_f32_16x16x32_bf16 v[36:39], v[236:239], v[68:71], v[112:115]
	v_mfma_f32_16x16x32_bf16 v[112:115], v[240:243], v[84:87], v[36:39]
	v_mfma_f32_16x16x32_bf16 v[36:39], v[244:247], v[68:71], v[116:119]
	v_mfma_f32_16x16x32_bf16 v[180:183], v[248:251], v[84:87], v[36:39]
	v_mfma_f32_16x16x32_bf16 v[36:39], v[236:239], v[210:213], v[128:131]
	v_mfma_f32_16x16x32_bf16 v[128:131], v[240:243], v[214:217], v[36:39]
	v_mfma_f32_16x16x32_bf16 v[36:39], v[244:247], v[210:213], v[132:135]
	v_mfma_f32_16x16x32_bf16 v[184:187], v[248:251], v[214:217], v[36:39]
	v_mfma_f32_16x16x32_bf16 v[36:39], v[236:239], v[218:221], v[144:147]
	v_mfma_f32_16x16x32_bf16 v[96:99], v[240:243], v[52:55], v[96:99]
	v_mfma_f32_16x16x32_bf16 v[144:147], v[240:243], v[228:231], v[36:39]
	v_mfma_f32_16x16x32_bf16 v[36:39], v[244:247], v[218:221], v[148:151]
	v_mfma_f32_16x16x32_bf16 v[210:213], v[248:251], v[228:231], v[36:39]
	s_setprio 0
	s_barrier
	ds_read_b128 v[148:151], v168
	ds_read_b128 v[214:217], v168 offset:1024
	ds_read_b128 v[218:221], v168 offset:2048
	ds_read_b128 v[228:231], v168 offset:3072
	ds_read_b128 v[100:103], v166 offset:32768
	ds_read_b128 v[108:111], v166 offset:33792
	ds_read_b128 v[116:119], v165 offset:32768
	ds_read_b128 v[132:135], v165 offset:33792
	ds_read_b128 v[236:239], v163 offset:32768
	ds_read_b128 v[240:243], v163 offset:33792
	ds_read_b128 v[244:247], v162 offset:32768
	ds_read_b128 v[248:251], v162 offset:33792
	s_waitcnt vmcnt(2)
	s_barrier
	s_waitcnt lgkmcnt(0)
	s_setprio 1
	s_waitcnt lgkmcnt(0)
	v_mfma_f32_16x16x32_bf16 v[36:39], v[148:151], v[100:103], v[44:47]
	v_mfma_f32_16x16x32_bf16 v[44:47], v[148:151], v[116:119], v[60:63]
	v_mfma_f32_16x16x32_bf16 v[52:55], v[214:217], v[132:135], v[44:47]
	v_mfma_f32_16x16x32_bf16 v[44:47], v[218:221], v[116:119], v[56:59]
	v_mfma_f32_16x16x32_bf16 v[56:59], v[228:231], v[132:135], v[44:47]
	v_mfma_f32_16x16x32_bf16 v[44:47], v[148:151], v[236:239], v[76:79]
	v_mfma_f32_16x16x32_bf16 v[68:71], v[214:217], v[240:243], v[44:47]
	v_mfma_f32_16x16x32_bf16 v[44:47], v[218:221], v[236:239], v[72:75]
	v_mfma_f32_16x16x32_bf16 v[72:75], v[228:231], v[240:243], v[44:47]
	v_mfma_f32_16x16x32_bf16 v[44:47], v[148:151], v[244:247], v[92:95]
	v_mfma_f32_16x16x32_bf16 v[40:43], v[218:221], v[100:103], v[40:43]
	v_mfma_f32_16x16x32_bf16 v[84:87], v[214:217], v[248:251], v[44:47]
	v_mfma_f32_16x16x32_bf16 v[44:47], v[218:221], v[244:247], v[88:91]
	v_mfma_f32_16x16x32_bf16 v[36:39], v[214:217], v[108:111], v[36:39]
	v_mfma_f32_16x16x32_bf16 v[40:43], v[228:231], v[108:111], v[40:43]
	v_mfma_f32_16x16x32_bf16 v[88:91], v[228:231], v[248:251], v[44:47]
	s_setprio 0
	s_barrier
	s_nop 2
	ds_read_b128 v[44:47], v167
	ds_read_b128 v[60:63], v167 offset:1024
	ds_read_b128 v[76:79], v167 offset:2048
	ds_read_b128 v[232:235], v167 offset:3072
	s_waitcnt vmcnt(0)
	s_barrier
	s_waitcnt lgkmcnt(0)
	s_setprio 1
	s_waitcnt lgkmcnt(0)
	v_mfma_f32_16x16x32_bf16 v[92:95], v[76:79], v[100:103], v[188:191]
	v_mfma_f32_16x16x32_bf16 v[176:179], v[232:235], v[108:111], v[92:95]
	v_mfma_f32_16x16x32_bf16 v[92:95], v[76:79], v[116:119], v[192:195]
	v_mfma_f32_16x16x32_bf16 v[32:35], v[44:47], v[100:103], v[32:35]
	v_mfma_f32_16x16x32_bf16 v[48:51], v[44:47], v[116:119], v[48:51]
	v_mfma_f32_16x16x32_bf16 v[168:171], v[232:235], v[132:135], v[92:95]
	v_mfma_f32_16x16x32_bf16 v[64:67], v[44:47], v[236:239], v[64:67]
	v_mfma_f32_16x16x32_bf16 v[92:95], v[76:79], v[236:239], v[202:205]
	v_mfma_f32_16x16x32_bf16 v[80:83], v[44:47], v[244:247], v[80:83]
	v_mfma_f32_16x16x32_bf16 v[100:103], v[76:79], v[244:247], v[206:209]
	v_mfma_f32_16x16x32_bf16 v[32:35], v[60:63], v[108:111], v[32:35]
	v_mfma_f32_16x16x32_bf16 v[48:51], v[60:63], v[132:135], v[48:51]
	v_mfma_f32_16x16x32_bf16 v[64:67], v[60:63], v[240:243], v[64:67]
	v_mfma_f32_16x16x32_bf16 v[92:95], v[232:235], v[240:243], v[92:95]
	v_mfma_f32_16x16x32_bf16 v[80:83], v[60:63], v[248:251], v[80:83]
	v_mfma_f32_16x16x32_bf16 v[108:111], v[232:235], v[248:251], v[100:103]
	s_setprio 0
	s_barrier
	ds_read_b128 v[188:191], v166 offset:49152
	ds_read_b128 v[192:195], v166 offset:50176
	ds_read_b128 v[202:205], v165 offset:49152
	ds_read_b128 v[206:209], v165 offset:50176
	ds_read_b128 v[236:239], v163 offset:49152
	ds_read_b128 v[240:243], v163 offset:50176
	ds_read_b128 v[244:247], v162 offset:49152
	ds_read_b128 v[160:163], v162 offset:50176
	s_barrier
	s_waitcnt lgkmcnt(0)
	s_setprio 1
	s_waitcnt lgkmcnt(0)
	v_mfma_f32_16x16x32_bf16 v[116:119], v[148:151], v[202:205], v[124:127]
	v_mfma_f32_16x16x32_bf16 v[124:127], v[148:151], v[236:239], v[140:143]
	v_mfma_f32_16x16x32_bf16 v[132:135], v[214:217], v[240:243], v[124:127]
	v_mfma_f32_16x16x32_bf16 v[124:127], v[218:221], v[236:239], v[136:139]
	v_mfma_f32_16x16x32_bf16 v[136:139], v[228:231], v[240:243], v[124:127]
	v_mfma_f32_16x16x32_bf16 v[124:127], v[148:151], v[244:247], v[156:159]
	v_mfma_f32_16x16x32_bf16 v[100:103], v[148:151], v[188:191], v[222:225]
	v_mfma_f32_16x16x32_bf16 v[104:107], v[218:221], v[188:191], v[104:107]
	v_mfma_f32_16x16x32_bf16 v[120:123], v[218:221], v[202:205], v[120:123]
	v_mfma_f32_16x16x32_bf16 v[148:151], v[214:217], v[160:163], v[124:127]
	v_mfma_f32_16x16x32_bf16 v[124:127], v[218:221], v[244:247], v[152:155]
	v_mfma_f32_16x16x32_bf16 v[100:103], v[214:217], v[192:195], v[100:103]
	v_mfma_f32_16x16x32_bf16 v[104:107], v[228:231], v[192:195], v[104:107]
	v_mfma_f32_16x16x32_bf16 v[116:119], v[214:217], v[206:209], v[116:119]
	v_mfma_f32_16x16x32_bf16 v[120:123], v[228:231], v[206:209], v[120:123]
	v_mfma_f32_16x16x32_bf16 v[152:155], v[228:231], v[160:163], v[124:127]
	s_setprio 0
	s_setprio 1
	v_mfma_f32_16x16x32_bf16 v[96:99], v[44:47], v[188:191], v[96:99]
	v_mfma_f32_16x16x32_bf16 v[112:115], v[44:47], v[202:205], v[112:115]
	v_mfma_f32_16x16x32_bf16 v[128:131], v[44:47], v[236:239], v[128:131]
	v_mfma_f32_16x16x32_bf16 v[44:47], v[44:47], v[244:247], v[144:147]
	v_mfma_f32_16x16x32_bf16 v[124:127], v[76:79], v[188:191], v[172:175]
	v_mfma_f32_16x16x32_bf16 v[140:143], v[76:79], v[202:205], v[180:183]
	v_mfma_f32_16x16x32_bf16 v[156:159], v[76:79], v[236:239], v[184:187]
	v_mfma_f32_16x16x32_bf16 v[144:147], v[60:63], v[160:163], v[44:47]
	v_mfma_f32_16x16x32_bf16 v[44:47], v[76:79], v[244:247], v[210:213]
	v_mfma_f32_16x16x32_bf16 v[96:99], v[60:63], v[192:195], v[96:99]
	v_mfma_f32_16x16x32_bf16 v[124:127], v[232:235], v[192:195], v[124:127]
	v_mfma_f32_16x16x32_bf16 v[112:115], v[60:63], v[206:209], v[112:115]
	v_mfma_f32_16x16x32_bf16 v[140:143], v[232:235], v[206:209], v[140:143]
	v_mfma_f32_16x16x32_bf16 v[128:131], v[60:63], v[240:243], v[128:131]
	v_mfma_f32_16x16x32_bf16 v[156:159], v[232:235], v[240:243], v[156:159]
	v_mfma_f32_16x16x32_bf16 v[160:163], v[232:235], v[160:163], v[44:47]
	s_setprio 0
	s_movk_i32 s6, 0x100
	v_cmp_gt_u32_e32 vcc, s6, v164
	s_barrier
	s_and_saveexec_b64 s[6:7], vcc
	s_cbranch_execz .LBB0_317
	s_barrier

.LBB0_568:
	ds_read_b128 v[140:143], v129
	ds_read_b128 v[144:147], v129 offset:1024
	ds_read_b128 v[148:151], v129 offset:2048
	ds_read_b128 v[152:155], v129 offset:3072
	s_add_u32 s28, s8, s10
	s_addc_u32 s29, s9, s11
	ds_read_b128 v[156:159], v136
	ds_read_b128 v[160:163], v136 offset:1024
	ds_read_b128 v[164:167], v135
	ds_read_b128 v[168:171], v135 offset:1024
	ds_read_b128 v[172:175], v134
	ds_read_b128 v[176:179], v134 offset:1024
	ds_read_b128 v[180:183], v133
	ds_read_b128 v[184:187], v133 offset:1024
	s_add_i32 s39, s68, 0xc000
	s_mov_b32 m0, s39
	s_add_i32 s38, s68, 0xe000
	s_add_u32 s98, s28, s44
	s_addc_u32 s99, s29, s45
	global_load_lds_dwordx4 v128, s[98:99]
	s_mov_b32 m0, s38
	s_nop 0
	global_load_lds_dwordx4 v130, s[98:99]
	s_waitcnt lgkmcnt(8)
	s_barrier
	s_waitcnt lgkmcnt(0)
	s_setprio 0
	s_waitcnt lgkmcnt(0)
	v_mfma_f32_16x16x32_bf16 v[124:127], v[140:143], v[156:159], v[124:127]
	v_mfma_f32_16x16x32_bf16 v[120:123], v[148:151], v[156:159], v[120:123]
	v_mfma_f32_16x16x32_bf16 v[116:119], v[140:143], v[164:167], v[116:119]
	v_mfma_f32_16x16x32_bf16 v[112:115], v[148:151], v[164:167], v[112:115]
	v_mfma_f32_16x16x32_bf16 v[108:111], v[140:143], v[172:175], v[108:111]
	v_mfma_f32_16x16x32_bf16 v[104:107], v[148:151], v[172:175], v[104:107]
	v_mfma_f32_16x16x32_bf16 v[100:103], v[140:143], v[180:183], v[100:103]
	v_mfma_f32_16x16x32_bf16 v[96:99], v[148:151], v[180:183], v[96:99]
	v_mfma_f32_16x16x32_bf16 v[124:127], v[144:147], v[160:163], v[124:127]
	v_mfma_f32_16x16x32_bf16 v[120:123], v[152:155], v[160:163], v[120:123]
	v_mfma_f32_16x16x32_bf16 v[116:119], v[144:147], v[168:171], v[116:119]
	v_mfma_f32_16x16x32_bf16 v[112:115], v[152:155], v[168:171], v[112:115]
	v_mfma_f32_16x16x32_bf16 v[108:111], v[144:147], v[176:179], v[108:111]
	v_mfma_f32_16x16x32_bf16 v[104:107], v[152:155], v[176:179], v[104:107]
	v_mfma_f32_16x16x32_bf16 v[100:103], v[144:147], v[184:187], v[100:103]
	v_mfma_f32_16x16x32_bf16 v[96:99], v[152:155], v[184:187], v[96:99]
	s_setprio 1
	s_barrier
	s_add_u32 s56, s6, s10
	s_addc_u32 s57, s7, s11
	ds_read_b128 v[188:191], v139
	ds_read_b128 v[192:195], v139 offset:1024
	ds_read_b128 v[202:205], v139 offset:2048
	ds_read_b128 v[206:209], v139 offset:3072
	s_add_i32 m0, s68, 0x10000
	s_add_u32 s98, s56, s0
	s_addc_u32 s99, s57, s1
	global_load_lds_dwordx4 v128, s[98:99]
	s_add_i32 m0, s68, 0x12000
	s_nop 0
	global_load_lds_dwordx4 v130, s[98:99]
	s_barrier
	s_waitcnt lgkmcnt(0)
	s_setprio 0
	s_waitcnt lgkmcnt(0)
	v_mfma_f32_16x16x32_bf16 v[92:95], v[188:191], v[156:159], v[92:95]
	v_mfma_f32_16x16x32_bf16 v[88:91], v[202:205], v[156:159], v[88:91]
	v_mfma_f32_16x16x32_bf16 v[84:87], v[188:191], v[164:167], v[84:87]
	v_mfma_f32_16x16x32_bf16 v[80:83], v[202:205], v[164:167], v[80:83]
	v_mfma_f32_16x16x32_bf16 v[76:79], v[188:191], v[172:175], v[76:79]
	v_mfma_f32_16x16x32_bf16 v[72:75], v[202:205], v[172:175], v[72:75]
	v_mfma_f32_16x16x32_bf16 v[68:71], v[188:191], v[180:183], v[68:71]
	v_mfma_f32_16x16x32_bf16 v[64:67], v[202:205], v[180:183], v[64:67]
	v_mfma_f32_16x16x32_bf16 v[92:95], v[192:195], v[160:163], v[92:95]
	v_mfma_f32_16x16x32_bf16 v[88:91], v[206:209], v[160:163], v[88:91]
	v_mfma_f32_16x16x32_bf16 v[84:87], v[192:195], v[168:171], v[84:87]
	v_mfma_f32_16x16x32_bf16 v[80:83], v[206:209], v[168:171], v[80:83]
	v_mfma_f32_16x16x32_bf16 v[76:79], v[192:195], v[176:179], v[76:79]
	v_mfma_f32_16x16x32_bf16 v[72:75], v[206:209], v[176:179], v[72:75]
	v_mfma_f32_16x16x32_bf16 v[68:71], v[192:195], v[184:187], v[68:71]
	v_mfma_f32_16x16x32_bf16 v[64:67], v[206:209], v[184:187], v[64:67]
	s_setprio 1
	s_barrier
	ds_read_b128 v[156:159], v136 offset:16384
	ds_read_b128 v[160:163], v136 offset:17408
	ds_read_b128 v[164:167], v135 offset:16384
	ds_read_b128 v[168:171], v135 offset:17408
	ds_read_b128 v[172:175], v134 offset:16384
	ds_read_b128 v[176:179], v134 offset:17408
	ds_read_b128 v[180:183], v133 offset:16384
	ds_read_b128 v[184:187], v133 offset:17408
	s_mov_b32 m0, s68
	s_add_u32 s98, s28, s0
	s_addc_u32 s99, s29, s1
	global_load_lds_dwordx4 v128, s[98:99]
	s_add_i32 m0, s68, 0x2000
	s_nop 0
	global_load_lds_dwordx4 v130, s[98:99]
	s_barrier
	s_waitcnt lgkmcnt(0)
	s_setprio 0
	s_waitcnt lgkmcnt(0)
	v_mfma_f32_16x16x32_bf16 v[60:63], v[140:143], v[156:159], v[60:63]
	v_mfma_f32_16x16x32_bf16 v[56:59], v[148:151], v[156:159], v[56:59]
	v_mfma_f32_16x16x32_bf16 v[52:55], v[140:143], v[164:167], v[52:55]
	v_mfma_f32_16x16x32_bf16 v[48:51], v[148:151], v[164:167], v[48:51]
	v_mfma_f32_16x16x32_bf16 v[44:47], v[140:143], v[172:175], v[44:47]
	v_mfma_f32_16x16x32_bf16 v[40:43], v[148:151], v[172:175], v[40:43]
	v_mfma_f32_16x16x32_bf16 v[36:39], v[140:143], v[180:183], v[36:39]
	v_mfma_f32_16x16x32_bf16 v[32:35], v[148:151], v[180:183], v[32:35]
	v_mfma_f32_16x16x32_bf16 v[60:63], v[144:147], v[160:163], v[60:63]
	v_mfma_f32_16x16x32_bf16 v[56:59], v[152:155], v[160:163], v[56:59]
	v_mfma_f32_16x16x32_bf16 v[52:55], v[144:147], v[168:171], v[52:55]
	v_mfma_f32_16x16x32_bf16 v[48:51], v[152:155], v[168:171], v[48:51]
	v_mfma_f32_16x16x32_bf16 v[44:47], v[144:147], v[176:179], v[44:47]
	v_mfma_f32_16x16x32_bf16 v[40:43], v[152:155], v[176:179], v[40:43]
	v_mfma_f32_16x16x32_bf16 v[36:39], v[144:147], v[184:187], v[36:39]
	v_mfma_f32_16x16x32_bf16 v[32:35], v[152:155], v[184:187], v[32:35]
	s_setprio 1
	s_barrier
	s_add_i32 m0, s68, 0x14000
	s_add_u32 s98, s56, s46
	s_addc_u32 s99, s57, s47
	global_load_lds_dwordx4 v128, s[98:99]
	s_add_i32 m0, s68, 0x16000
	s_nop 0
	global_load_lds_dwordx4 v130, s[98:99]
	s_waitcnt vmcnt(6)
	s_barrier
	s_setprio 0
	v_mfma_f32_16x16x32_bf16 v[28:31], v[188:191], v[156:159], v[28:31]
	v_mfma_f32_16x16x32_bf16 v[24:27], v[202:205], v[156:159], v[24:27]
	v_mfma_f32_16x16x32_bf16 v[20:23], v[188:191], v[164:167], v[20:23]
	v_mfma_f32_16x16x32_bf16 v[16:19], v[202:205], v[164:167], v[16:19]
	v_mfma_f32_16x16x32_bf16 v[12:15], v[188:191], v[172:175], v[12:15]
	v_mfma_f32_16x16x32_bf16 v[8:11], v[202:205], v[172:175], v[8:11]
	v_mfma_f32_16x16x32_bf16 v[4:7], v[188:191], v[180:183], v[4:7]
	v_mfma_f32_16x16x32_bf16 v[0:3], v[202:205], v[180:183], v[0:3]
	v_mfma_f32_16x16x32_bf16 v[28:31], v[192:195], v[160:163], v[28:31]
	v_mfma_f32_16x16x32_bf16 v[24:27], v[206:209], v[160:163], v[24:27]
	v_mfma_f32_16x16x32_bf16 v[20:23], v[192:195], v[168:171], v[20:23]
	v_mfma_f32_16x16x32_bf16 v[16:19], v[206:209], v[168:171], v[16:19]
	v_mfma_f32_16x16x32_bf16 v[12:15], v[192:195], v[176:179], v[12:15]
	v_mfma_f32_16x16x32_bf16 v[8:11], v[206:209], v[176:179], v[8:11]
	v_mfma_f32_16x16x32_bf16 v[4:7], v[192:195], v[184:187], v[4:7]
	v_mfma_f32_16x16x32_bf16 v[0:3], v[206:209], v[184:187], v[0:3]
	s_setprio 1
	s_barrier
	ds_read_b128 v[140:143], v138
	ds_read_b128 v[144:147], v138 offset:1024
	ds_read_b128 v[148:151], v138 offset:2048
	ds_read_b128 v[152:155], v138 offset:3072
	ds_read_b128 v[156:159], v136 offset:32768
	ds_read_b128 v[160:163], v136 offset:33792
	ds_read_b128 v[164:167], v135 offset:32768
	ds_read_b128 v[168:171], v135 offset:33792
	ds_read_b128 v[172:175], v134 offset:32768
	ds_read_b128 v[176:179], v134 offset:33792
	ds_read_b128 v[180:183], v133 offset:32768
	ds_read_b128 v[184:187], v133 offset:33792
	s_add_i32 m0, s68, 0x4000
	s_add_u32 s98, s28, s46
	s_addc_u32 s99, s29, s47
	global_load_lds_dwordx4 v128, s[98:99]
	s_add_i32 m0, s68, 0x6000
	s_nop 0
	global_load_lds_dwordx4 v130, s[98:99]
	s_waitcnt lgkmcnt(8)
	s_barrier
	s_waitcnt lgkmcnt(0)
	s_setprio 0
	s_waitcnt lgkmcnt(0)
	v_mfma_f32_16x16x32_bf16 v[124:127], v[140:143], v[156:159], v[124:127]
	v_mfma_f32_16x16x32_bf16 v[120:123], v[148:151], v[156:159], v[120:123]
	v_mfma_f32_16x16x32_bf16 v[116:119], v[140:143], v[164:167], v[116:119]
	v_mfma_f32_16x16x32_bf16 v[112:115], v[148:151], v[164:167], v[112:115]
	v_mfma_f32_16x16x32_bf16 v[108:111], v[140:143], v[172:175], v[108:111]
	v_mfma_f32_16x16x32_bf16 v[104:107], v[148:151], v[172:175], v[104:107]
	v_mfma_f32_16x16x32_bf16 v[100:103], v[140:143], v[180:183], v[100:103]
	v_mfma_f32_16x16x32_bf16 v[96:99], v[148:151], v[180:183], v[96:99]
	v_mfma_f32_16x16x32_bf16 v[124:127], v[144:147], v[160:163], v[124:127]
	v_mfma_f32_16x16x32_bf16 v[120:123], v[152:155], v[160:163], v[120:123]
	v_mfma_f32_16x16x32_bf16 v[116:119], v[144:147], v[168:171], v[116:119]
	v_mfma_f32_16x16x32_bf16 v[112:115], v[152:155], v[168:171], v[112:115]
	v_mfma_f32_16x16x32_bf16 v[108:111], v[144:147], v[176:179], v[108:111]
	v_mfma_f32_16x16x32_bf16 v[104:107], v[152:155], v[176:179], v[104:107]
	v_mfma_f32_16x16x32_bf16 v[100:103], v[144:147], v[184:187], v[100:103]
	v_mfma_f32_16x16x32_bf16 v[96:99], v[152:155], v[184:187], v[96:99]
	s_setprio 1
	s_barrier
	ds_read_b128 v[188:191], v137
	ds_read_b128 v[192:195], v137 offset:1024
	ds_read_b128 v[202:205], v137 offset:2048
	ds_read_b128 v[206:209], v137 offset:3072
	s_mov_b32 m0, s69
	s_add_u32 s98, s56, s30
	s_addc_u32 s99, s57, s31
	global_load_lds_dwordx4 v128, s[98:99]
	s_mov_b32 m0, s70
	s_nop 0
	global_load_lds_dwordx4 v130, s[98:99]
	s_barrier
	s_waitcnt lgkmcnt(0)
	s_setprio 0
	s_waitcnt lgkmcnt(0)
	v_mfma_f32_16x16x32_bf16 v[92:95], v[188:191], v[156:159], v[92:95]
	v_mfma_f32_16x16x32_bf16 v[88:91], v[202:205], v[156:159], v[88:91]
	v_mfma_f32_16x16x32_bf16 v[84:87], v[188:191], v[164:167], v[84:87]
	v_mfma_f32_16x16x32_bf16 v[80:83], v[202:205], v[164:167], v[80:83]
	v_mfma_f32_16x16x32_bf16 v[76:79], v[188:191], v[172:175], v[76:79]
	v_mfma_f32_16x16x32_bf16 v[72:75], v[202:205], v[172:175], v[72:75]
	v_mfma_f32_16x16x32_bf16 v[68:71], v[188:191], v[180:183], v[68:71]
	v_mfma_f32_16x16x32_bf16 v[64:67], v[202:205], v[180:183], v[64:67]
	v_mfma_f32_16x16x32_bf16 v[92:95], v[192:195], v[160:163], v[92:95]
	v_mfma_f32_16x16x32_bf16 v[88:91], v[206:209], v[160:163], v[88:91]
	v_mfma_f32_16x16x32_bf16 v[84:87], v[192:195], v[168:171], v[84:87]
	v_mfma_f32_16x16x32_bf16 v[80:83], v[206:209], v[168:171], v[80:83]
	v_mfma_f32_16x16x32_bf16 v[76:79], v[192:195], v[176:179], v[76:79]
	v_mfma_f32_16x16x32_bf16 v[72:75], v[206:209], v[176:179], v[72:75]
	v_mfma_f32_16x16x32_bf16 v[68:71], v[192:195], v[184:187], v[68:71]
	v_mfma_f32_16x16x32_bf16 v[64:67], v[206:209], v[184:187], v[64:67]
	s_setprio 1
	v_mov_b32_e32 v210, v130
	s_barrier
	ds_read_b128 v[156:159], v136 offset:49152
	ds_read_b128 v[160:163], v136 offset:50176
	ds_read_b128 v[164:167], v135 offset:49152
	ds_read_b128 v[168:171], v135 offset:50176
	ds_read_b128 v[172:175], v134 offset:49152
	ds_read_b128 v[176:179], v134 offset:50176
	ds_read_b128 v[180:183], v133 offset:49152
	ds_read_b128 v[184:187], v133 offset:50176
	v_mov_b32_e32 v211, v197
	s_mov_b32 m0, s71
	s_add_u32 s98, s28, s30
	s_addc_u32 s99, s29, s31
	global_load_lds_dwordx4 v128, s[98:99]
	s_mov_b32 m0, s33
	s_nop 0
	global_load_lds_dwordx4 v130, s[98:99]
	s_barrier
	s_waitcnt lgkmcnt(0)
	s_setprio 0
	s_waitcnt lgkmcnt(0)
	v_mfma_f32_16x16x32_bf16 v[60:63], v[140:143], v[156:159], v[60:63]
	v_mfma_f32_16x16x32_bf16 v[56:59], v[148:151], v[156:159], v[56:59]
	v_mfma_f32_16x16x32_bf16 v[52:55], v[140:143], v[164:167], v[52:55]
	v_mfma_f32_16x16x32_bf16 v[48:51], v[148:151], v[164:167], v[48:51]
	v_mfma_f32_16x16x32_bf16 v[44:47], v[140:143], v[172:175], v[44:47]
	v_mfma_f32_16x16x32_bf16 v[40:43], v[148:151], v[172:175], v[40:43]
	v_mfma_f32_16x16x32_bf16 v[36:39], v[140:143], v[180:183], v[36:39]
	v_mfma_f32_16x16x32_bf16 v[32:35], v[148:151], v[180:183], v[32:35]
	v_mfma_f32_16x16x32_bf16 v[60:63], v[144:147], v[160:163], v[60:63]
	v_mfma_f32_16x16x32_bf16 v[56:59], v[152:155], v[160:163], v[56:59]
	v_mfma_f32_16x16x32_bf16 v[52:55], v[144:147], v[168:171], v[52:55]
	v_mfma_f32_16x16x32_bf16 v[48:51], v[152:155], v[168:171], v[48:51]
	v_mfma_f32_16x16x32_bf16 v[44:47], v[144:147], v[176:179], v[44:47]
	v_mfma_f32_16x16x32_bf16 v[40:43], v[152:155], v[176:179], v[40:43]
	v_mfma_f32_16x16x32_bf16 v[36:39], v[144:147], v[184:187], v[36:39]
	v_mfma_f32_16x16x32_bf16 v[32:35], v[152:155], v[184:187], v[32:35]
	s_setprio 1
	s_barrier
	v_mov_b32_e32 v196, v128
	s_mov_b32 m0, s72
	s_add_u32 s98, s56, s48
	s_addc_u32 s99, s57, s49
	global_load_lds_dwordx4 v128, s[98:99]
	s_mov_b32 m0, s36
	s_nop 0
	global_load_lds_dwordx4 v130, s[98:99]
	s_waitcnt vmcnt(6)
	s_barrier
	s_setprio 0
	v_mfma_f32_16x16x32_bf16 v[28:31], v[188:191], v[156:159], v[28:31]
	v_mfma_f32_16x16x32_bf16 v[24:27], v[202:205], v[156:159], v[24:27]
	v_mfma_f32_16x16x32_bf16 v[20:23], v[188:191], v[164:167], v[20:23]
	v_mfma_f32_16x16x32_bf16 v[16:19], v[202:205], v[164:167], v[16:19]
	v_mfma_f32_16x16x32_bf16 v[12:15], v[188:191], v[172:175], v[12:15]
	v_mfma_f32_16x16x32_bf16 v[8:11], v[202:205], v[172:175], v[8:11]
	v_mfma_f32_16x16x32_bf16 v[4:7], v[188:191], v[180:183], v[4:7]
	v_mfma_f32_16x16x32_bf16 v[0:3], v[202:205], v[180:183], v[0:3]
	v_mfma_f32_16x16x32_bf16 v[28:31], v[192:195], v[160:163], v[28:31]
	v_mfma_f32_16x16x32_bf16 v[24:27], v[206:209], v[160:163], v[24:27]
	v_mfma_f32_16x16x32_bf16 v[20:23], v[192:195], v[168:171], v[20:23]
	v_mfma_f32_16x16x32_bf16 v[16:19], v[206:209], v[168:171], v[16:19]
	v_mfma_f32_16x16x32_bf16 v[12:15], v[192:195], v[176:179], v[12:15]
	v_mfma_f32_16x16x32_bf16 v[8:11], v[206:209], v[176:179], v[8:11]
	v_mfma_f32_16x16x32_bf16 v[4:7], v[192:195], v[184:187], v[4:7]
	v_mfma_f32_16x16x32_bf16 v[0:3], v[206:209], v[184:187], v[0:3]
	s_setprio 1
	s_add_i32 s37, s37, 2
	s_add_u32 s10, s10, 0x100
	s_addc_u32 s11, s11, 0
	s_cmp_lt_u32 s37, 28
	s_barrier
	s_cbranch_scc1 .LBB0_568
	s_setprio 0
	s_lshl_b64 s[4:5], s[4:5], 12
	s_add_u32 s4, s67, s4
	s_addc_u32 s5, s53, s5
	ds_read_b128 v[140:143], v129
	ds_read_b128 v[144:147], v129 offset:1024
	ds_read_b128 v[148:151], v129 offset:2048
	ds_read_b128 v[152:155], v129 offset:3072
	ds_read_b128 v[156:159], v136
	ds_read_b128 v[160:163], v136 offset:1024
	ds_read_b128 v[164:167], v135
	ds_read_b128 v[168:171], v135 offset:1024
	ds_read_b128 v[172:175], v134
	ds_read_b128 v[176:179], v134 offset:1024
	ds_read_b128 v[180:183], v133
	ds_read_b128 v[184:187], v133 offset:1024
	v_mov_b32_e32 v129, v197
	v_lshl_add_u64 v[128:129], s[4:5], 0, v[128:129]
	s_mov_b64 s[6:7], 0xf80
	s_mov_b32 m0, s39
	v_lshl_add_u64 v[128:129], v[128:129], 0, s[6:7]
	v_mov_b32_e32 v131, v197
	global_load_lds_dwordx4 v[128:129], off
	v_lshl_add_u64 v[128:129], s[4:5], 0, v[130:131]
	v_lshl_add_u64 v[128:129], v[128:129], 0, s[6:7]
	s_mov_b32 m0, s38
	s_nop 0
	global_load_lds_dwordx4 v[128:129], off
	s_barrier
	s_waitcnt lgkmcnt(0)
	s_setprio 1
	s_waitcnt lgkmcnt(0)
	v_mfma_f32_16x16x32_bf16 v[124:127], v[140:143], v[156:159], v[124:127]
	v_mfma_f32_16x16x32_bf16 v[120:123], v[148:151], v[156:159], v[120:123]
	v_mfma_f32_16x16x32_bf16 v[116:119], v[140:143], v[164:167], v[116:119]
	v_mfma_f32_16x16x32_bf16 v[112:115], v[148:151], v[164:167], v[112:115]
	v_mfma_f32_16x16x32_bf16 v[100:103], v[140:143], v[180:183], v[100:103]
	v_mfma_f32_16x16x32_bf16 v[96:99], v[148:151], v[180:183], v[96:99]
	v_mfma_f32_16x16x32_bf16 v[124:127], v[144:147], v[160:163], v[124:127]
	v_mfma_f32_16x16x32_bf16 v[120:123], v[152:155], v[160:163], v[120:123]
	v_mfma_f32_16x16x32_bf16 v[116:119], v[144:147], v[168:171], v[116:119]
	v_mfma_f32_16x16x32_bf16 v[112:115], v[152:155], v[168:171], v[112:115]
	v_mfma_f32_16x16x32_bf16 v[108:111], v[140:143], v[172:175], v[108:111]
	v_mfma_f32_16x16x32_bf16 v[104:107], v[148:151], v[172:175], v[104:107]
	v_mfma_f32_16x16x32_bf16 v[100:103], v[144:147], v[184:187], v[100:103]
	v_mfma_f32_16x16x32_bf16 v[96:99], v[152:155], v[184:187], v[96:99]
	v_mfma_f32_16x16x32_bf16 v[128:131], v[144:147], v[176:179], v[108:111]
	v_mfma_f32_16x16x32_bf16 v[188:191], v[152:155], v[176:179], v[104:107]
	s_setprio 0
	s_barrier
	s_nop 1
	ds_read_b128 v[104:107], v139
	ds_read_b128 v[108:111], v139 offset:1024
	ds_read_b128 v[192:195], v139 offset:2048
	ds_read_b128 v[202:205], v139 offset:3072
	s_barrier
	s_waitcnt lgkmcnt(0)
	s_setprio 1
	s_waitcnt lgkmcnt(0)
	v_mfma_f32_16x16x32_bf16 v[84:87], v[104:107], v[164:167], v[84:87]
	v_mfma_f32_16x16x32_bf16 v[80:83], v[192:195], v[164:167], v[80:83]
	v_mfma_f32_16x16x32_bf16 v[68:71], v[104:107], v[180:183], v[68:71]
	v_mfma_f32_16x16x32_bf16 v[64:67], v[192:195], v[180:183], v[64:67]
	v_mfma_f32_16x16x32_bf16 v[92:95], v[104:107], v[156:159], v[92:95]
	v_mfma_f32_16x16x32_bf16 v[88:91], v[192:195], v[156:159], v[88:91]
	v_mfma_f32_16x16x32_bf16 v[84:87], v[108:111], v[168:171], v[84:87]
	v_mfma_f32_16x16x32_bf16 v[80:83], v[202:205], v[168:171], v[80:83]
	v_mfma_f32_16x16x32_bf16 v[76:79], v[104:107], v[172:175], v[76:79]
	v_mfma_f32_16x16x32_bf16 v[72:75], v[192:195], v[172:175], v[72:75]
	v_mfma_f32_16x16x32_bf16 v[68:71], v[108:111], v[184:187], v[68:71]
	v_mfma_f32_16x16x32_bf16 v[64:67], v[202:205], v[184:187], v[64:67]
	v_mfma_f32_16x16x32_bf16 v[206:209], v[108:111], v[160:163], v[92:95]
	v_mfma_f32_16x16x32_bf16 v[156:159], v[202:205], v[160:163], v[88:91]
	v_mfma_f32_16x16x32_bf16 v[160:163], v[108:111], v[176:179], v[76:79]
	v_mfma_f32_16x16x32_bf16 v[164:167], v[202:205], v[176:179], v[72:75]
	s_setprio 0
	s_barrier
	s_nop 0
	ds_read_b128 v[72:75], v136 offset:16384
	ds_read_b128 v[76:79], v136 offset:17408
	ds_read_b128 v[88:91], v135 offset:16384
	ds_read_b128 v[92:95], v135 offset:17408
	ds_read_b128 v[168:171], v134 offset:16384
	ds_read_b128 v[172:175], v134 offset:17408
	ds_read_b128 v[176:179], v133 offset:16384
	ds_read_b128 v[180:183], v133 offset:17408
	s_waitcnt vmcnt(4)
	s_barrier
	s_waitcnt lgkmcnt(0)
	s_setprio 1
	s_waitcnt lgkmcnt(0)
	v_mfma_f32_16x16x32_bf16 v[60:63], v[140:143], v[72:75], v[60:63]
	v_mfma_f32_16x16x32_bf16 v[56:59], v[148:151], v[72:75], v[56:59]
	v_mfma_f32_16x16x32_bf16 v[52:55], v[140:143], v[88:91], v[52:55]
	v_mfma_f32_16x16x32_bf16 v[48:51], v[148:151], v[88:91], v[48:51]
	v_mfma_f32_16x16x32_bf16 v[36:39], v[140:143], v[176:179], v[36:39]
	v_mfma_f32_16x16x32_bf16 v[32:35], v[148:151], v[176:179], v[32:35]
	v_mfma_f32_16x16x32_bf16 v[60:63], v[144:147], v[76:79], v[60:63]
	v_mfma_f32_16x16x32_bf16 v[56:59], v[152:155], v[76:79], v[56:59]
	v_mfma_f32_16x16x32_bf16 v[52:55], v[144:147], v[92:95], v[52:55]
	v_mfma_f32_16x16x32_bf16 v[48:51], v[152:155], v[92:95], v[48:51]
	v_mfma_f32_16x16x32_bf16 v[44:47], v[140:143], v[168:171], v[44:47]
	v_mfma_f32_16x16x32_bf16 v[40:43], v[148:151], v[168:171], v[40:43]
	v_mfma_f32_16x16x32_bf16 v[36:39], v[144:147], v[180:183], v[36:39]
	v_mfma_f32_16x16x32_bf16 v[32:35], v[152:155], v[180:183], v[32:35]
	v_mfma_f32_16x16x32_bf16 v[184:187], v[144:147], v[172:175], v[44:47]
	v_mfma_f32_16x16x32_bf16 v[210:213], v[152:155], v[172:175], v[40:43]
	s_setprio 0
	s_setprio 1
	v_mfma_f32_16x16x32_bf16 v[20:23], v[104:107], v[88:91], v[20:23]
	v_mfma_f32_16x16x32_bf16 v[16:19], v[192:195], v[88:91], v[16:19]
	v_mfma_f32_16x16x32_bf16 v[4:7], v[104:107], v[176:179], v[4:7]
	v_mfma_f32_16x16x32_bf16 v[0:3], v[192:195], v[176:179], v[0:3]
	v_mfma_f32_16x16x32_bf16 v[28:31], v[104:107], v[72:75], v[28:31]
	v_mfma_f32_16x16x32_bf16 v[24:27], v[192:195], v[72:75], v[24:27]
	v_mfma_f32_16x16x32_bf16 v[20:23], v[108:111], v[92:95], v[20:23]
	v_mfma_f32_16x16x32_bf16 v[16:19], v[202:205], v[92:95], v[16:19]
	v_mfma_f32_16x16x32_bf16 v[12:15], v[104:107], v[168:171], v[12:15]
	v_mfma_f32_16x16x32_bf16 v[8:11], v[192:195], v[168:171], v[8:11]
	v_mfma_f32_16x16x32_bf16 v[4:7], v[108:111], v[180:183], v[4:7]
	v_mfma_f32_16x16x32_bf16 v[0:3], v[202:205], v[180:183], v[0:3]
	v_mfma_f32_16x16x32_bf16 v[140:143], v[108:111], v[76:79], v[28:31]
	v_mfma_f32_16x16x32_bf16 v[144:147], v[202:205], v[76:79], v[24:27]
	v_mfma_f32_16x16x32_bf16 v[148:151], v[108:111], v[172:175], v[12:15]
	v_mfma_f32_16x16x32_bf16 v[152:155], v[202:205], v[172:175], v[8:11]
	s_setprio 0
	s_barrier
	s_nop 0
	ds_read_b128 v[8:11], v138
	ds_read_b128 v[12:15], v138 offset:1024
	ds_read_b128 v[168:171], v138 offset:2048
	ds_read_b128 v[172:175], v138 offset:3072
	ds_read_b128 v[24:27], v136 offset:32768
	ds_read_b128 v[28:31], v136 offset:33792
	ds_read_b128 v[40:43], v135 offset:32768
	ds_read_b128 v[44:47], v135 offset:33792
	ds_read_b128 v[176:179], v134 offset:32768
	ds_read_b128 v[180:183], v134 offset:33792
	ds_read_b128 v[192:195], v133 offset:32768
	ds_read_b128 v[202:205], v133 offset:33792
	s_waitcnt vmcnt(2)
	s_barrier
	s_waitcnt lgkmcnt(0)
	s_setprio 1
	s_waitcnt lgkmcnt(0)
	v_mfma_f32_16x16x32_bf16 v[72:75], v[8:11], v[24:27], v[124:127]
	v_mfma_f32_16x16x32_bf16 v[124:127], v[12:15], v[28:31], v[72:75]
	v_mfma_f32_16x16x32_bf16 v[72:75], v[168:171], v[24:27], v[120:123]
	v_mfma_f32_16x16x32_bf16 v[120:123], v[172:175], v[28:31], v[72:75]
	v_mfma_f32_16x16x32_bf16 v[72:75], v[8:11], v[40:43], v[116:119]
	v_mfma_f32_16x16x32_bf16 v[108:111], v[12:15], v[44:47], v[72:75]
	v_mfma_f32_16x16x32_bf16 v[72:75], v[168:171], v[40:43], v[112:115]
	v_mfma_f32_16x16x32_bf16 v[104:107], v[172:175], v[44:47], v[72:75]
	v_mfma_f32_16x16x32_bf16 v[72:75], v[8:11], v[176:179], v[128:131]
	v_mfma_f32_16x16x32_bf16 v[92:95], v[12:15], v[180:183], v[72:75]
	v_mfma_f32_16x16x32_bf16 v[72:75], v[168:171], v[176:179], v[188:191]
	v_mfma_f32_16x16x32_bf16 v[88:91], v[172:175], v[180:183], v[72:75]
	v_mfma_f32_16x16x32_bf16 v[72:75], v[8:11], v[192:195], v[100:103]
	v_mfma_f32_16x16x32_bf16 v[76:79], v[12:15], v[202:205], v[72:75]
	v_mfma_f32_16x16x32_bf16 v[72:75], v[168:171], v[192:195], v[96:99]
	v_mfma_f32_16x16x32_bf16 v[72:75], v[172:175], v[202:205], v[72:75]
	s_setprio 0
	s_barrier
	ds_read_b128 v[128:131], v137
	ds_read_b128 v[188:191], v137 offset:1024
	ds_read_b128 v[214:217], v137 offset:2048
	ds_read_b128 v[218:221], v137 offset:3072
	s_waitcnt vmcnt(0)
	s_barrier
	s_waitcnt lgkmcnt(0)
	s_setprio 1
	s_waitcnt lgkmcnt(0)
	v_mfma_f32_16x16x32_bf16 v[96:99], v[128:131], v[24:27], v[206:209]
	v_mfma_f32_16x16x32_bf16 v[24:27], v[214:217], v[24:27], v[156:159]
	v_mfma_f32_16x16x32_bf16 v[112:115], v[218:221], v[28:31], v[24:27]
	v_mfma_f32_16x16x32_bf16 v[24:27], v[128:131], v[40:43], v[84:87]
	v_mfma_f32_16x16x32_bf16 v[100:103], v[188:191], v[44:47], v[24:27]
	v_mfma_f32_16x16x32_bf16 v[24:27], v[214:217], v[40:43], v[80:83]
	v_mfma_f32_16x16x32_bf16 v[116:119], v[188:191], v[28:31], v[96:99]
	v_mfma_f32_16x16x32_bf16 v[96:99], v[218:221], v[44:47], v[24:27]
	v_mfma_f32_16x16x32_bf16 v[24:27], v[128:131], v[176:179], v[160:163]
	v_mfma_f32_16x16x32_bf16 v[84:87], v[188:191], v[180:183], v[24:27]
	v_mfma_f32_16x16x32_bf16 v[24:27], v[214:217], v[176:179], v[164:167]
	v_mfma_f32_16x16x32_bf16 v[80:83], v[218:221], v[180:183], v[24:27]
	v_mfma_f32_16x16x32_bf16 v[24:27], v[128:131], v[192:195], v[68:71]
	v_mfma_f32_16x16x32_bf16 v[68:71], v[188:191], v[202:205], v[24:27]
	v_mfma_f32_16x16x32_bf16 v[24:27], v[214:217], v[192:195], v[64:67]
	v_mfma_f32_16x16x32_bf16 v[64:67], v[218:221], v[202:205], v[24:27]
	s_setprio 0
	s_barrier
	ds_read_b128 v[156:159], v136 offset:49152
	ds_read_b128 v[136:139], v136 offset:50176
	ds_read_b128 v[160:163], v135 offset:49152
	ds_read_b128 v[164:167], v135 offset:50176
	ds_read_b128 v[176:179], v134 offset:49152
	ds_read_b128 v[180:183], v134 offset:50176
	ds_read_b128 v[192:195], v133 offset:49152
	ds_read_b128 v[202:205], v133 offset:50176
	s_barrier
	s_waitcnt lgkmcnt(0)
	s_setprio 1
	s_waitcnt lgkmcnt(0)
	v_mfma_f32_16x16x32_bf16 v[24:27], v[8:11], v[156:159], v[60:63]
	v_mfma_f32_16x16x32_bf16 v[60:63], v[12:15], v[136:139], v[24:27]
	v_mfma_f32_16x16x32_bf16 v[24:27], v[168:171], v[156:159], v[56:59]
	v_mfma_f32_16x16x32_bf16 v[56:59], v[172:175], v[136:139], v[24:27]
	v_mfma_f32_16x16x32_bf16 v[24:27], v[8:11], v[160:163], v[52:55]
	v_mfma_f32_16x16x32_bf16 v[44:47], v[12:15], v[164:167], v[24:27]
	v_mfma_f32_16x16x32_bf16 v[24:27], v[168:171], v[160:163], v[48:51]
	v_mfma_f32_16x16x32_bf16 v[40:43], v[172:175], v[164:167], v[24:27]
	v_mfma_f32_16x16x32_bf16 v[24:27], v[8:11], v[176:179], v[184:187]
	v_mfma_f32_16x16x32_bf16 v[8:11], v[8:11], v[192:195], v[36:39]
	v_mfma_f32_16x16x32_bf16 v[28:31], v[12:15], v[180:183], v[24:27]
	v_mfma_f32_16x16x32_bf16 v[24:27], v[168:171], v[176:179], v[210:213]
	v_mfma_f32_16x16x32_bf16 v[12:15], v[12:15], v[202:205], v[8:11]
	v_mfma_f32_16x16x32_bf16 v[8:11], v[168:171], v[192:195], v[32:35]
	v_mfma_f32_16x16x32_bf16 v[24:27], v[172:175], v[180:183], v[24:27]
	v_mfma_f32_16x16x32_bf16 v[8:11], v[172:175], v[202:205], v[8:11]
	s_setprio 0
	s_setprio 1
	v_mfma_f32_16x16x32_bf16 v[32:35], v[128:131], v[156:159], v[140:143]
	v_mfma_f32_16x16x32_bf16 v[52:55], v[188:191], v[136:139], v[32:35]
	v_mfma_f32_16x16x32_bf16 v[32:35], v[214:217], v[156:159], v[144:147]
	v_mfma_f32_16x16x32_bf16 v[16:19], v[214:217], v[160:163], v[16:19]
	v_mfma_f32_16x16x32_bf16 v[48:51], v[218:221], v[136:139], v[32:35]
	v_mfma_f32_16x16x32_bf16 v[20:23], v[128:131], v[160:163], v[20:23]
	v_mfma_f32_16x16x32_bf16 v[32:35], v[218:221], v[164:167], v[16:19]
	v_mfma_f32_16x16x32_bf16 v[16:19], v[128:131], v[176:179], v[148:151]
	v_mfma_f32_16x16x32_bf16 v[36:39], v[188:191], v[164:167], v[20:23]
	v_mfma_f32_16x16x32_bf16 v[20:23], v[188:191], v[180:183], v[16:19]
	v_mfma_f32_16x16x32_bf16 v[16:19], v[214:217], v[176:179], v[152:155]
	v_mfma_f32_16x16x32_bf16 v[4:7], v[128:131], v[192:195], v[4:7]
	v_mfma_f32_16x16x32_bf16 v[0:3], v[214:217], v[192:195], v[0:3]
	v_mfma_f32_16x16x32_bf16 v[16:19], v[218:221], v[180:183], v[16:19]
	v_mfma_f32_16x16x32_bf16 v[4:7], v[188:191], v[202:205], v[4:7]
	v_mfma_f32_16x16x32_bf16 v[0:3], v[218:221], v[202:205], v[0:3]
	s_setprio 0
	s_movk_i32 s4, 0x100
	v_cmp_gt_u32_e32 vcc, s4, v132
	s_barrier
	s_and_saveexec_b64 s[4:5], vcc
	s_cbranch_execz .LBB0_571
	s_barrier
